# group barrier: 10 of 13 grid syncs now sync only the 32 blocks sharing blockIdx%8 (batch-local dataflow), one-level counter, no L2 writeback when the group sits on one XCD; plus permlane swaps for xor
# speedup vs baseline: 1.0385x; 1.0385x over previous
_Z4mega6Params:
	s_load_dwordx2 s[82:83], s[0:1], 0xc0
	s_mov_b64 s[68:69], s[0:1]
	s_and_b32 s3, s2, 7
	s_lshl_b32 s3, s3, 8
	s_add_u32 s3, s3, 0x123600
	v_writelane_b32 v250, s3, 63
	v_writelane_b32 v250, 0, 61
	v_writelane_b32 v250, 0, 60
	s_add_u32 s6, s68, 0xc0
	v_and_b32_e32 v196, 0x3ff, v0
	s_addc_u32 s7, s69, 0
	s_mov_b64 s[8:9], s[0:1]
	s_mov_b32 s16, 0
	v_cmp_eq_u32_e64 s[70:71], 0, v196
	s_and_saveexec_b64 s[4:5], s[70:71]
	s_cbranch_execz .LBB0_3
	s_add_i32 s0, 0, 0x23fc0
	v_mov_b32_e32 v1, 0
	v_mov_b32_e32 v2, s0
	s_add_i32 s0, 0, 0x23fc4
	s_mov_b64 s[10:11], exec
	ds_write_b32 v2, v1
	v_mov_b32_e32 v2, s0
	ds_write_b32 v2, v1
	v_mbcnt_lo_u32_b32 v1, s10, 0
	v_mbcnt_hi_u32_b32 v1, s11, v1
	v_cmp_eq_u32_e32 vcc, 0, v1
	s_getreg_b32 s0, hwreg(HW_REG_XCC_ID, 0, 4)
	s_and_b64 s[12:13], exec, vcc
	s_mov_b64 exec, s[12:13]
	s_cbranch_execz .LBB0_3
	s_load_dwordx2 s[8:9], s[8:9], 0xb8
	s_lshl_b32 s0, s0, 8
	s_and_b32 s0, s0, 0xf00
	v_mov_b32_e32 v1, 0x120000
	s_waitcnt lgkmcnt(0)
	s_add_u32 s0, s8, s0
	s_addc_u32 s1, s9, 0
	s_bcnt1_i32_b64 s3, s[10:11]
	v_mov_b32_e32 v2, s3
	global_atomic_add v1, v2, s[0:1] offset:1024
	s_getreg_b32 s3, hwreg(HW_REG_XCC_ID, 0, 4)
	s_lshl_b32 s3, 1, s3
	v_mov_b32_e32 v2, s3
	s_and_b32 s3, s2, 7
	s_lshl_b32 s3, s3, 8
	s_add_u32 s0, s8, s3
	s_addc_u32 s1, s9, 0
	v_mov_b32_e32 v1, 0x123680
	global_atomic_or v1, v2, s[0:1]
.LBB0_3:
	s_or_b64 exec, exec, s[4:5]
	s_waitcnt lgkmcnt(0)
	s_and_b32 s4, s2, 7
	s_sub_u32 s4, s82, s4
	s_add_u32 s4, s4, 7
	s_lshr_b32 s4, s4, 3
	v_writelane_b32 v250, s4, 59
	s_abs_i32 s0, s82
	v_cvt_f32_u32_e32 v1, s0
	s_sub_i32 s4, 0, s0
	s_add_i32 s72, s82, s2
	s_lshl_b32 s1, s82, 8
	v_rcp_iflag_f32_e32 v1, v1
	s_lshl_b32 s3, s2, 8
	v_mov_b32_e32 v34, 0
	s_movk_i32 s17, 0x5800
	v_mul_f32_e32 v1, 0x4f7ffffe, v1
	v_cvt_u32_f32_e32 v1, v1
	s_movk_i32 s18, 0x104
	s_movk_i32 s19, 0x400
	s_movk_i32 s20, 0x1600
	v_readfirstlane_b32 s5, v1
	s_mul_i32 s4, s4, s5
	s_mul_hi_u32 s4, s5, s4
	s_add_i32 s33, s5, s4
	v_mov_b32_e32 v1, 0xffff7e00
	s_mov_b32 s30, 0
	s_barrier
	s_branch .LBB0_5

.LBB0_434:
	s_or_b64 exec, exec, s[4:5]
	s_waitcnt lgkmcnt(0)
	s_mov_b64 s[6:7], s[68:69]
	s_waitcnt vmcnt(0)
	s_barrier
	s_and_saveexec_b64 s[0:1], s[70:71]
	s_xor_b64 s[4:5], exec, s[0:1]
	v_writelane_b32 v250, s22, 11
	s_cbranch_execz .LBB0_488
	v_writelane_b32 v250, s8, 44
	v_writelane_b32 v250, s9, 45
	v_writelane_b32 v250, s10, 46
	v_writelane_b32 v250, s11, 47
	v_writelane_b32 v250, s12, 48
	v_writelane_b32 v250, s13, 49
	v_writelane_b32 v250, s14, 50
	v_writelane_b32 v250, s15, 51
	s_load_dwordx2 s[8:9], s[68:69], 0xb8
	v_readfirstlane_b32 s12, v0
	v_readfirstlane_b32 s13, v1
	v_readlane_b32 s10, v250, 63
	v_readlane_b32 s11, v250, 61
	v_readlane_b32 s14, v250, 59
	v_mov_b32_e32 v0, 0
	s_mov_b32 s15, 0
	s_waitcnt lgkmcnt(0)
	s_add_u32 s8, s8, s10
	s_addc_u32 s9, s9, 0
	s_cmp_lg_u32 s11, 0
	s_cbranch_scc1 .Lgb1_known
	global_load_dword v1, v0, s[8:9] offset:128 sc1
	s_waitcnt vmcnt(0)
	v_readfirstlane_b32 s10, v1
	s_sub_u32 s11, s10, 1
	s_and_b32 s11, s11, s10
	s_cmp_eq_u32 s11, 0
	s_cselect_b32 s11, 2, 1
	s_cmp_eq_u32 s10, 0
	s_cselect_b32 s11, 1, s11
	v_writelane_b32 v250, s11, 61
	s_nop 0
.Lgb1_known:
	v_readlane_b32 s10, v250, 60
	v_mov_b32_e32 v1, 1
	s_add_u32 s10, s10, s14
	v_writelane_b32 v250, s10, 60
	s_cmp_eq_u32 s11, 2
	s_cbranch_scc1 .Lgb1_pure
	buffer_wbl2 sc1
	s_waitcnt vmcnt(0)
	global_atomic_add v0, v1, s[8:9]
	s_branch .Lgb1_spin
.Lgb1_pure:
	buffer_inv sc1
	global_atomic_add v0, v1, s[8:9]
.Lgb1_spin:
	global_load_dword v1, v0, s[8:9] sc1
	s_add_u32 s15, s15, 1
	s_waitcnt vmcnt(0)
	v_cmp_gt_u32_e32 vcc, s10, v1
	s_cbranch_vccz .Lgb1_rel
	s_cmp_lt_u32 s15, 0x200000
	s_cbranch_scc0 .Lgb1_rel
	s_sleep 1
	s_branch .Lgb1_spin
.Lgb1_rel:
	s_cmp_eq_u32 s11, 2
	s_cbranch_scc1 .Lgb1_done
	buffer_inv sc1
	s_waitcnt vmcnt(0)
.Lgb1_done:
	v_mov_b32_e32 v0, s12
	v_mov_b32_e32 v1, s13
	v_readlane_b32 s8, v250, 44
	v_readlane_b32 s9, v250, 45
	v_readlane_b32 s10, v250, 46
	v_readlane_b32 s11, v250, 47
	v_readlane_b32 s12, v250, 48
	v_readlane_b32 s13, v250, 49
	v_readlane_b32 s14, v250, 50
	v_readlane_b32 s15, v250, 51
	s_branch .LBB0_488
.LBB0_445:
	s_branch .LBB0_430
.LBB0_488:
	s_or_b64 exec, exec, s[4:5]
	s_cmp_lg_u32 s22, 1
	s_mov_b64 s[4:5], -1
	s_waitcnt lgkmcnt(0)
	s_barrier
	s_cbranch_scc0 .LBB0_659
	s_lshr_b32 s0, s22, 1
	v_readlane_b32 s1, v251, 55
	s_add_i32 s0, s0, s1
	s_mov_b64 s[4:5], s[68:69]
	s_mov_b64 s[10:11], s[68:69]
	s_mov_b64 s[12:13], s[68:69]
	s_movk_i32 s22, 0x400
	s_movk_i32 s18, 0x400
	s_movk_i32 s6, 0x400
	s_movk_i32 s7, 0x1600
	s_movk_i32 s1, 0x4000
	s_ashr_i32 s8, s1, 31
	s_lshr_b32 s8, s8, 24
	s_add_i32 s1, s1, s8
	s_ashr_i32 s8, s7, 31
	s_lshr_b32 s8, s8, 24
	s_add_i32 s7, s7, s8
	s_ashr_i32 s1, s1, 8
	s_ashr_i32 s20, s7, 8
	s_mul_i32 s8, s20, s1
	v_mov_b32_e32 v12, v196
	v_readlane_b32 s7, v251, 17
	s_cmp_lt_i32 s7, s8
	v_readfirstlane_b32 s24, v12
	s_cbranch_scc0 .LBB0_518
	s_ashr_i32 s9, s8, 31
	s_lshr_b32 s7, s9, 29
	s_add_i32 s7, s8, s7
	s_ashr_i32 s34, s7, 3
	s_and_b32 s7, s7, -8
	s_sub_i32 s35, s8, s7
	s_add_i32 s36, s34, 1
	v_readlane_b32 s7, v251, 18
	s_cmp_ge_i32 s7, s35
	s_mov_b64 s[16:17], -1
	s_mul_i32 s37, s36, s35
	s_cbranch_scc0 .LBB0_492
	v_readlane_b32 s7, v251, 18
	s_sub_i32 s7, s7, s35
	s_mul_i32 s7, s7, s34
	s_add_i32 s21, s7, s37
	s_mov_b64 s[16:17], 0

.LBB0_518:
	s_mov_b64 s[6:7], s[68:69]
	s_waitcnt vmcnt(0)
	s_waitcnt vmcnt(0) lgkmcnt(0)
	s_barrier
	s_and_saveexec_b64 s[4:5], s[70:71]
	s_xor_b64 s[4:5], exec, s[4:5]
	s_cbranch_execz .LBB0_571
	v_writelane_b32 v250, s8, 44
	v_writelane_b32 v250, s9, 45
	v_writelane_b32 v250, s10, 46
	v_writelane_b32 v250, s11, 47
	v_writelane_b32 v250, s12, 48
	v_writelane_b32 v250, s13, 49
	v_writelane_b32 v250, s14, 50
	v_writelane_b32 v250, s15, 51
	s_load_dwordx2 s[8:9], s[68:69], 0xb8
	v_readfirstlane_b32 s12, v0
	v_readfirstlane_b32 s13, v1
	v_readlane_b32 s10, v250, 63
	v_readlane_b32 s11, v250, 61
	v_readlane_b32 s14, v250, 59
	v_mov_b32_e32 v0, 0
	s_mov_b32 s15, 0
	s_waitcnt lgkmcnt(0)
	s_add_u32 s8, s8, s10
	s_addc_u32 s9, s9, 0
	s_cmp_lg_u32 s11, 0
	s_cbranch_scc1 .Lgb2_known
	global_load_dword v1, v0, s[8:9] offset:128 sc1
	s_waitcnt vmcnt(0)
	v_readfirstlane_b32 s10, v1
	s_sub_u32 s11, s10, 1
	s_and_b32 s11, s11, s10
	s_cmp_eq_u32 s11, 0
	s_cselect_b32 s11, 2, 1
	s_cmp_eq_u32 s10, 0
	s_cselect_b32 s11, 1, s11
	v_writelane_b32 v250, s11, 61
	s_nop 0

.Lgb2_done:
	v_mov_b32_e32 v0, s12
	v_mov_b32_e32 v1, s13
	v_readlane_b32 s8, v250, 44
	v_readlane_b32 s9, v250, 45
	v_readlane_b32 s10, v250, 46
	v_readlane_b32 s11, v250, 47
	v_readlane_b32 s12, v250, 48
	v_readlane_b32 s13, v250, 49
	v_readlane_b32 s14, v250, 50
	v_readlane_b32 s15, v250, 51

.LBB0_604:
	s_mov_b64 s[4:5], s[68:69]
	s_waitcnt vmcnt(0)
	s_waitcnt lgkmcnt(0)
	s_barrier
	s_and_saveexec_b64 s[0:1], s[70:71]
	s_xor_b64 s[2:3], exec, s[0:1]
	v_readlane_b32 s22, v250, 11
	s_cbranch_execz .LBB0_658
	v_writelane_b32 v250, s8, 44
	v_writelane_b32 v250, s9, 45
	v_writelane_b32 v250, s10, 46
	v_writelane_b32 v250, s11, 47
	v_writelane_b32 v250, s12, 48
	v_writelane_b32 v250, s13, 49
	v_writelane_b32 v250, s14, 50
	v_writelane_b32 v250, s15, 51
	s_load_dwordx2 s[8:9], s[68:69], 0xb8
	v_readfirstlane_b32 s12, v0
	v_readfirstlane_b32 s13, v1
	v_readlane_b32 s10, v250, 63
	v_readlane_b32 s11, v250, 61
	v_readlane_b32 s14, v250, 59
	v_mov_b32_e32 v0, 0
	s_mov_b32 s15, 0
	s_waitcnt lgkmcnt(0)
	s_add_u32 s8, s8, s10
	s_addc_u32 s9, s9, 0
	s_cmp_lg_u32 s11, 0
	s_cbranch_scc1 .Lgb3_known
	global_load_dword v1, v0, s[8:9] offset:128 sc1
	s_waitcnt vmcnt(0)
	v_readfirstlane_b32 s10, v1
	s_sub_u32 s11, s10, 1
	s_and_b32 s11, s11, s10
	s_cmp_eq_u32 s11, 0
	s_cselect_b32 s11, 2, 1
	s_cmp_eq_u32 s10, 0
	s_cselect_b32 s11, 1, s11
	v_writelane_b32 v250, s11, 61
	s_nop 0

.LBB0_615:
	s_branch .LBB0_573
.LBB0_658:
	s_or_b64 exec, exec, s[2:3]
	s_mov_b64 s[4:5], 0
	s_waitcnt lgkmcnt(0)
	s_barrier

.LBB0_884:
	s_waitcnt lgkmcnt(0)
	s_mov_b64 s[4:5], s[68:69]
	s_waitcnt vmcnt(0)
	s_waitcnt vmcnt(0)
	s_barrier
	s_and_saveexec_b64 s[0:1], s[70:71]
	s_xor_b64 s[2:3], exec, s[0:1]
	s_cbranch_execz .LBB0_937
	v_writelane_b32 v250, s8, 44
	v_writelane_b32 v250, s9, 45
	v_writelane_b32 v250, s10, 46
	v_writelane_b32 v250, s11, 47
	v_writelane_b32 v250, s12, 48
	v_writelane_b32 v250, s13, 49
	v_writelane_b32 v250, s14, 50
	v_writelane_b32 v250, s15, 51
	s_load_dwordx2 s[8:9], s[68:69], 0xb8
	v_readfirstlane_b32 s12, v0
	v_readfirstlane_b32 s13, v1
	v_readlane_b32 s10, v250, 63
	v_readlane_b32 s11, v250, 61
	v_readlane_b32 s14, v250, 59
	v_mov_b32_e32 v0, 0
	s_mov_b32 s15, 0
	s_waitcnt lgkmcnt(0)
	s_add_u32 s8, s8, s10
	s_addc_u32 s9, s9, 0
	s_cmp_lg_u32 s11, 0
	s_cbranch_scc1 .Lgb4_known
	global_load_dword v1, v0, s[8:9] offset:128 sc1
	s_waitcnt vmcnt(0)
	v_readfirstlane_b32 s10, v1
	s_sub_u32 s11, s10, 1
	s_and_b32 s11, s11, s10
	s_cmp_eq_u32 s11, 0
	s_cselect_b32 s11, 2, 1
	s_cmp_eq_u32 s10, 0
	s_cselect_b32 s11, 1, s11
	v_writelane_b32 v250, s11, 61
	s_nop 0

.LBB0_1108:
	s_or_b64 exec, exec, s[2:3]
	v_readlane_b32 s2, v251, 0
	s_lshr_b32 s1, s0, 4
	v_readlane_b32 s3, v251, 1
	s_and_b64 s[2:3], s[2:3], exec
	s_cselect_b32 s1, s0, s1
	s_lshr_b32 s0, s7, 1
	s_lshl_b32 s92, s1, 5
	s_lshl_b32 s1, s7, 3
	s_sub_i32 s95, 0x7e0, s92
	v_and_or_b32 v78, s1, 8, v159
	s_lshl_b32 s1, s0, 22
	v_readlane_b32 s2, v250, 21
	s_add_u32 s2, s2, s1
	v_readlane_b32 s1, v250, 22
	v_add_u32_e32 v152, s95, v213
	s_addc_u32 s3, s1, 0
	v_lshlrev_b32_e32 v92, 7, v78
	v_lshl_add_u64 v[0:1], s[2:3], 0, v[92:93]
	v_mov_b32_e32 v151, v93
	v_ashrrev_i32_e32 v153, 31, v152
	v_lshl_add_u64 v[0:1], v[0:1], 0, v[150:151]
	v_lshlrev_b64 v[2:3], 11, v[152:153]
	v_lshl_add_u64 v[2:3], v[0:1], 0, v[2:3]
	global_load_dwordx4 v[96:99], v[2:3], off
	v_or_b32_e32 v154, 2, v152
	v_ashrrev_i32_e32 v155, 31, v154
	v_lshlrev_b64 v[4:5], 11, v[154:155]
	v_lshl_add_u64 v[0:1], v[0:1], 0, v[4:5]
	global_load_dwordx4 v[100:103], v[2:3], off offset:64
	global_load_dwordx4 v[104:107], v[0:1], off
	global_load_dwordx4 v[108:111], v[0:1], off offset:64
	v_mov_b32_e32 v11, v196
	s_add_i32 s1, 0, 0x12000
	s_waitcnt lgkmcnt(0)
	s_barrier
	v_cmp_lt_i32_e32 vcc, v205, v198
	v_bfe_u32 v79, v11, 4, 2
	v_and_b32_e32 v42, 15, v11
	v_lshl_add_u32 v77, v79, 4, s1
	v_mad_u32_u24 v8, v42, s88, v77
	ds_read_b128 v[0:3], v8
	ds_read_b128 v[4:7], v8 offset:64
	ds_read_b128 v[12:15], v8 offset:2304
	ds_read_b128 v[16:19], v8 offset:2368
	ds_read_b128 v[20:23], v8 offset:4608
	ds_read_b128 v[24:27], v8 offset:4672
	ds_read_b128 v[28:31], v8 offset:6912
	ds_read_b128 v[32:35], v8 offset:6976
	ds_read_b128 v[36:39], v8 offset:9216
	ds_read_b128 v[44:47], v8 offset:9280
	ds_read_b128 v[48:51], v8 offset:11520
	ds_read_b128 v[52:55], v8 offset:11584
	v_cmp_ne_u32_e64 s[78:79], 3, v79
	v_cmp_eq_u32_e64 s[74:75], 0, v79
	v_readlane_b32 s1, v250, 20
	s_waitcnt vmcnt(3) lgkmcnt(1)
	v_mfma_f32_16x16x32_bf16 v[56:59], v[48:51], v[96:99], 0
	ds_read_b128 v[48:51], v8 offset:13824
	ds_read_b128 v[60:63], v8 offset:13888
	v_mfma_f32_16x16x32_bf16 v[0:3], v[0:3], v[96:99], 0
	s_waitcnt lgkmcnt(1)
	v_mfma_f32_16x16x32_bf16 v[64:67], v[48:51], v[96:99], 0
	ds_read_b128 v[48:51], v8 offset:16128
	ds_read_b128 v[68:71], v8 offset:16192
	v_cndmask_b32_e32 v8, v197, v205, vcc
	v_lshlrev_b32_e32 v151, 2, v8
	v_mfma_f32_16x16x32_bf16 v[12:15], v[12:15], v[96:99], 0
	v_lshlrev_b32_e32 v8, 6, v79
	v_add_u32_e32 v41, 0x4f, v8
	v_or_b32_e32 v40, 0x11f, v8
	v_mfma_f32_16x16x32_bf16 v[20:23], v[20:23], v[96:99], 0
	v_add_u32_e32 v76, 0x74f, v8
	v_mfma_f32_16x16x32_bf16 v[36:39], v[36:39], v[96:99], 0
	s_waitcnt vmcnt(2)
	v_mfma_f32_16x16x32_bf16 v[0:3], v[4:7], v[100:103], v[0:3]
	s_waitcnt lgkmcnt(1)
	v_mfma_f32_16x16x32_bf16 v[72:75], v[48:51], v[96:99], 0
	v_or_b32_e32 v50, 31, v8
	v_cmp_le_i32_e32 vcc, v50, v152
	v_or_b32_e32 v49, 0x12f, v8
	v_mfma_f32_16x16x32_bf16 v[4:7], v[16:19], v[100:103], v[12:15]
	s_nop 1
	v_cndmask_b32_e32 v0, v158, v0, vcc
	v_or_b32_e32 v51, 0x13f, v8
	v_mfma_f32_16x16x32_bf16 v[12:15], v[24:27], v[100:103], v[20:23]
	v_mfma_f32_16x16x32_bf16 v[20:23], v[44:47], v[100:103], v[36:39]
	s_nop 2
	v_or_b32_e32 v39, 47, v8
	v_or_b32_e32 v38, 63, v8
	v_cmp_le_i32_e32 vcc, v39, v152
	v_mfma_f32_16x16x32_bf16 v[28:31], v[28:31], v[96:99], 0
	s_nop 0
	v_cndmask_b32_e32 v1, v158, v1, vcc
	v_cmp_le_i32_e32 vcc, v38, v152
	v_mfma_f32_16x16x32_bf16 v[24:27], v[52:55], v[100:103], v[56:59]
	v_add_u32_e32 v52, 0x14f, v8
	v_cndmask_b32_e32 v2, v158, v2, vcc
	v_cmp_le_i32_e32 vcc, v41, v152
	v_or_b32_e32 v53, 0x21f, v8
	v_or_b32_e32 v54, 0x22f, v8
	v_cndmask_b32_e32 v3, v158, v3, vcc
	v_cmp_le_i32_e32 vcc, v40, v152
	v_mfma_f32_16x16x32_bf16 v[16:19], v[32:35], v[100:103], v[28:31]
	v_or_b32_e32 v55, 0x23f, v8
	v_cndmask_b32_e32 v9, v158, v4, vcc
	v_cmp_le_i32_e32 vcc, v49, v152
	v_add_u32_e32 v56, 0x24f, v8
	v_or_b32_e32 v57, 0x31f, v8
	v_cndmask_b32_e32 v10, v158, v5, vcc
	v_cmp_le_i32_e32 vcc, v51, v152
	v_or_b32_e32 v58, 0x32f, v8
	v_or_b32_e32 v59, 0x33f, v8
	v_cndmask_b32_e32 v6, v158, v6, vcc
	v_cmp_le_i32_e32 vcc, v52, v152
	v_mfma_f32_16x16x32_bf16 v[28:31], v[60:63], v[100:103], v[64:67]
	v_add_u32_e32 v60, 0x34f, v8
	v_cndmask_b32_e32 v7, v158, v7, vcc
	v_cmp_le_i32_e32 vcc, v53, v152
	v_or_b32_e32 v61, 0x41f, v8
	v_or_b32_e32 v62, 0x42f, v8
	v_cndmask_b32_e32 v36, v158, v12, vcc
	v_cmp_le_i32_e32 vcc, v54, v152
	v_or_b32_e32 v63, 0x43f, v8
	v_add_u32_e32 v64, 0x44f, v8
	v_cndmask_b32_e32 v37, v158, v13, vcc
	v_cmp_le_i32_e32 vcc, v55, v152
	v_max3_f32 v4, v0, s87, v1
	v_or_b32_e32 v65, 0x51f, v8
	v_cndmask_b32_e32 v43, v158, v14, vcc
	v_cmp_le_i32_e32 vcc, v56, v152
	v_max3_f32 v4, v4, v2, v3
	v_or_b32_e32 v66, 0x52f, v8
	v_cndmask_b32_e32 v44, v158, v15, vcc
	v_cmp_le_i32_e32 vcc, v57, v152
	v_max3_f32 v4, v4, v9, v10
	v_or_b32_e32 v67, 0x53f, v8
	v_cndmask_b32_e32 v16, v158, v16, vcc
	v_cmp_le_i32_e32 vcc, v58, v152
	s_waitcnt lgkmcnt(0)
	v_mfma_f32_16x16x32_bf16 v[32:35], v[68:71], v[100:103], v[72:75]
	v_max3_f32 v4, v4, v6, v7
	v_cndmask_b32_e32 v17, v158, v17, vcc
	v_cmp_le_i32_e32 vcc, v59, v152
	v_add_u32_e32 v68, 0x54f, v8
	v_max3_f32 v4, v4, v36, v37
	v_cndmask_b32_e32 v18, v158, v18, vcc
	v_cmp_le_i32_e32 vcc, v60, v152
	v_or_b32_e32 v69, 0x61f, v8
	v_max3_f32 v4, v4, v43, v44
	v_cndmask_b32_e32 v19, v158, v19, vcc
	v_cmp_le_i32_e32 vcc, v61, v152
	v_or_b32_e32 v70, 0x62f, v8
	v_max3_f32 v4, v4, v16, v17
	v_cndmask_b32_e32 v45, v158, v20, vcc
	v_cmp_le_i32_e32 vcc, v62, v152
	v_or_b32_e32 v71, 0x63f, v8
	v_max3_f32 v4, v4, v18, v19
	v_cndmask_b32_e32 v46, v158, v21, vcc
	v_cmp_le_i32_e32 vcc, v63, v152
	v_add_u32_e32 v72, 0x64f, v8
	v_max3_f32 v4, v4, v45, v46
	v_cndmask_b32_e32 v47, v158, v22, vcc
	v_cmp_le_i32_e32 vcc, v64, v152
	v_or_b32_e32 v73, 0x71f, v8
	v_or_b32_e32 v74, 0x72f, v8
	v_cndmask_b32_e32 v48, v158, v23, vcc
	v_cmp_le_i32_e32 vcc, v65, v152
	v_max3_f32 v4, v4, v47, v48
	v_or_b32_e32 v75, 0x73f, v8
	v_cndmask_b32_e32 v24, v158, v24, vcc
	v_cmp_le_i32_e32 vcc, v66, v152
	s_nop 1
	v_cndmask_b32_e32 v25, v158, v25, vcc
	v_cmp_le_i32_e32 vcc, v67, v152
	v_max3_f32 v4, v4, v24, v25
	s_nop 0
	v_cndmask_b32_e32 v80, v158, v26, vcc
	v_cmp_le_i32_e32 vcc, v68, v152
	s_nop 1
	v_cndmask_b32_e32 v81, v158, v27, vcc
	v_cmp_le_i32_e32 vcc, v69, v152
	v_max3_f32 v4, v4, v80, v81
	s_nop 0
	v_cndmask_b32_e32 v82, v158, v28, vcc
	v_cmp_le_i32_e32 vcc, v70, v152
	s_nop 1
	v_cndmask_b32_e32 v83, v158, v29, vcc
	v_cmp_le_i32_e32 vcc, v71, v152
	v_max3_f32 v4, v4, v82, v83
	s_nop 0
	v_cndmask_b32_e32 v84, v158, v30, vcc
	v_cmp_le_i32_e32 vcc, v72, v152
	s_nop 1
	v_cndmask_b32_e32 v85, v158, v31, vcc
	v_cmp_le_i32_e32 vcc, v73, v152
	v_max3_f32 v4, v4, v84, v85
	s_nop 0
	v_cndmask_b32_e32 v86, v158, v32, vcc
	v_cmp_le_i32_e32 vcc, v74, v152
	s_nop 1
	v_cndmask_b32_e32 v87, v158, v33, vcc
	v_cmp_le_i32_e32 vcc, v75, v152
	v_max3_f32 v4, v4, v86, v87
	s_nop 0
	v_cndmask_b32_e32 v34, v158, v34, vcc
	v_cmp_le_i32_e32 vcc, v76, v152
	s_and_b64 vcc, s[78:79], vcc
	s_nop 0
	v_cndmask_b32_e32 v35, v158, v35, vcc
	v_max3_f32 v4, v4, v34, v35
	ds_bpermute_b32 v5, v151, v4
	v_cmp_lt_i32_e32 vcc, v204, v198
	s_waitcnt lgkmcnt(0)
	v_max_f32_e32 v5, v5, v5
	v_cndmask_b32_e32 v8, v197, v204, vcc
	v_lshlrev_b32_e32 v217, 2, v8
	v_max_f32_e32 v4, v4, v5
	ds_bpermute_b32 v5, v217, v4
	v_cmp_lt_f32_e32 vcc, s86, v0
	s_waitcnt lgkmcnt(0)
	v_max_f32_e32 v5, v5, v5
	v_max_f32_e32 v88, v4, v5
	v_sub_f32_e32 v4, v0, v88
	v_exp_f32_e32 v4, v4
	v_sub_f32_e32 v5, v1, v88
	v_exp_f32_e32 v5, v5
	v_sub_f32_e32 v8, v3, v88
	v_cndmask_b32_e32 v4, 0, v4, vcc
	v_cmp_lt_f32_e32 vcc, s86, v1
	v_add_f32_e32 v0, 0, v4
	v_exp_f32_e32 v8, v8
	v_cndmask_b32_e32 v5, 0, v5, vcc
	v_add_f32_e32 v1, v5, v0
	v_sub_f32_e32 v0, v2, v88
	v_exp_f32_e32 v0, v0
	v_cmp_lt_f32_e32 vcc, s86, v2
	s_nop 1
	v_cndmask_b32_e32 v0, 0, v0, vcc
	v_cmp_lt_f32_e32 vcc, s86, v3
	v_sub_f32_e32 v3, v9, v88
	v_exp_f32_e32 v3, v3
	v_add_f32_e32 v2, v0, v1
	v_cndmask_b32_e32 v1, 0, v8, vcc
	v_sub_f32_e32 v8, v10, v88
	v_cmp_lt_f32_e32 vcc, s86, v9
	v_exp_f32_e32 v8, v8
	v_add_f32_e32 v2, v1, v2
	v_cndmask_b32_e32 v14, 0, v3, vcc
	v_sub_f32_e32 v3, v6, v88
	v_exp_f32_e32 v3, v3
	v_cmp_lt_f32_e32 vcc, s86, v10
	v_add_f32_e32 v2, v14, v2
	v_sub_f32_e32 v10, v35, v88
	v_cndmask_b32_e32 v15, 0, v8, vcc
	v_sub_f32_e32 v8, v7, v88
	v_cmp_lt_f32_e32 vcc, s86, v6
	v_exp_f32_e32 v8, v8
	v_sub_f32_e32 v6, v37, v88
	v_cndmask_b32_e32 v12, 0, v3, vcc
	v_sub_f32_e32 v3, v36, v88
	v_exp_f32_e32 v3, v3
	v_exp_f32_e32 v6, v6
	v_cmp_lt_f32_e32 vcc, s86, v7
	v_add_f32_e32 v2, v15, v2
	v_add_f32_e32 v2, v12, v2
	v_cndmask_b32_e32 v13, 0, v8, vcc
	v_cmp_lt_f32_e32 vcc, s86, v36
	v_add_f32_e32 v2, v13, v2
	v_exp_f32_e32 v10, v10
	v_cndmask_b32_e32 v22, 0, v3, vcc
	v_cmp_lt_f32_e32 vcc, s86, v37
	v_sub_f32_e32 v3, v43, v88
	v_exp_f32_e32 v3, v3
	v_cndmask_b32_e32 v23, 0, v6, vcc
	v_sub_f32_e32 v6, v44, v88
	v_exp_f32_e32 v6, v6
	v_cmp_lt_f32_e32 vcc, s86, v43
	v_add_f32_e32 v2, v22, v2
	v_add_f32_e32 v2, v23, v2
	v_cndmask_b32_e32 v20, 0, v3, vcc
	v_cmp_lt_f32_e32 vcc, s86, v44
	v_sub_f32_e32 v3, v16, v88
	v_exp_f32_e32 v3, v3
	v_cndmask_b32_e32 v21, 0, v6, vcc
	v_sub_f32_e32 v6, v17, v88
	v_exp_f32_e32 v6, v6
	v_cmp_lt_f32_e32 vcc, s86, v16
	v_add_f32_e32 v2, v20, v2
	v_add_f32_e32 v2, v21, v2
	v_cndmask_b32_e32 v30, 0, v3, vcc
	v_cmp_lt_f32_e32 vcc, s86, v17
	v_sub_f32_e32 v3, v18, v88
	v_exp_f32_e32 v3, v3
	v_cndmask_b32_e32 v31, 0, v6, vcc
	v_sub_f32_e32 v6, v19, v88
	v_exp_f32_e32 v6, v6
	v_cmp_lt_f32_e32 vcc, s86, v18
	v_add_f32_e32 v2, v30, v2
	v_add_f32_e32 v2, v31, v2
	v_cndmask_b32_e32 v26, 0, v3, vcc
	v_cmp_lt_f32_e32 vcc, s86, v19
	v_sub_f32_e32 v3, v45, v88
	v_exp_f32_e32 v3, v3
	v_cndmask_b32_e32 v27, 0, v6, vcc
	v_sub_f32_e32 v6, v46, v88
	v_exp_f32_e32 v6, v6
	v_cmp_lt_f32_e32 vcc, s86, v45
	v_add_f32_e32 v2, v26, v2
	v_add_f32_e32 v2, v27, v2
	v_cndmask_b32_e32 v28, 0, v3, vcc
	v_cmp_lt_f32_e32 vcc, s86, v46
	v_sub_f32_e32 v3, v47, v88
	v_exp_f32_e32 v3, v3
	v_cndmask_b32_e32 v29, 0, v6, vcc
	v_sub_f32_e32 v6, v48, v88
	v_exp_f32_e32 v6, v6
	v_cmp_lt_f32_e32 vcc, s86, v47
	v_add_f32_e32 v2, v28, v2
	v_add_f32_e32 v2, v29, v2
	v_cndmask_b32_e32 v32, 0, v3, vcc
	v_cmp_lt_f32_e32 vcc, s86, v48
	v_sub_f32_e32 v3, v24, v88
	v_exp_f32_e32 v3, v3
	v_cndmask_b32_e32 v33, 0, v6, vcc
	v_sub_f32_e32 v6, v25, v88
	v_exp_f32_e32 v6, v6
	v_cmp_lt_f32_e32 vcc, s86, v24
	v_add_f32_e32 v2, v32, v2
	v_add_f32_e32 v2, v33, v2
	v_cndmask_b32_e32 v18, 0, v3, vcc
	v_cmp_lt_f32_e32 vcc, s86, v25
	v_sub_f32_e32 v3, v80, v88
	v_exp_f32_e32 v3, v3
	v_cndmask_b32_e32 v19, 0, v6, vcc
	v_sub_f32_e32 v6, v81, v88
	v_exp_f32_e32 v6, v6
	v_cmp_lt_f32_e32 vcc, s86, v80
	v_add_f32_e32 v2, v18, v2
	v_add_f32_e32 v2, v19, v2
	v_cndmask_b32_e32 v24, 0, v3, vcc
	v_cmp_lt_f32_e32 vcc, s86, v81
	v_sub_f32_e32 v3, v82, v88
	v_exp_f32_e32 v3, v3
	v_cndmask_b32_e32 v25, 0, v6, vcc
	v_sub_f32_e32 v6, v83, v88
	v_exp_f32_e32 v6, v6
	v_cmp_lt_f32_e32 vcc, s86, v82
	v_add_f32_e32 v2, v24, v2
	v_add_f32_e32 v2, v25, v2
	v_cndmask_b32_e32 v8, 0, v3, vcc
	v_cmp_lt_f32_e32 vcc, s86, v83
	v_sub_f32_e32 v3, v84, v88
	v_exp_f32_e32 v3, v3
	v_cndmask_b32_e32 v9, 0, v6, vcc
	v_sub_f32_e32 v6, v85, v88
	v_exp_f32_e32 v6, v6
	v_add_f32_e32 v2, v8, v2
	v_cmp_lt_f32_e32 vcc, s86, v84
	v_add_f32_e32 v2, v9, v2
	v_add_u32_e32 v36, 48, v11
	v_cndmask_b32_e32 v16, 0, v3, vcc
	v_cmp_lt_f32_e32 vcc, s86, v85
	v_add_f32_e32 v2, v16, v2
	v_and_or_b32 v36, v36, 63, v210
	v_cndmask_b32_e32 v17, 0, v6, vcc
	v_add_f32_e32 v3, v17, v2
	v_sub_f32_e32 v2, v86, v88
	v_exp_f32_e32 v2, v2
	v_sub_f32_e32 v6, v87, v88
	v_exp_f32_e32 v6, v6
	v_cmp_lt_f32_e32 vcc, s86, v86
	v_lshlrev_b32_e32 v43, 2, v36
	s_nop 0
	v_cndmask_b32_e32 v2, 0, v2, vcc
	v_cmp_lt_f32_e32 vcc, s86, v87
	v_add_f32_e32 v7, v2, v3
	s_nop 0
	v_cndmask_b32_e32 v3, 0, v6, vcc
	v_sub_f32_e32 v6, v34, v88
	v_exp_f32_e32 v6, v6
	v_cmp_lt_f32_e32 vcc, s86, v34
	v_add_f32_e32 v7, v3, v7
	s_nop 0
	v_cndmask_b32_e32 v6, 0, v6, vcc
	v_cmp_lt_f32_e32 vcc, s86, v35
	v_add_f32_e32 v34, v6, v7
	v_bfe_u32 v35, v11, 3, 1
	v_cndmask_b32_e32 v7, 0, v10, vcc
	v_add_f32_e32 v10, v7, v34
	v_mov_b32_e32 v34, v10
	s_nop 1
	v_permlane16_swap_b32_e32 v34, v10
	v_cmp_lt_i32_e32 vcc, v199, v198
	v_or_b32_e32 v35, s1, v35
	s_movk_i32 s1, 0x84
	v_cndmask_b32_e32 v37, v197, v199, vcc
	s_waitcnt lgkmcnt(0)
	v_add_f32_e32 v10, v10, v34
	v_mov_b32_e32 v34, v10
	s_nop 1
	v_permlane32_swap_b32_e32 v34, v10
	v_lshlrev_b32_e32 v44, 2, v37
	v_mul_lo_u32 v35, v35, s1
	s_waitcnt lgkmcnt(0)
	v_add_f32_e32 v10, v10, v34
	v_max_f32_e32 v10, 0x1e3ce508, v10
	v_div_scale_f32 v34, s[2:3], v10, v10, 1.0
	v_rcp_f32_e32 v36, v34
	s_nop 0
	v_fma_f32 v37, -v34, v36, 1.0
	v_fmac_f32_e32 v36, v37, v36
	v_div_scale_f32 v37, vcc, 1.0, v10, 1.0
	v_mul_f32_e32 v45, v37, v36
	v_fma_f32 v46, -v34, v45, v37
	v_fmac_f32_e32 v45, v46, v36
	v_fma_f32 v34, -v34, v45, v37
	v_div_fmas_f32 v34, v34, v36, v45
	v_div_fixup_f32 v10, v34, v10, 1.0
	v_pk_mul_f32 v[0:1], v[0:1], v[10:11] op_sel_hi:[1,0]
	v_pk_mul_f32 v[4:5], v[4:5], v[10:11] op_sel_hi:[1,0]
	v_mul_f32_e32 v36, 0.5, v1
	ds_bpermute_b32 v34, v43, v36
	v_add_f32_e32 v37, v4, v5
	v_fma_f32 v45, 0.5, v1, v0
	v_add_f32_e32 v37, v37, v45
	v_cmp_lt_i32_e32 vcc, v201, v198
	s_waitcnt lgkmcnt(0)
	v_cndmask_b32_e64 v34, v34, 0, s[74:75]
	v_add_f32_e32 v34, v37, v34
	ds_bpermute_b32 v37, v44, v34
	v_cndmask_b32_e32 v45, v197, v201, vcc
	v_lshlrev_b32_e32 v45, 2, v45
	v_cmp_lt_i32_e32 vcc, v202, v198
	v_and_b32_e32 v11, 7, v11
	s_waitcnt lgkmcnt(0)
	v_add_f32_e32 v34, v34, v37
	ds_bpermute_b32 v37, v45, v34
	v_cndmask_b32_e32 v46, v197, v202, vcc
	v_lshlrev_b32_e32 v46, 2, v46
	v_cmp_eq_u32_e64 s[76:77], 0, v11
	s_waitcnt lgkmcnt(0)
	v_add_f32_e32 v11, v34, v37
	ds_bpermute_b32 v34, v46, v11
	v_lshl_add_u32 v37, v79, 2, s33
	v_add_u32_e32 v47, v37, v35
	s_and_saveexec_b64 s[2:3], s[76:77]
	s_cbranch_execz .LBB0_1110
	s_waitcnt lgkmcnt(0)
	v_add_f32_e32 v11, v11, v34
	ds_write_b32 v47, v11

.LBB0_1124:
	s_or_b64 exec, exec, s[2:3]
	s_lshl_b32 s96, s0, 11
	v_mul_u32_u24_e32 v10, 3, v78
	v_readlane_b32 s0, v250, 23
	v_lshlrev_b32_e32 v162, 2, v10
	v_mov_b32_e32 v163, v93
	v_readlane_b32 s1, v250, 24
	v_lshlrev_b32_e32 v218, 6, v78
	v_lshl_add_u32 v48, v79, 3, s83
	v_lshl_add_u64 v[18:19], s[0:1], 0, v[162:163]
	v_readlane_b32 s0, v250, 25
	v_lshlrev_b32_e32 v94, 2, v218
	v_mov_b32_e32 v95, v93
	v_readlane_b32 s1, v250, 26
	v_cvt_pk_bf16_f32 v82, v4, v5
	v_mad_u32_u24 v4, v42, s12, v48
	s_waitcnt lgkmcnt(0)
	v_lshl_add_u64 v[10:11], s[0:1], 0, v[94:95]
	v_lshlrev_b32_e32 v92, 4, v79
	v_add_u32_e32 v78, 0x1000, v4
	v_add_u32_e32 v79, 0x2000, v4
	v_add_u32_e32 v81, 0x3000, v4
	v_lshl_add_u64 v[16:17], v[10:11], 0, v[92:93]
	v_cvt_pk_bf16_f32 v85, v12, v13
	ds_read2_b64 v[10:13], v4 offset1:4
	ds_read2_b64 v[86:89], v78 offset0:32 offset1:36
	ds_read2_b64 v[112:115], v79 offset0:64 offset1:68
	ds_read2_b64 v[116:119], v81 offset0:96 offset1:100
	v_cvt_pk_bf16_f32 v83, v0, v1
	v_cvt_pk_bf16_f32 v84, v14, v15
	v_cvt_pk_bf16_f32 v2, v2, v3
	v_cvt_pk_bf16_f32 v3, v6, v7
	s_waitcnt lgkmcnt(3)
	v_mfma_f32_16x16x32_bf16 v[10:13], v[10:13], v[82:85], 0
	v_cvt_pk_bf16_f32 v0, v8, v9
	v_cvt_pk_bf16_f32 v1, v36, v37
	v_lshl_add_u64 v[156:157], v[152:153], 0, s[96:97]
	s_waitcnt lgkmcnt(2)
	v_mfma_f32_16x16x32_bf16 v[86:89], v[86:89], v[82:85], 0
	s_movk_i32 s2, 0xc0
	v_lshlrev_b64 v[164:165], 12, v[156:157]
	v_mul_u32_u24_e32 v80, 0x90, v42
	s_waitcnt lgkmcnt(1)
	v_mfma_f32_16x16x32_bf16 v[112:115], v[112:115], v[82:85], 0
	v_add_u32_e32 v36, v77, v80
	v_cmp_le_i32_e32 vcc, v50, v154
	s_waitcnt lgkmcnt(0)
	v_mfma_f32_16x16x32_bf16 v[82:85], v[116:119], v[82:85], 0
	v_cvt_pk_bf16_f32 v116, v22, v23
	v_cvt_pk_bf16_f32 v117, v20, v21
	ds_read2_b64 v[20:23], v4 offset0:8 offset1:12
	v_cvt_pk_bf16_f32 v118, v30, v31
	v_cvt_pk_bf16_f32 v119, v26, v27
	v_cvt_pk_bf16_f32 v27, v32, v33
	ds_read2_b64 v[30:33], v4 offset0:16 offset1:20
	s_waitcnt lgkmcnt(1)
	v_mfma_f32_16x16x32_bf16 v[10:13], v[20:23], v[116:119], v[10:13]
	ds_read2_b64 v[20:23], v78 offset0:40 offset1:44
	v_cvt_pk_bf16_f32 v26, v28, v29
	v_cvt_pk_bf16_f32 v28, v34, v35
	v_cvt_pk_bf16_f32 v29, v24, v25
	ds_read2_b64 v[4:7], v4 offset0:24 offset1:28
	s_waitcnt lgkmcnt(1)
	v_mfma_f32_16x16x32_bf16 v[20:23], v[20:23], v[116:119], v[86:89]
	s_nop 2
	ds_read2_b64 v[86:89], v79 offset0:72 offset1:76
	v_mfma_f32_16x16x32_bf16 v[10:13], v[30:33], v[26:29], v[10:13]
	ds_read2_b64 v[30:33], v78 offset0:48 offset1:52
	s_waitcnt lgkmcnt(0)
	v_mfma_f32_16x16x32_bf16 v[20:23], v[30:33], v[26:29], v[20:23]
	ds_read2_b64 v[30:33], v79 offset0:80 offset1:84
	v_mfma_f32_16x16x32_bf16 v[12:15], v[4:7], v[0:3], v[10:13]
	ds_read2_b64 v[4:7], v78 offset0:56 offset1:60
	v_mfma_f32_16x16x32_bf16 v[86:89], v[86:89], v[116:119], v[112:115]
	s_nop 2
	ds_read2_b64 v[112:115], v81 offset0:104 offset1:108
	s_waitcnt lgkmcnt(2)
	v_mfma_f32_16x16x32_bf16 v[30:33], v[30:33], v[26:29], v[86:89]
	s_nop 2
	ds_read2_b64 v[86:89], v81 offset0:112 offset1:116
	s_waitcnt lgkmcnt(2)
	v_mfma_f32_16x16x32_bf16 v[8:11], v[4:7], v[0:3], v[20:23]
	ds_read2_b64 v[4:7], v79 offset0:88 offset1:92
	s_nop 1
	ds_read2_b64 v[20:23], v81 offset0:120 offset1:124
	s_waitcnt lgkmcnt(3)
	v_mfma_f32_16x16x32_bf16 v[82:85], v[112:115], v[116:119], v[82:85]
	s_waitcnt lgkmcnt(2)
	v_mfma_f32_16x16x32_bf16 v[24:27], v[86:89], v[26:29], v[82:85]
	s_waitcnt lgkmcnt(1)
	v_mfma_f32_16x16x32_bf16 v[4:7], v[4:7], v[0:3], v[30:33]
	s_waitcnt lgkmcnt(0)
	v_mfma_f32_16x16x32_bf16 v[0:3], v[20:23], v[0:3], v[24:27]
	v_mad_u64_u32 v[20:21], s[0:1], v156, s2, v[18:19]
	v_mad_i32_i24 v21, v157, s2, v21
	global_load_dword v20, v[20:21], off
	v_lshl_add_u64 v[22:23], v[16:17], 0, v[164:165]
	s_waitcnt vmcnt(0)
	v_pk_mul_f32 v[14:15], v[14:15], v[20:21] op_sel_hi:[1,0]
	v_pk_mul_f32 v[12:13], v[12:13], v[20:21] op_sel_hi:[1,0]
	v_pk_mul_f32 v[10:11], v[10:11], v[20:21] op_sel_hi:[1,0]
	v_pk_mul_f32 v[8:9], v[8:9], v[20:21] op_sel_hi:[1,0]
	v_pk_mul_f32 v[6:7], v[6:7], v[20:21] op_sel_hi:[1,0]
	v_pk_mul_f32 v[4:5], v[4:5], v[20:21] op_sel_hi:[1,0]
	v_pk_mul_f32 v[2:3], v[2:3], v[20:21] op_sel_hi:[1,0]
	v_pk_mul_f32 v[0:1], v[0:1], v[20:21] op_sel_hi:[1,0]
	global_store_dwordx4 v[22:23], v[12:15], off
	global_store_dwordx4 v[22:23], v[8:11], off offset:64
	global_store_dwordx4 v[22:23], v[4:7], off offset:128
	global_store_dwordx4 v[22:23], v[0:3], off offset:192
	ds_read_b128 v[0:3], v36
	ds_read_b128 v[4:7], v36 offset:64
	s_waitcnt lgkmcnt(1)
	v_mfma_f32_16x16x32_bf16 v[0:3], v[0:3], v[104:107], 0
	ds_read_b128 v[8:11], v36 offset:2368
	ds_read_b128 v[12:15], v36 offset:4672
	ds_read_b128 v[20:23], v36 offset:6976
	s_waitcnt lgkmcnt(3)
	v_mfma_f32_16x16x32_bf16 v[0:3], v[4:7], v[108:111], v[0:3]
	ds_read_b128 v[4:7], v36 offset:2304
	ds_read_b128 v[24:27], v36 offset:9280
	ds_read_b128 v[28:31], v36 offset:11584
	s_waitcnt lgkmcnt(2)
	v_mfma_f32_16x16x32_bf16 v[4:7], v[4:7], v[104:107], 0
	ds_read_b128 v[32:35], v36 offset:13888
	ds_read_b128 v[78:81], v36 offset:16192
	s_nop 0
	v_cndmask_b32_e32 v0, v158, v0, vcc
	v_mfma_f32_16x16x32_bf16 v[4:7], v[8:11], v[108:111], v[4:7]
	ds_read_b128 v[8:11], v36 offset:4608
	v_cmp_le_i32_e32 vcc, v39, v154
	s_waitcnt lgkmcnt(0)
	v_mfma_f32_16x16x32_bf16 v[8:11], v[8:11], v[104:107], 0
	v_cndmask_b32_e32 v1, v158, v1, vcc
	v_cmp_le_i32_e32 vcc, v38, v154
	v_mfma_f32_16x16x32_bf16 v[8:11], v[12:15], v[108:111], v[8:11]
	ds_read_b128 v[12:15], v36 offset:6912
	v_cndmask_b32_e32 v2, v158, v2, vcc
	v_cmp_le_i32_e32 vcc, v41, v154
	s_waitcnt lgkmcnt(0)
	v_mfma_f32_16x16x32_bf16 v[12:15], v[12:15], v[104:107], 0
	v_cndmask_b32_e32 v3, v158, v3, vcc
	v_cmp_le_i32_e32 vcc, v40, v154
	v_mfma_f32_16x16x32_bf16 v[12:15], v[20:23], v[108:111], v[12:15]
	ds_read_b128 v[20:23], v36 offset:9216
	v_cndmask_b32_e32 v4, v158, v4, vcc
	v_cmp_le_i32_e32 vcc, v49, v154
	s_waitcnt lgkmcnt(0)
	v_mfma_f32_16x16x32_bf16 v[20:23], v[20:23], v[104:107], 0
	v_cndmask_b32_e32 v5, v158, v5, vcc
	v_cmp_le_i32_e32 vcc, v51, v154
	v_mfma_f32_16x16x32_bf16 v[20:23], v[24:27], v[108:111], v[20:23]
	ds_read_b128 v[24:27], v36 offset:11520
	s_waitcnt lgkmcnt(0)
	v_mfma_f32_16x16x32_bf16 v[24:27], v[24:27], v[104:107], 0
	v_mfma_f32_16x16x32_bf16 v[24:27], v[28:31], v[108:111], v[24:27]
	ds_read_b128 v[28:31], v36 offset:13824
	s_waitcnt lgkmcnt(0)
	v_mfma_f32_16x16x32_bf16 v[28:31], v[28:31], v[104:107], 0
	v_mfma_f32_16x16x32_bf16 v[32:35], v[32:35], v[108:111], v[28:31]
	s_nop 6
	ds_read_b128 v[28:31], v36 offset:16128
	s_waitcnt lgkmcnt(0)
	v_mfma_f32_16x16x32_bf16 v[28:31], v[28:31], v[104:107], 0
	v_mfma_f32_16x16x32_bf16 v[78:81], v[78:81], v[108:111], v[28:31]
	s_nop 6
	v_cndmask_b32_e32 v30, v158, v6, vcc
	v_cmp_le_i32_e32 vcc, v52, v154
	v_max3_f32 v28, v0, s87, v1
	v_max3_f32 v28, v28, v2, v3
	v_cndmask_b32_e32 v37, v158, v7, vcc
	v_cmp_le_i32_e32 vcc, v53, v154
	v_max3_f32 v28, v28, v4, v5
	v_max3_f32 v6, v28, v30, v37
	v_cndmask_b32_e32 v38, v158, v8, vcc
	v_cmp_le_i32_e32 vcc, v54, v154
	s_nop 1
	v_cndmask_b32_e32 v39, v158, v9, vcc
	v_cmp_le_i32_e32 vcc, v55, v154
	v_max3_f32 v6, v6, v38, v39
	s_nop 0
	v_cndmask_b32_e32 v10, v158, v10, vcc
	v_cmp_le_i32_e32 vcc, v56, v154
	s_nop 1
	v_cndmask_b32_e32 v11, v158, v11, vcc
	v_cmp_le_i32_e32 vcc, v57, v154
	v_max3_f32 v6, v6, v10, v11
	s_nop 0
	v_cndmask_b32_e32 v40, v158, v12, vcc
	v_cmp_le_i32_e32 vcc, v58, v154
	s_nop 1
	v_cndmask_b32_e32 v41, v158, v13, vcc
	v_cmp_le_i32_e32 vcc, v59, v154
	v_max3_f32 v6, v6, v40, v41
	s_nop 0
	v_cndmask_b32_e32 v14, v158, v14, vcc
	v_cmp_le_i32_e32 vcc, v60, v154
	s_nop 1
	v_cndmask_b32_e32 v15, v158, v15, vcc
	v_cmp_le_i32_e32 vcc, v61, v154
	v_max3_f32 v6, v6, v14, v15
	s_nop 0
	v_cndmask_b32_e32 v49, v158, v20, vcc
	v_cmp_le_i32_e32 vcc, v62, v154
	s_nop 1
	v_cndmask_b32_e32 v50, v158, v21, vcc
	v_cmp_le_i32_e32 vcc, v63, v154
	v_max3_f32 v6, v6, v49, v50
	s_nop 0
	v_cndmask_b32_e32 v22, v158, v22, vcc
	v_cmp_le_i32_e32 vcc, v64, v154
	s_nop 1
	v_cndmask_b32_e32 v23, v158, v23, vcc
	v_cmp_le_i32_e32 vcc, v65, v154
	v_max3_f32 v6, v6, v22, v23
	s_nop 0
	v_cndmask_b32_e32 v51, v158, v24, vcc
	v_cmp_le_i32_e32 vcc, v66, v154
	s_nop 1
	v_cndmask_b32_e32 v52, v158, v25, vcc
	v_cmp_le_i32_e32 vcc, v67, v154
	v_max3_f32 v6, v6, v51, v52
	s_nop 0
	v_cndmask_b32_e32 v53, v158, v26, vcc
	v_cmp_le_i32_e32 vcc, v68, v154
	s_nop 1
	v_cndmask_b32_e32 v31, v158, v27, vcc
	v_cmp_le_i32_e32 vcc, v69, v154
	v_max3_f32 v6, v6, v53, v31
	s_nop 0
	v_cndmask_b32_e32 v26, v158, v32, vcc
	v_cmp_le_i32_e32 vcc, v70, v154
	s_nop 1
	v_cndmask_b32_e32 v27, v158, v33, vcc
	v_cmp_le_i32_e32 vcc, v71, v154
	v_max3_f32 v6, v6, v26, v27
	s_nop 0
	v_cndmask_b32_e32 v32, v158, v34, vcc
	v_cmp_le_i32_e32 vcc, v72, v154
	s_nop 1
	v_cndmask_b32_e32 v33, v158, v35, vcc
	v_cmp_le_i32_e32 vcc, v73, v154
	v_max3_f32 v6, v6, v32, v33
	s_nop 0
	v_cndmask_b32_e32 v28, v158, v78, vcc
	v_cmp_le_i32_e32 vcc, v74, v154
	s_nop 1
	v_cndmask_b32_e32 v29, v158, v79, vcc
	v_cmp_le_i32_e32 vcc, v75, v154
	v_max3_f32 v6, v6, v28, v29
	s_nop 0
	v_cndmask_b32_e32 v34, v158, v80, vcc
	v_cmp_le_i32_e32 vcc, v76, v154
	s_and_b64 vcc, s[78:79], vcc
	s_nop 0
	v_cndmask_b32_e32 v35, v158, v81, vcc
	v_max3_f32 v6, v6, v34, v35
	ds_bpermute_b32 v7, v151, v6
	v_cmp_lt_f32_e32 vcc, s86, v0
	s_waitcnt lgkmcnt(0)
	v_max_f32_e32 v7, v7, v7
	v_max_f32_e32 v6, v6, v7
	ds_bpermute_b32 v7, v217, v6
	s_waitcnt lgkmcnt(0)
	v_max_f32_e32 v7, v7, v7
	v_max_f32_e32 v36, v6, v7
	v_sub_f32_e32 v0, v0, v36
	v_exp_f32_e32 v0, v0
	s_nop 0
	v_cndmask_b32_e32 v0, 0, v0, vcc
	v_cmp_lt_f32_e32 vcc, s86, v1
	v_sub_f32_e32 v1, v1, v36
	v_exp_f32_e32 v1, v1
	v_add_f32_e32 v6, 0, v0
	v_cndmask_b32_e32 v1, 0, v1, vcc
	v_cmp_lt_f32_e32 vcc, s86, v2
	v_sub_f32_e32 v2, v2, v36
	v_exp_f32_e32 v2, v2
	v_add_f32_e32 v7, v1, v6
	v_cndmask_b32_e32 v6, 0, v2, vcc
	v_cmp_lt_f32_e32 vcc, s86, v3
	v_sub_f32_e32 v3, v3, v36
	v_exp_f32_e32 v3, v3
	v_add_f32_e32 v2, v6, v7
	v_cndmask_b32_e32 v7, 0, v3, vcc
	v_add_f32_e32 v3, v7, v2
	v_sub_f32_e32 v2, v4, v36
	v_exp_f32_e32 v2, v2
	v_cmp_lt_f32_e32 vcc, s86, v4
	s_nop 1
	v_cndmask_b32_e32 v2, 0, v2, vcc
	v_add_f32_e32 v4, v2, v3
	v_sub_f32_e32 v3, v5, v36
	v_cmp_lt_f32_e32 vcc, s86, v5
	v_exp_f32_e32 v3, v3
	v_sub_f32_e32 v5, v30, v36
	v_exp_f32_e32 v5, v5
	v_cndmask_b32_e32 v3, 0, v3, vcc
	v_cmp_lt_f32_e32 vcc, s86, v30
	v_add_f32_e32 v4, v3, v4
	s_nop 0
	v_cndmask_b32_e32 v8, 0, v5, vcc
	v_sub_f32_e32 v5, v37, v36
	v_exp_f32_e32 v5, v5
	v_cmp_lt_f32_e32 vcc, s86, v37
	v_add_f32_e32 v4, v8, v4
	s_nop 0
	v_cndmask_b32_e32 v9, 0, v5, vcc
	v_add_f32_e32 v5, v9, v4
	v_sub_f32_e32 v4, v38, v36
	v_exp_f32_e32 v4, v4
	v_cmp_lt_f32_e32 vcc, s86, v38
	s_nop 1
	v_cndmask_b32_e32 v4, 0, v4, vcc
	v_add_f32_e32 v12, v4, v5
	v_sub_f32_e32 v5, v39, v36
	v_exp_f32_e32 v5, v5
	v_cmp_lt_f32_e32 vcc, s86, v39
	s_nop 1
	v_cndmask_b32_e32 v5, 0, v5, vcc
	v_cmp_lt_f32_e32 vcc, s86, v10
	v_sub_f32_e32 v10, v10, v36
	v_exp_f32_e32 v10, v10
	v_add_f32_e32 v13, v5, v12
	v_cndmask_b32_e32 v12, 0, v10, vcc
	v_cmp_lt_f32_e32 vcc, s86, v11
	v_sub_f32_e32 v11, v11, v36
	v_exp_f32_e32 v11, v11
	v_add_f32_e32 v10, v12, v13
	v_cndmask_b32_e32 v13, 0, v11, vcc
	v_add_f32_e32 v11, v13, v10
	v_sub_f32_e32 v10, v40, v36
	v_exp_f32_e32 v10, v10
	v_cmp_lt_f32_e32 vcc, s86, v40
	s_nop 1
	v_cndmask_b32_e32 v10, 0, v10, vcc
	v_add_f32_e32 v20, v10, v11
	v_sub_f32_e32 v11, v41, v36
	v_exp_f32_e32 v11, v11
	v_cmp_lt_f32_e32 vcc, s86, v41
	s_nop 1
	v_cndmask_b32_e32 v11, 0, v11, vcc
	v_cmp_lt_f32_e32 vcc, s86, v14
	v_sub_f32_e32 v14, v14, v36
	v_exp_f32_e32 v14, v14
	v_add_f32_e32 v21, v11, v20
	v_cndmask_b32_e32 v20, 0, v14, vcc
	v_cmp_lt_f32_e32 vcc, s86, v15
	v_sub_f32_e32 v15, v15, v36
	v_exp_f32_e32 v15, v15
	v_add_f32_e32 v14, v20, v21
	v_cndmask_b32_e32 v21, 0, v15, vcc
	v_add_f32_e32 v15, v21, v14
	v_sub_f32_e32 v14, v49, v36
	v_exp_f32_e32 v14, v14
	v_cmp_lt_f32_e32 vcc, s86, v49
	s_nop 1
	v_cndmask_b32_e32 v14, 0, v14, vcc
	v_add_f32_e32 v24, v14, v15
	v_sub_f32_e32 v15, v50, v36
	v_exp_f32_e32 v15, v15
	v_cmp_lt_f32_e32 vcc, s86, v50
	s_nop 1
	v_cndmask_b32_e32 v15, 0, v15, vcc
	v_cmp_lt_f32_e32 vcc, s86, v22
	v_sub_f32_e32 v22, v22, v36
	v_exp_f32_e32 v22, v22
	v_add_f32_e32 v25, v15, v24
	v_cndmask_b32_e32 v24, 0, v22, vcc
	v_cmp_lt_f32_e32 vcc, s86, v23
	v_sub_f32_e32 v23, v23, v36
	v_exp_f32_e32 v23, v23
	v_add_f32_e32 v22, v24, v25
	v_cndmask_b32_e32 v25, 0, v23, vcc
	v_add_f32_e32 v23, v25, v22
	v_sub_f32_e32 v22, v51, v36
	v_exp_f32_e32 v22, v22
	v_cmp_lt_f32_e32 vcc, s86, v51
	s_nop 1
	v_cndmask_b32_e32 v22, 0, v22, vcc
	v_add_f32_e32 v30, v22, v23
	v_sub_f32_e32 v23, v52, v36
	v_exp_f32_e32 v23, v23
	v_cmp_lt_f32_e32 vcc, s86, v52
	s_nop 1
	v_cndmask_b32_e32 v23, 0, v23, vcc
	v_add_f32_e32 v37, v23, v30
	v_sub_f32_e32 v30, v53, v36
	v_exp_f32_e32 v30, v30
	v_cmp_lt_f32_e32 vcc, s86, v53
	s_nop 1
	v_cndmask_b32_e32 v30, 0, v30, vcc
	v_cmp_lt_f32_e32 vcc, s86, v31
	v_sub_f32_e32 v31, v31, v36
	v_exp_f32_e32 v31, v31
	v_add_f32_e32 v37, v30, v37
	v_cndmask_b32_e32 v31, 0, v31, vcc
	v_cmp_lt_f32_e32 vcc, s86, v26
	v_sub_f32_e32 v26, v26, v36
	v_exp_f32_e32 v26, v26
	v_add_f32_e32 v37, v31, v37
	v_cndmask_b32_e32 v26, 0, v26, vcc
	v_cmp_lt_f32_e32 vcc, s86, v27
	v_sub_f32_e32 v27, v27, v36
	v_exp_f32_e32 v27, v27
	v_add_f32_e32 v37, v26, v37
	v_cndmask_b32_e32 v27, 0, v27, vcc
	v_cmp_lt_f32_e32 vcc, s86, v32
	v_sub_f32_e32 v32, v32, v36
	v_exp_f32_e32 v32, v32
	v_add_f32_e32 v37, v27, v37
	v_cndmask_b32_e32 v32, 0, v32, vcc
	v_cmp_lt_f32_e32 vcc, s86, v33
	v_sub_f32_e32 v33, v33, v36
	v_exp_f32_e32 v33, v33
	v_add_f32_e32 v37, v32, v37
	v_cndmask_b32_e32 v33, 0, v33, vcc
	v_cmp_lt_f32_e32 vcc, s86, v28
	v_sub_f32_e32 v28, v28, v36
	v_exp_f32_e32 v28, v28
	v_add_f32_e32 v37, v33, v37
	v_cndmask_b32_e32 v28, 0, v28, vcc
	v_cmp_lt_f32_e32 vcc, s86, v29
	v_sub_f32_e32 v29, v29, v36
	v_exp_f32_e32 v29, v29
	v_add_f32_e32 v37, v28, v37
	v_cndmask_b32_e32 v29, 0, v29, vcc
	v_cmp_lt_f32_e32 vcc, s86, v34
	v_sub_f32_e32 v34, v34, v36
	v_exp_f32_e32 v34, v34
	v_add_f32_e32 v37, v29, v37
	v_cndmask_b32_e32 v34, 0, v34, vcc
	v_cmp_lt_f32_e32 vcc, s86, v35
	v_sub_f32_e32 v35, v35, v36
	v_exp_f32_e32 v35, v35
	v_add_f32_e32 v37, v34, v37
	v_cndmask_b32_e32 v35, 0, v35, vcc
	v_add_f32_e32 v36, v35, v37
	v_mov_b32_e32 v37, v36
	s_nop 1
	v_permlane16_swap_b32_e32 v37, v36
	s_waitcnt lgkmcnt(0)
	v_add_f32_e32 v36, v36, v37
	v_mov_b32_e32 v37, v36
	s_nop 1
	v_permlane32_swap_b32_e32 v37, v36
	s_waitcnt lgkmcnt(0)
	v_add_f32_e32 v36, v36, v37
	v_max_f32_e32 v36, 0x1e3ce508, v36
	v_div_scale_f32 v37, s[0:1], v36, v36, 1.0
	v_rcp_f32_e32 v38, v37
	s_nop 0
	v_fma_f32 v39, -v37, v38, 1.0
	v_fmac_f32_e32 v38, v39, v38
	v_div_scale_f32 v39, vcc, 1.0, v36, 1.0
	v_mul_f32_e32 v40, v39, v38
	v_fma_f32 v41, -v37, v40, v39
	v_fmac_f32_e32 v40, v41, v38
	v_fma_f32 v37, -v37, v40, v39
	v_div_fmas_f32 v37, v37, v38, v40
	v_div_fixup_f32 v36, v37, v36, 1.0
	v_pk_mul_f32 v[6:7], v[6:7], v[36:37] op_sel_hi:[1,0]
	v_pk_mul_f32 v[0:1], v[0:1], v[36:37] op_sel_hi:[1,0]
	v_mul_f32_e32 v49, 0.5, v7
	v_add_f32_e32 v37, v0, v1
	v_fma_f32 v38, 0.5, v7, v6
	v_add_f32_e32 v37, v37, v38
	ds_bpermute_b32 v38, v43, v49
	s_waitcnt lgkmcnt(0)
	v_cndmask_b32_e64 v38, v38, 0, s[74:75]
	v_add_f32_e32 v37, v37, v38
	ds_bpermute_b32 v38, v44, v37
	s_waitcnt lgkmcnt(0)
	v_add_f32_e32 v37, v37, v38
	ds_bpermute_b32 v38, v45, v37
	s_waitcnt lgkmcnt(0)
	v_add_f32_e32 v37, v37, v38
	ds_bpermute_b32 v38, v46, v37
	s_and_saveexec_b64 s[2:3], s[76:77]
	s_cbranch_execz .LBB0_1126
	s_waitcnt lgkmcnt(0)
	v_add_f32_e32 v37, v37, v38
	ds_write_b32 v47, v37 offset:264

.LBB0_1284:
	s_lshl_b32 s13, s14, 6
	s_lshl_b32 s14, 1, s14
	s_mul_i32 s2, s0, 0x4800
	v_and_b32_e32 v32, s14, v172
	s_add_i32 s96, s2, 0
	v_cmp_ne_u32_e32 vcc, 0, v32
	s_cmp_eq_u64 vcc, 0
	s_cselect_b64 s[2:3], -1, 0
	s_cmp_gt_i32 s13, s76
	s_cselect_b64 s[74:75], -1, 0
	s_or_b64 s[2:3], s[2:3], s[74:75]
	v_mov_b32_e32 v133, v196
	s_and_b64 vcc, exec, s[2:3]
	s_cbranch_vccnz .LBB0_1306
	v_cmp_eq_u32_e32 vcc, 0, v32
	s_or_b32 s15, s13, 63
	v_cmp_le_i32_e64 s[74:75], s15, v152
	v_cndmask_b32_e32 v138, 0, v211, vcc
	v_cmp_ge_u32_e64 s[2:3], s13, v138
	s_and_b64 s[2:3], s[2:3], s[74:75]
	v_and_b32_e32 v139, 63, v133
	v_cndmask_b32_e64 v32, 0, 1, s[2:3]
	v_cmp_ne_u32_e64 s[2:3], 0, v32
	v_and_b32_e32 v137, 15, v133
	v_and_b32_e32 v32, 48, v133
	v_or_b32_e32 v135, 48, v139
	s_mov_b64 s[74:75], -1
	s_cmp_lg_u64 s[2:3], exec
	v_add_u32_e32 v136, s96, v32
	v_mul_u32_u24_e32 v134, 0x90, v137
	v_mul_u32_u24_e32 v132, 0x90, v135
	s_cbranch_scc0 .LBB0_1299
	v_mad_u32_u24 v32, v137, s88, v136
	ds_read_b128 v[52:55], v32
	ds_read_b128 v[56:59], v32 offset:64
	ds_read_b128 v[60:63], v32 offset:2304
	ds_read_b128 v[64:67], v32 offset:2368
	ds_read_b128 v[68:71], v32 offset:4608
	ds_read_b128 v[72:75], v32 offset:4672
	v_mad_u32_u24 v32, v135, s88, v136
	ds_read_b128 v[76:79], v32
	ds_read_b128 v[48:51], v32 offset:64
	s_cmp_gt_i32 s15, s78
	s_mov_b64 s[2:3], -1
	s_cbranch_scc1 .LBB0_1292
	s_waitcnt lgkmcnt(7)
	v_mfma_f32_16x16x32_bf16 v[32:35], v[52:55], v[96:99], 0
	s_waitcnt lgkmcnt(5)
	v_mfma_f32_16x16x32_bf16 v[36:39], v[60:63], v[96:99], 0
	s_waitcnt lgkmcnt(3)
	v_mfma_f32_16x16x32_bf16 v[40:43], v[68:71], v[96:99], 0
	s_waitcnt lgkmcnt(1)
	v_mfma_f32_16x16x32_bf16 v[44:47], v[76:79], v[96:99], 0
	v_mfma_f32_16x16x32_bf16 v[32:35], v[56:59], v[100:103], v[32:35]
	v_mfma_f32_16x16x32_bf16 v[36:39], v[64:67], v[100:103], v[36:39]
	v_mfma_f32_16x16x32_bf16 v[40:43], v[72:75], v[100:103], v[40:43]
	s_waitcnt lgkmcnt(0)
	v_mfma_f32_16x16x32_bf16 v[44:47], v[48:51], v[100:103], v[44:47]
	s_nop 7
	s_nop 7
	s_nop 0
	v_max3_f32 v80, v158, v32, v33
	s_nop 0
	v_max3_f32 v80, v80, v34, v35
	s_nop 0
	v_max3_f32 v80, v80, v36, v37
	s_nop 0
	v_max3_f32 v80, v80, v38, v39
	s_nop 0
	v_max3_f32 v80, v80, v40, v41
	s_nop 0
	v_max3_f32 v80, v80, v42, v43
	s_nop 0
	v_max3_f32 v80, v80, v44, v45
	s_nop 0
	v_max3_f32 v80, v80, v46, v47
	s_nop 0
	v_cndmask_b32_e32 v80, v80, v158, vcc
	v_mov_b32_e32 v81, v80
	s_nop 1
	v_permlane16_swap_b32_e32 v81, v80
	s_waitcnt lgkmcnt(0)
	v_max3_f32 v80, v80, v81, v158
	v_mov_b32_e32 v81, v80
	s_nop 1
	v_permlane32_swap_b32_e32 v81, v80
	s_waitcnt lgkmcnt(0)
	v_max3_f32 v80, v80, v81, v158
	s_nop 0
	v_max3_f32 v163, v155, v80, v158
	s_nop 0
	v_cndmask_b32_e32 v84, v163, v212, vcc
	v_sub_f32_e32 v35, v35, v84
	v_sub_f32_e32 v34, v34, v84
	v_sub_f32_e32 v33, v33, v84
	v_sub_f32_e32 v32, v32, v84
	v_sub_f32_e32 v39, v39, v84
	v_sub_f32_e32 v38, v38, v84
	v_exp_f32_e32 v88, v32
	v_exp_f32_e32 v89, v33
	v_exp_f32_e32 v90, v34
	v_exp_f32_e32 v91, v35
	v_sub_f32_e32 v32, v37, v84
	v_sub_f32_e32 v33, v36, v84
	v_exp_f32_e32 v128, v33
	v_exp_f32_e32 v130, v38
	v_exp_f32_e32 v131, v39
	v_exp_f32_e32 v129, v32
	v_sub_f32_e32 v36, v43, v84
	v_sub_f32_e32 v37, v42, v84
	v_sub_f32_e32 v38, v41, v84
	v_sub_f32_e32 v39, v40, v84
	v_exp_f32_e32 v80, v39
	v_exp_f32_e32 v81, v38
	v_exp_f32_e32 v82, v37
	v_exp_f32_e32 v83, v36
	v_sub_f32_e32 v36, v47, v84
	v_sub_f32_e32 v37, v46, v84
	v_sub_f32_e32 v38, v45, v84
	v_sub_f32_e32 v39, v44, v84
	v_exp_f32_e32 v84, v39
	v_exp_f32_e32 v86, v37
	v_exp_f32_e32 v87, v36
	v_exp_f32_e32 v85, v38
	v_pk_add_f32 v[32:33], v[88:89], 0 op_sel_hi:[1,0]
	v_pk_add_f32 v[34:35], v[90:91], 0 op_sel_hi:[1,0]
	v_pk_add_f32 v[32:33], v[128:129], v[32:33]
	v_pk_add_f32 v[34:35], v[130:131], v[34:35]
	v_pk_add_f32 v[32:33], v[80:81], v[32:33]
	v_pk_add_f32 v[34:35], v[82:83], v[34:35]
	v_pk_add_f32 v[32:33], v[84:85], v[32:33]
	v_pk_add_f32 v[34:35], v[86:87], v[34:35]
	v_add_f32_e32 v32, v32, v33
	v_add_f32_e32 v33, v34, v35
	v_add_f32_e32 v32, v32, v33
	v_mov_b32_e32 v33, v32
	s_nop 1
	v_permlane16_swap_b32_e32 v33, v32
	v_sub_f32_e32 v34, v155, v163
	v_exp_f32_e32 v92, v34
	s_waitcnt lgkmcnt(0)
	v_add_f32_e32 v140, v32, v33
	ds_bpermute_b32 v141, v217, v140
	v_cmp_eq_f32_e32 vcc, 1.0, v92
	s_cmp_lg_u64 vcc, exec
	s_cbranch_scc0 .LBB0_1289
	v_pk_mul_f32 v[46:47], v[18:19], v[92:93] op_sel_hi:[1,0]
	v_pk_mul_f32 v[44:45], v[16:17], v[92:93] op_sel_hi:[1,0]
	v_pk_mul_f32 v[42:43], v[22:23], v[92:93] op_sel_hi:[1,0]
	v_pk_mul_f32 v[40:41], v[20:21], v[92:93] op_sel_hi:[1,0]
	v_pk_mul_f32 v[38:39], v[26:27], v[92:93] op_sel_hi:[1,0]
	v_pk_mul_f32 v[36:37], v[24:25], v[92:93] op_sel_hi:[1,0]
	v_pk_mul_f32 v[34:35], v[30:31], v[92:93] op_sel_hi:[1,0]
	v_pk_mul_f32 v[32:33], v[28:29], v[92:93] op_sel_hi:[1,0]
	s_mov_b64 s[2:3], 0

.LBB0_1292:
	s_and_b64 vcc, exec, s[2:3]
	s_cbranch_vccz .LBB0_1298
	s_waitcnt lgkmcnt(1)
	v_mfma_f32_16x16x32_bf16 v[44:47], v[76:79], v[96:99], 0
	v_mfma_f32_16x16x32_bf16 v[32:35], v[52:55], v[96:99], 0
	v_lshrrev_b32_e32 v52, 4, v139
	v_mfma_f32_16x16x32_bf16 v[36:39], v[60:63], v[96:99], 0
	v_mfma_f32_16x16x32_bf16 v[40:43], v[68:71], v[96:99], 0
	s_waitcnt lgkmcnt(0)
	v_mfma_f32_16x16x32_bf16 v[44:47], v[48:51], v[100:103], v[44:47]
	v_lshl_or_b32 v48, v52, 2, s13
	v_cmp_ge_u32_e32 vcc, v48, v138
	v_cmp_le_i32_e64 s[2:3], v48, v152
	v_mfma_f32_16x16x32_bf16 v[32:35], v[56:59], v[100:103], v[32:35]
	s_and_b64 vcc, vcc, s[2:3]
	v_or_b32_e32 v49, 1, v48
	v_cmp_lt_i32_e64 s[2:3], v48, v152
	v_mfma_f32_16x16x32_bf16 v[36:39], v[64:67], v[100:103], v[36:39]
	v_or_b32_e32 v50, 2, v48
	v_mfma_f32_16x16x32_bf16 v[40:43], v[72:75], v[100:103], v[40:43]
	s_nop 7
	s_nop 7
	s_nop 1
	v_cndmask_b32_e32 v32, v158, v32, vcc
	v_cmp_ge_u32_e32 vcc, v49, v138
	s_and_b64 vcc, s[2:3], vcc
	v_cmp_le_i32_e64 s[2:3], v50, v152
	v_cndmask_b32_e32 v33, v158, v33, vcc
	v_cmp_ge_u32_e32 vcc, v50, v138
	s_and_b64 vcc, vcc, s[2:3]
	v_or_b32_e32 v50, 3, v48
	v_cndmask_b32_e32 v34, v158, v34, vcc
	v_cmp_ge_u32_e32 vcc, v50, v138
	v_cmp_le_i32_e64 s[2:3], v50, v152
	s_and_b64 vcc, vcc, s[2:3]
	v_or_b32_e32 v50, 16, v48
	v_cndmask_b32_e32 v35, v158, v35, vcc
	v_cmp_ge_u32_e32 vcc, v50, v138
	v_cmp_le_i32_e64 s[2:3], v50, v152
	s_and_b64 vcc, vcc, s[2:3]
	v_or_b32_e32 v50, 17, v48
	v_cndmask_b32_e32 v36, v158, v36, vcc
	v_cmp_ge_u32_e32 vcc, v50, v138
	v_cmp_le_i32_e64 s[2:3], v50, v152
	s_and_b64 vcc, vcc, s[2:3]
	v_or_b32_e32 v50, 18, v48
	v_cndmask_b32_e32 v37, v158, v37, vcc
	v_cmp_ge_u32_e32 vcc, v50, v138
	v_cmp_le_i32_e64 s[2:3], v50, v152
	s_and_b64 vcc, vcc, s[2:3]
	v_or_b32_e32 v50, 19, v48
	v_cndmask_b32_e32 v38, v158, v38, vcc
	v_cmp_ge_u32_e32 vcc, v50, v138
	v_cmp_le_i32_e64 s[2:3], v50, v152
	s_and_b64 vcc, vcc, s[2:3]
	v_or_b32_e32 v50, 32, v48
	v_cndmask_b32_e32 v39, v158, v39, vcc
	v_cmp_ge_u32_e32 vcc, v50, v138
	v_cmp_le_i32_e64 s[2:3], v50, v152
	s_and_b64 vcc, vcc, s[2:3]
	v_or_b32_e32 v50, 33, v48
	v_cndmask_b32_e32 v40, v158, v40, vcc
	v_cmp_ge_u32_e32 vcc, v50, v138
	v_cmp_le_i32_e64 s[2:3], v50, v152
	s_and_b64 vcc, vcc, s[2:3]
	v_or_b32_e32 v50, 34, v48
	v_cndmask_b32_e32 v41, v158, v41, vcc
	v_cmp_ge_u32_e32 vcc, v50, v138
	v_cmp_le_i32_e64 s[2:3], v50, v152
	s_and_b64 vcc, vcc, s[2:3]
	v_or_b32_e32 v50, 35, v48
	v_cndmask_b32_e32 v42, v158, v42, vcc
	v_cmp_ge_u32_e32 vcc, v50, v138
	v_cmp_le_i32_e64 s[2:3], v50, v152
	s_and_b64 vcc, vcc, s[2:3]
	v_or_b32_e32 v50, 48, v48
	v_cndmask_b32_e32 v43, v158, v43, vcc
	v_cmp_ge_u32_e32 vcc, v50, v138
	v_cmp_le_i32_e64 s[2:3], v50, v152
	s_and_b64 vcc, vcc, s[2:3]
	v_or_b32_e32 v50, 49, v48
	v_max3_f32 v49, v32, s87, v33
	v_cndmask_b32_e32 v44, v158, v44, vcc
	v_cmp_ge_u32_e32 vcc, v50, v138
	v_cmp_le_i32_e64 s[2:3], v50, v152
	v_max3_f32 v49, v49, v34, v35
	s_and_b64 vcc, vcc, s[2:3]
	v_or_b32_e32 v50, 50, v48
	v_max3_f32 v49, v49, v36, v37
	v_cndmask_b32_e32 v45, v158, v45, vcc
	v_cmp_ge_u32_e32 vcc, v50, v138
	v_cmp_le_i32_e64 s[2:3], v50, v152
	v_max3_f32 v49, v49, v38, v39
	s_and_b64 vcc, vcc, s[2:3]
	v_or_b32_e32 v48, 51, v48
	v_max3_f32 v49, v49, v40, v41
	v_cndmask_b32_e32 v46, v158, v46, vcc
	v_cmp_ge_u32_e32 vcc, v48, v138
	v_cmp_le_i32_e64 s[2:3], v48, v152
	v_max3_f32 v49, v49, v42, v43
	s_and_b64 vcc, vcc, s[2:3]
	v_max3_f32 v49, v49, v44, v45
	v_cndmask_b32_e32 v47, v158, v47, vcc
	v_max3_f32 v48, v49, v46, v47
	v_mov_b32_e32 v49, v48
	s_nop 1
	v_permlane16_swap_b32_e32 v49, v48
	s_waitcnt lgkmcnt(0)
	v_max3_f32 v48, v48, v49, v158
	v_mov_b32_e32 v49, v48
	s_nop 1
	v_permlane32_swap_b32_e32 v49, v48
	s_waitcnt lgkmcnt(0)
	v_max3_f32 v48, v48, v49, v158
	v_cmp_lt_f32_e32 vcc, s86, v32
	v_max3_f32 v163, v155, v48, v158
	s_mov_b64 s[2:3], -1
	v_sub_f32_e32 v48, v32, v163
	v_exp_f32_e32 v48, v48
	v_sub_f32_e32 v49, v33, v163
	v_exp_f32_e32 v49, v49
	v_cndmask_b32_e32 v56, 0, v48, vcc
	v_cmp_lt_f32_e32 vcc, s86, v33
	v_sub_f32_e32 v33, v34, v163
	v_exp_f32_e32 v33, v33
	v_cndmask_b32_e32 v57, 0, v49, vcc
	v_sub_f32_e32 v48, v35, v163
	v_cmp_lt_f32_e32 vcc, s86, v34
	v_exp_f32_e32 v48, v48
	v_sub_f32_e32 v34, v37, v163
	v_cndmask_b32_e32 v60, 0, v33, vcc
	v_sub_f32_e32 v33, v36, v163
	v_exp_f32_e32 v33, v33
	v_exp_f32_e32 v34, v34
	v_cmp_lt_f32_e32 vcc, s86, v35
	v_add_f32_e32 v32, 0, v56
	v_add_f32_e32 v32, v57, v32
	v_cndmask_b32_e32 v61, 0, v48, vcc
	v_cmp_lt_f32_e32 vcc, s86, v36
	v_add_f32_e32 v32, v60, v32
	v_add_f32_e32 v32, v61, v32
	v_cndmask_b32_e32 v62, 0, v33, vcc
	v_cmp_lt_f32_e32 vcc, s86, v37
	v_sub_f32_e32 v33, v38, v163
	v_exp_f32_e32 v33, v33
	v_cndmask_b32_e32 v63, 0, v34, vcc
	v_sub_f32_e32 v34, v39, v163
	v_exp_f32_e32 v34, v34
	v_cmp_lt_f32_e32 vcc, s86, v38
	v_add_f32_e32 v32, v62, v32
	v_add_f32_e32 v32, v63, v32
	v_cndmask_b32_e32 v64, 0, v33, vcc
	v_cmp_lt_f32_e32 vcc, s86, v39
	v_sub_f32_e32 v33, v40, v163
	v_exp_f32_e32 v33, v33
	v_cndmask_b32_e32 v65, 0, v34, vcc
	v_sub_f32_e32 v34, v41, v163
	v_exp_f32_e32 v34, v34
	v_cmp_lt_f32_e32 vcc, s86, v40
	v_add_f32_e32 v32, v64, v32
	v_add_f32_e32 v32, v65, v32
	v_cndmask_b32_e32 v49, 0, v33, vcc
	v_cmp_lt_f32_e32 vcc, s86, v41
	v_sub_f32_e32 v33, v42, v163
	v_exp_f32_e32 v33, v33
	v_cndmask_b32_e32 v50, 0, v34, vcc
	v_sub_f32_e32 v34, v43, v163
	v_exp_f32_e32 v34, v34
	v_cmp_lt_f32_e32 vcc, s86, v42
	v_add_f32_e32 v32, v49, v32
	v_add_f32_e32 v32, v50, v32
	v_cndmask_b32_e32 v51, 0, v33, vcc
	v_cmp_lt_f32_e32 vcc, s86, v43
	v_sub_f32_e32 v33, v44, v163
	v_exp_f32_e32 v33, v33
	v_cndmask_b32_e32 v53, 0, v34, vcc
	v_sub_f32_e32 v34, v45, v163
	v_exp_f32_e32 v34, v34
	v_cmp_lt_f32_e32 vcc, s86, v44
	v_add_f32_e32 v32, v51, v32
	v_add_f32_e32 v32, v53, v32
	v_cndmask_b32_e32 v54, 0, v33, vcc
	v_cmp_lt_f32_e32 vcc, s86, v45
	v_sub_f32_e32 v33, v46, v163
	v_exp_f32_e32 v33, v33
	v_cndmask_b32_e32 v55, 0, v34, vcc
	v_sub_f32_e32 v34, v47, v163
	v_exp_f32_e32 v34, v34
	v_add_f32_e32 v32, v54, v32
	v_cmp_lt_f32_e32 vcc, s86, v46
	v_add_f32_e32 v32, v55, v32
	s_nop 0
	v_cndmask_b32_e32 v58, 0, v33, vcc
	v_cmp_lt_f32_e32 vcc, s86, v47
	v_add_f32_e32 v32, v58, v32
	s_nop 0
	v_cndmask_b32_e32 v59, 0, v34, vcc
	v_add_f32_e32 v32, v59, v32
	v_mov_b32_e32 v33, v32
	s_nop 1
	v_permlane16_swap_b32_e32 v33, v32
	v_sub_f32_e32 v34, v155, v163
	v_exp_f32_e32 v48, v34
	s_waitcnt lgkmcnt(0)
	v_add_f32_e32 v66, v32, v33
	ds_bpermute_b32 v67, v217, v66
	v_cmp_eq_f32_e32 vcc, 1.0, v48
	s_cmp_lg_u64 vcc, exec
	s_cbranch_scc0 .LBB0_1295
	v_pk_mul_f32 v[46:47], v[18:19], v[48:49] op_sel_hi:[1,0]
	v_pk_mul_f32 v[44:45], v[16:17], v[48:49] op_sel_hi:[1,0]
	v_pk_mul_f32 v[42:43], v[22:23], v[48:49] op_sel_hi:[1,0]
	v_pk_mul_f32 v[40:41], v[20:21], v[48:49] op_sel_hi:[1,0]
	v_pk_mul_f32 v[38:39], v[26:27], v[48:49] op_sel_hi:[1,0]
	v_pk_mul_f32 v[36:37], v[24:25], v[48:49] op_sel_hi:[1,0]
	v_pk_mul_f32 v[34:35], v[30:31], v[48:49] op_sel_hi:[1,0]
	v_pk_mul_f32 v[32:33], v[28:29], v[48:49] op_sel_hi:[1,0]
	s_mov_b64 s[2:3], 0

.LBB0_1299:
	s_andn2_b64 vcc, exec, s[74:75]
	s_cbranch_vccnz .LBB0_1305
	s_nop 4
	v_mad_u32_u24 v44, v137, s88, v136
	ds_read_b128 v[32:35], v44
	ds_read_b128 v[40:43], v44 offset:64
	ds_read_b128 v[36:39], v44 offset:2304
	s_waitcnt lgkmcnt(3)
	v_mad_u32_u24 v48, v135, s88, v136
	s_mov_b64 s[2:3], -1
	s_waitcnt lgkmcnt(2)
	v_mfma_f32_16x16x32_bf16 v[32:35], v[32:35], v[96:99], 0
	s_waitcnt lgkmcnt(1)
	v_mfma_f32_16x16x32_bf16 v[32:35], v[40:43], v[100:103], v[32:35]
	ds_read_b128 v[40:43], v44 offset:2368
	s_waitcnt lgkmcnt(1)
	v_mfma_f32_16x16x32_bf16 v[36:39], v[36:39], v[96:99], 0
	s_waitcnt lgkmcnt(0)
	v_mfma_f32_16x16x32_bf16 v[36:39], v[40:43], v[100:103], v[36:39]
	ds_read_b128 v[40:43], v44 offset:4608
	ds_read_b128 v[44:47], v44 offset:4672
	s_waitcnt lgkmcnt(1)
	v_mfma_f32_16x16x32_bf16 v[40:43], v[40:43], v[96:99], 0
	s_waitcnt lgkmcnt(0)
	v_mfma_f32_16x16x32_bf16 v[40:43], v[44:47], v[100:103], v[40:43]
	ds_read_b128 v[44:47], v48
	ds_read_b128 v[48:51], v48 offset:64
	s_waitcnt lgkmcnt(1)
	v_mfma_f32_16x16x32_bf16 v[44:47], v[44:47], v[96:99], 0
	s_waitcnt lgkmcnt(0)
	v_mfma_f32_16x16x32_bf16 v[44:47], v[48:51], v[100:103], v[44:47]
	s_nop 7
	s_nop 7
	s_nop 0
	v_max3_f32 v48, v158, v32, v33
	s_nop 0
	v_max3_f32 v48, v48, v34, v35
	s_nop 0
	v_max3_f32 v48, v48, v36, v37
	s_nop 0
	v_max3_f32 v48, v48, v38, v39
	s_nop 0
	v_max3_f32 v48, v48, v40, v41
	s_nop 0
	v_max3_f32 v48, v48, v42, v43
	s_nop 0
	v_max3_f32 v48, v48, v44, v45
	s_nop 0
	v_max3_f32 v48, v48, v46, v47
	v_mov_b32_e32 v49, v48
	s_nop 1
	v_permlane16_swap_b32_e32 v49, v48
	s_waitcnt lgkmcnt(0)
	v_max3_f32 v48, v48, v49, v158
	v_mov_b32_e32 v49, v48
	s_nop 1
	v_permlane32_swap_b32_e32 v49, v48
	s_waitcnt lgkmcnt(0)
	v_max3_f32 v48, v48, v49, v158
	s_nop 0
	v_max3_f32 v163, v155, v48, v158
	s_nop 0
	v_sub_f32_e32 v35, v35, v163
	v_sub_f32_e32 v34, v34, v163
	v_sub_f32_e32 v33, v33, v163
	v_sub_f32_e32 v32, v32, v163
	v_sub_f32_e32 v39, v39, v163
	v_sub_f32_e32 v38, v38, v163
	v_exp_f32_e32 v56, v32
	v_exp_f32_e32 v57, v33
	v_exp_f32_e32 v58, v34
	v_exp_f32_e32 v59, v35
	v_sub_f32_e32 v32, v37, v163
	v_sub_f32_e32 v33, v36, v163
	v_exp_f32_e32 v60, v33
	v_exp_f32_e32 v62, v38
	v_exp_f32_e32 v63, v39
	v_exp_f32_e32 v61, v32
	v_sub_f32_e32 v36, v43, v163
	v_sub_f32_e32 v37, v42, v163
	v_sub_f32_e32 v38, v41, v163
	v_sub_f32_e32 v39, v40, v163
	v_exp_f32_e32 v48, v39
	v_exp_f32_e32 v49, v38
	v_exp_f32_e32 v50, v37
	v_exp_f32_e32 v51, v36
	v_sub_f32_e32 v36, v47, v163
	v_sub_f32_e32 v37, v46, v163
	v_sub_f32_e32 v38, v45, v163
	v_sub_f32_e32 v39, v44, v163
	v_exp_f32_e32 v52, v39
	v_exp_f32_e32 v54, v37
	v_exp_f32_e32 v55, v36
	v_exp_f32_e32 v53, v38
	v_pk_add_f32 v[32:33], v[56:57], 0 op_sel_hi:[1,0]
	v_pk_add_f32 v[34:35], v[58:59], 0 op_sel_hi:[1,0]
	v_pk_add_f32 v[32:33], v[60:61], v[32:33]
	v_pk_add_f32 v[34:35], v[62:63], v[34:35]
	v_pk_add_f32 v[32:33], v[48:49], v[32:33]
	v_pk_add_f32 v[34:35], v[50:51], v[34:35]
	v_pk_add_f32 v[32:33], v[52:53], v[32:33]
	v_pk_add_f32 v[34:35], v[54:55], v[34:35]
	v_add_f32_e32 v32, v32, v33
	v_add_f32_e32 v33, v34, v35
	v_add_f32_e32 v32, v32, v33
	v_mov_b32_e32 v33, v32
	s_nop 1
	v_permlane16_swap_b32_e32 v33, v32
	v_sub_f32_e32 v34, v155, v163
	v_exp_f32_e32 v64, v34
	s_waitcnt lgkmcnt(0)
	v_add_f32_e32 v65, v32, v33
	ds_bpermute_b32 v66, v217, v65
	v_cmp_eq_f32_e32 vcc, 1.0, v64
	s_cmp_lg_u64 vcc, exec
	s_cbranch_scc0 .LBB0_1302
	v_pk_mul_f32 v[46:47], v[18:19], v[64:65] op_sel_hi:[1,0]
	v_pk_mul_f32 v[44:45], v[16:17], v[64:65] op_sel_hi:[1,0]
	v_pk_mul_f32 v[42:43], v[22:23], v[64:65] op_sel_hi:[1,0]
	v_pk_mul_f32 v[40:41], v[20:21], v[64:65] op_sel_hi:[1,0]
	v_pk_mul_f32 v[38:39], v[26:27], v[64:65] op_sel_hi:[1,0]
	v_pk_mul_f32 v[36:37], v[24:25], v[64:65] op_sel_hi:[1,0]
	v_pk_mul_f32 v[34:35], v[30:31], v[64:65] op_sel_hi:[1,0]
	v_pk_mul_f32 v[32:33], v[28:29], v[64:65] op_sel_hi:[1,0]
	s_mov_b64 s[2:3], 0

.LBB0_1307:
	v_and_b32_e32 v16, s14, v173
	v_cmp_ne_u32_e32 vcc, 0, v16
	s_cmp_eq_u64 vcc, 0
	s_cselect_b64 s[2:3], -1, 0
	s_cmp_gt_i32 s13, s77
	s_cselect_b64 s[14:15], -1, 0
	s_or_b64 s[2:3], s[2:3], s[14:15]
	v_mov_b32_e32 v181, v196
	s_and_b64 vcc, exec, s[2:3]
	s_cbranch_vccnz .LBB0_1330
	v_cmp_eq_u32_e32 vcc, 0, v16
	s_or_b32 s14, s13, 63
	v_cmp_le_i32_e64 s[74:75], s14, v154
	v_cndmask_b32_e32 v186, 0, v211, vcc
	v_cmp_ge_u32_e64 s[2:3], s13, v186
	s_and_b64 s[2:3], s[2:3], s[74:75]
	v_and_b32_e32 v187, 63, v181
	v_cndmask_b32_e64 v16, 0, 1, s[2:3]
	v_cmp_ne_u32_e64 s[2:3], 0, v16
	v_and_b32_e32 v185, 15, v181
	v_and_b32_e32 v16, 48, v181
	v_or_b32_e32 v183, 48, v187
	s_mov_b64 s[74:75], -1
	s_cmp_lg_u64 s[2:3], exec
	v_add_u32_e32 v184, s96, v16
	v_mul_u32_u24_e32 v182, 0x90, v185
	v_mul_u32_u24_e32 v155, 0x90, v183
	s_cbranch_scc0 .LBB0_1322
	v_mad_u32_u24 v16, v185, s88, v184
	ds_read_b128 v[20:23], v16
	ds_read_b128 v[24:27], v16 offset:64
	s_waitcnt lgkmcnt(3)
	ds_read_b128 v[76:79], v16 offset:2304
	ds_read_b128 v[80:83], v16 offset:2368
	ds_read_b128 v[84:87], v16 offset:4608
	ds_read_b128 v[88:91], v16 offset:4672
	v_mad_u32_u24 v16, v183, s88, v184
	ds_read_b128 v[128:131], v16
	ds_read_b128 v[16:19], v16 offset:64
	s_cmp_gt_i32 s14, s93
	s_mov_b64 s[2:3], -1
	s_cbranch_scc1 .LBB0_1315
	s_waitcnt lgkmcnt(7)
	v_mfma_f32_16x16x32_bf16 v[44:47], v[20:23], v[104:107], 0
	s_waitcnt lgkmcnt(5)
	v_mfma_f32_16x16x32_bf16 v[48:51], v[76:79], v[104:107], 0
	s_waitcnt lgkmcnt(3)
	v_mfma_f32_16x16x32_bf16 v[52:55], v[84:87], v[104:107], 0
	s_waitcnt lgkmcnt(1)
	v_mfma_f32_16x16x32_bf16 v[56:59], v[128:131], v[104:107], 0
	v_mfma_f32_16x16x32_bf16 v[44:47], v[24:27], v[108:111], v[44:47]
	v_mfma_f32_16x16x32_bf16 v[48:51], v[80:83], v[108:111], v[48:51]
	v_mfma_f32_16x16x32_bf16 v[52:55], v[88:91], v[108:111], v[52:55]
	s_waitcnt lgkmcnt(0)
	v_mfma_f32_16x16x32_bf16 v[56:59], v[16:19], v[108:111], v[56:59]
	s_nop 7
	s_nop 7
	s_nop 0
	v_max3_f32 v92, v158, v44, v45
	s_nop 0
	v_max3_f32 v92, v92, v46, v47
	s_nop 0
	v_max3_f32 v92, v92, v48, v49
	s_nop 0
	v_max3_f32 v92, v92, v50, v51
	s_nop 0
	v_max3_f32 v92, v92, v52, v53
	s_nop 0
	v_max3_f32 v92, v92, v54, v55
	s_nop 0
	v_max3_f32 v92, v92, v56, v57
	s_nop 0
	v_max3_f32 v92, v92, v58, v59
	s_nop 0
	v_cndmask_b32_e32 v92, v92, v158, vcc
	v_mov_b32_e32 v132, v92
	s_nop 1
	v_permlane16_swap_b32_e32 v132, v92
	s_waitcnt lgkmcnt(0)
	v_max3_f32 v92, v92, v132, v158
	v_mov_b32_e32 v132, v92
	s_nop 1
	v_permlane32_swap_b32_e32 v132, v92
	s_waitcnt lgkmcnt(0)
	v_max3_f32 v92, v92, v132, v158
	s_nop 0
	v_max3_f32 v175, v153, v92, v158
	s_nop 0
	v_cndmask_b32_e32 v92, v175, v212, vcc
	v_sub_f32_e32 v47, v47, v92
	v_sub_f32_e32 v46, v46, v92
	v_sub_f32_e32 v45, v45, v92
	v_sub_f32_e32 v44, v44, v92
	v_sub_f32_e32 v51, v51, v92
	v_sub_f32_e32 v50, v50, v92
	v_exp_f32_e32 v140, v44
	v_exp_f32_e32 v141, v45
	v_exp_f32_e32 v142, v46
	v_exp_f32_e32 v143, v47
	v_sub_f32_e32 v44, v49, v92
	v_sub_f32_e32 v45, v48, v92
	v_exp_f32_e32 v144, v45
	v_exp_f32_e32 v146, v50
	v_exp_f32_e32 v147, v51
	v_exp_f32_e32 v145, v44
	v_sub_f32_e32 v48, v55, v92
	v_sub_f32_e32 v49, v54, v92
	v_sub_f32_e32 v50, v53, v92
	v_sub_f32_e32 v51, v52, v92
	v_exp_f32_e32 v132, v51
	v_exp_f32_e32 v133, v50
	v_exp_f32_e32 v134, v49
	v_exp_f32_e32 v135, v48
	v_sub_f32_e32 v48, v59, v92
	v_sub_f32_e32 v49, v58, v92
	v_sub_f32_e32 v50, v57, v92
	v_sub_f32_e32 v51, v56, v92
	v_exp_f32_e32 v136, v51
	v_exp_f32_e32 v138, v49
	v_exp_f32_e32 v139, v48
	v_exp_f32_e32 v137, v50
	v_pk_add_f32 v[44:45], v[140:141], 0 op_sel_hi:[1,0]
	v_pk_add_f32 v[46:47], v[142:143], 0 op_sel_hi:[1,0]
	v_pk_add_f32 v[44:45], v[144:145], v[44:45]
	v_pk_add_f32 v[46:47], v[146:147], v[46:47]
	v_pk_add_f32 v[44:45], v[132:133], v[44:45]
	v_pk_add_f32 v[46:47], v[134:135], v[46:47]
	v_pk_add_f32 v[44:45], v[136:137], v[44:45]
	v_pk_add_f32 v[46:47], v[138:139], v[46:47]
	v_add_f32_e32 v44, v44, v45
	v_add_f32_e32 v45, v46, v47
	v_add_f32_e32 v44, v44, v45
	v_mov_b32_e32 v45, v44
	s_nop 1
	v_permlane16_swap_b32_e32 v45, v44
	v_sub_f32_e32 v46, v153, v175
	v_exp_f32_e32 v92, v46
	s_waitcnt lgkmcnt(0)
	v_add_f32_e32 v188, v44, v45
	ds_bpermute_b32 v189, v217, v188
	v_cmp_eq_f32_e32 vcc, 1.0, v92
	s_cmp_lg_u64 vcc, exec
	s_cbranch_scc0 .LBB0_1312
	v_pk_mul_f32 v[58:59], v[2:3], v[92:93] op_sel_hi:[1,0]
	v_pk_mul_f32 v[56:57], v[0:1], v[92:93] op_sel_hi:[1,0]
	v_pk_mul_f32 v[54:55], v[6:7], v[92:93] op_sel_hi:[1,0]
	v_pk_mul_f32 v[52:53], v[4:5], v[92:93] op_sel_hi:[1,0]
	v_pk_mul_f32 v[50:51], v[10:11], v[92:93] op_sel_hi:[1,0]
	v_pk_mul_f32 v[48:49], v[8:9], v[92:93] op_sel_hi:[1,0]
	v_pk_mul_f32 v[46:47], v[14:15], v[92:93] op_sel_hi:[1,0]
	v_pk_mul_f32 v[44:45], v[12:13], v[92:93] op_sel_hi:[1,0]
	s_mov_b64 s[2:3], 0

.LBB0_1315:
	s_and_b64 vcc, exec, s[2:3]
	s_cbranch_vccz .LBB0_1321
	s_waitcnt lgkmcnt(7)
	v_mfma_f32_16x16x32_bf16 v[20:23], v[20:23], v[104:107], 0
	v_lshrrev_b32_e32 v49, 4, v187
	v_lshl_or_b32 v48, v49, 2, s13
	v_cmp_ge_u32_e32 vcc, v48, v186
	s_waitcnt lgkmcnt(6)
	v_mfma_f32_16x16x32_bf16 v[20:23], v[24:27], v[108:111], v[20:23]
	v_cmp_le_i32_e64 s[2:3], v48, v154
	s_and_b64 vcc, vcc, s[2:3]
	v_cmp_lt_i32_e64 s[2:3], v48, v154
	s_waitcnt lgkmcnt(5)
	v_mfma_f32_16x16x32_bf16 v[24:27], v[76:79], v[104:107], 0
	s_waitcnt lgkmcnt(3)
	v_mfma_f32_16x16x32_bf16 v[44:47], v[84:87], v[104:107], 0
	s_waitcnt lgkmcnt(1)
	v_mfma_f32_16x16x32_bf16 v[50:53], v[128:131], v[104:107], 0
	v_mfma_f32_16x16x32_bf16 v[24:27], v[80:83], v[108:111], v[24:27]
	v_mfma_f32_16x16x32_bf16 v[44:47], v[88:91], v[108:111], v[44:47]
	s_waitcnt lgkmcnt(0)
	v_mfma_f32_16x16x32_bf16 v[16:19], v[16:19], v[108:111], v[50:53]
	s_nop 7
	s_nop 7
	s_nop 0
	v_cndmask_b32_e32 v20, v158, v20, vcc
	s_nop 1
	v_or_b32_e32 v50, 1, v48
	v_cmp_ge_u32_e32 vcc, v50, v186
	s_and_b64 vcc, s[2:3], vcc
	v_or_b32_e32 v51, 2, v48
	v_cndmask_b32_e32 v21, v158, v21, vcc
	v_cmp_ge_u32_e32 vcc, v51, v186
	v_cmp_le_i32_e64 s[2:3], v48, v152
	s_and_b64 vcc, s[2:3], vcc
	v_or_b32_e32 v51, 3, v48
	v_cndmask_b32_e32 v22, v158, v22, vcc
	v_cmp_ge_u32_e32 vcc, v51, v186
	v_cmp_le_i32_e64 s[2:3], v51, v154
	s_and_b64 vcc, vcc, s[2:3]
	v_or_b32_e32 v51, 16, v48
	v_cndmask_b32_e32 v23, v158, v23, vcc
	v_cmp_ge_u32_e32 vcc, v51, v186
	v_cmp_le_i32_e64 s[2:3], v51, v154
	s_and_b64 vcc, vcc, s[2:3]
	v_or_b32_e32 v51, 17, v48
	v_cndmask_b32_e32 v24, v158, v24, vcc
	v_cmp_ge_u32_e32 vcc, v51, v186
	v_cmp_le_i32_e64 s[2:3], v51, v154
	s_and_b64 vcc, vcc, s[2:3]
	v_or_b32_e32 v51, 18, v48
	v_cndmask_b32_e32 v25, v158, v25, vcc
	v_cmp_ge_u32_e32 vcc, v51, v186
	v_cmp_le_i32_e64 s[2:3], v51, v154
	s_and_b64 vcc, vcc, s[2:3]
	v_or_b32_e32 v51, 19, v48
	v_cndmask_b32_e32 v26, v158, v26, vcc
	v_cmp_ge_u32_e32 vcc, v51, v186
	v_cmp_le_i32_e64 s[2:3], v51, v154
	s_and_b64 vcc, vcc, s[2:3]
	v_or_b32_e32 v51, 32, v48
	v_cndmask_b32_e32 v27, v158, v27, vcc
	v_cmp_ge_u32_e32 vcc, v51, v186
	v_cmp_le_i32_e64 s[2:3], v51, v154
	s_and_b64 vcc, vcc, s[2:3]
	v_or_b32_e32 v51, 33, v48
	v_cndmask_b32_e32 v44, v158, v44, vcc
	v_cmp_ge_u32_e32 vcc, v51, v186
	v_cmp_le_i32_e64 s[2:3], v51, v154
	s_and_b64 vcc, vcc, s[2:3]
	v_or_b32_e32 v51, 34, v48
	v_cndmask_b32_e32 v45, v158, v45, vcc
	v_cmp_ge_u32_e32 vcc, v51, v186
	v_cmp_le_i32_e64 s[2:3], v51, v154
	s_and_b64 vcc, vcc, s[2:3]
	v_or_b32_e32 v51, 35, v48
	v_cndmask_b32_e32 v46, v158, v46, vcc
	v_cmp_ge_u32_e32 vcc, v51, v186
	v_cmp_le_i32_e64 s[2:3], v51, v154
	s_and_b64 vcc, vcc, s[2:3]
	v_or_b32_e32 v51, 48, v48
	v_cndmask_b32_e32 v47, v158, v47, vcc
	v_cmp_ge_u32_e32 vcc, v51, v186
	v_cmp_le_i32_e64 s[2:3], v51, v154
	s_and_b64 vcc, vcc, s[2:3]
	v_or_b32_e32 v51, 49, v48
	v_max3_f32 v50, v20, s87, v21
	v_cndmask_b32_e32 v16, v158, v16, vcc
	v_cmp_ge_u32_e32 vcc, v51, v186
	v_cmp_le_i32_e64 s[2:3], v51, v154
	v_max3_f32 v50, v50, v22, v23
	s_and_b64 vcc, vcc, s[2:3]
	v_or_b32_e32 v51, 50, v48
	v_max3_f32 v50, v50, v24, v25
	v_cndmask_b32_e32 v17, v158, v17, vcc
	v_cmp_ge_u32_e32 vcc, v51, v186
	v_cmp_le_i32_e64 s[2:3], v51, v154
	v_max3_f32 v50, v50, v26, v27
	s_and_b64 vcc, vcc, s[2:3]
	v_or_b32_e32 v48, 51, v48
	v_max3_f32 v50, v50, v44, v45
	v_cndmask_b32_e32 v18, v158, v18, vcc
	v_cmp_ge_u32_e32 vcc, v48, v186
	v_cmp_le_i32_e64 s[2:3], v48, v154
	v_max3_f32 v50, v50, v46, v47
	s_and_b64 vcc, vcc, s[2:3]
	v_max3_f32 v50, v50, v16, v17
	v_cndmask_b32_e32 v19, v158, v19, vcc
	v_max3_f32 v48, v50, v18, v19
	v_mov_b32_e32 v50, v48
	s_nop 1
	v_permlane16_swap_b32_e32 v50, v48
	s_waitcnt lgkmcnt(0)
	v_max3_f32 v48, v48, v50, v158
	v_mov_b32_e32 v50, v48
	s_nop 1
	v_permlane32_swap_b32_e32 v50, v48
	s_waitcnt lgkmcnt(0)
	v_max3_f32 v48, v48, v50, v158
	v_cmp_lt_f32_e32 vcc, s86, v20
	v_max3_f32 v175, v153, v48, v158
	s_mov_b64 s[2:3], -1
	v_sub_f32_e32 v48, v20, v175
	v_exp_f32_e32 v48, v48
	v_sub_f32_e32 v50, v21, v175
	v_exp_f32_e32 v50, v50
	v_cndmask_b32_e32 v56, 0, v48, vcc
	v_cmp_lt_f32_e32 vcc, s86, v21
	v_sub_f32_e32 v21, v22, v175
	v_exp_f32_e32 v21, v21
	v_cndmask_b32_e32 v57, 0, v50, vcc
	v_sub_f32_e32 v48, v23, v175
	v_cmp_lt_f32_e32 vcc, s86, v22
	v_exp_f32_e32 v48, v48
	v_sub_f32_e32 v22, v25, v175
	v_cndmask_b32_e32 v76, 0, v21, vcc
	v_sub_f32_e32 v21, v24, v175
	v_exp_f32_e32 v21, v21
	v_cmp_lt_f32_e32 vcc, s86, v23
	v_exp_f32_e32 v22, v22
	v_add_f32_e32 v20, 0, v56
	v_cndmask_b32_e32 v77, 0, v48, vcc
	v_cmp_lt_f32_e32 vcc, s86, v24
	v_add_f32_e32 v20, v57, v20
	v_add_f32_e32 v20, v76, v20
	v_cndmask_b32_e32 v78, 0, v21, vcc
	v_sub_f32_e32 v21, v26, v175
	v_exp_f32_e32 v21, v21
	v_cmp_lt_f32_e32 vcc, s86, v25
	v_add_f32_e32 v20, v77, v20
	v_add_f32_e32 v20, v78, v20
	v_cndmask_b32_e32 v79, 0, v22, vcc
	v_sub_f32_e32 v22, v27, v175
	v_cmp_lt_f32_e32 vcc, s86, v26
	v_exp_f32_e32 v22, v22
	v_add_f32_e32 v20, v79, v20
	v_cndmask_b32_e32 v80, 0, v21, vcc
	v_sub_f32_e32 v21, v44, v175
	v_exp_f32_e32 v21, v21
	v_cmp_lt_f32_e32 vcc, s86, v27
	v_add_f32_e32 v20, v80, v20
	s_nop 0
	v_cndmask_b32_e32 v81, 0, v22, vcc
	v_sub_f32_e32 v22, v45, v175
	v_cmp_lt_f32_e32 vcc, s86, v44
	v_exp_f32_e32 v22, v22
	v_add_f32_e32 v20, v81, v20
	v_cndmask_b32_e32 v50, 0, v21, vcc
	v_sub_f32_e32 v21, v46, v175
	v_exp_f32_e32 v21, v21
	v_cmp_lt_f32_e32 vcc, s86, v45
	v_add_f32_e32 v20, v50, v20
	s_nop 0
	v_cndmask_b32_e32 v51, 0, v22, vcc
	v_sub_f32_e32 v22, v47, v175
	v_cmp_lt_f32_e32 vcc, s86, v46
	v_exp_f32_e32 v22, v22
	v_add_f32_e32 v20, v51, v20
	v_cndmask_b32_e32 v52, 0, v21, vcc
	v_sub_f32_e32 v21, v16, v175
	v_exp_f32_e32 v21, v21
	v_cmp_lt_f32_e32 vcc, s86, v47
	v_add_f32_e32 v20, v52, v20
	s_nop 0
	v_cndmask_b32_e32 v53, 0, v22, vcc
	v_sub_f32_e32 v22, v17, v175
	v_cmp_lt_f32_e32 vcc, s86, v16
	v_add_f32_e32 v20, v53, v20
	v_exp_f32_e32 v22, v22
	v_cndmask_b32_e32 v54, 0, v21, vcc
	v_cmp_lt_f32_e32 vcc, s86, v17
	v_sub_f32_e32 v17, v18, v175
	v_add_f32_e32 v16, v54, v20
	v_exp_f32_e32 v17, v17
	v_sub_f32_e32 v20, v19, v175
	v_exp_f32_e32 v20, v20
	v_cndmask_b32_e32 v55, 0, v22, vcc
	v_cmp_lt_f32_e32 vcc, s86, v18
	v_add_f32_e32 v16, v55, v16
	v_sub_f32_e32 v18, v153, v175
	v_cndmask_b32_e32 v58, 0, v17, vcc
	v_cmp_lt_f32_e32 vcc, s86, v19
	v_add_f32_e32 v16, v58, v16
	v_exp_f32_e32 v48, v18
	v_cndmask_b32_e32 v59, 0, v20, vcc
	v_add_f32_e32 v16, v59, v16
	v_mov_b32_e32 v17, v16
	s_nop 1
	v_permlane16_swap_b32_e32 v17, v16
	v_cmp_eq_f32_e32 vcc, 1.0, v48
	s_cmp_lg_u64 vcc, exec
	s_waitcnt lgkmcnt(0)
	v_add_f32_e32 v82, v16, v17
	ds_bpermute_b32 v83, v217, v82
	s_cbranch_scc0 .LBB0_1318
	v_pk_mul_f32 v[46:47], v[2:3], v[48:49] op_sel_hi:[1,0]
	v_pk_mul_f32 v[44:45], v[0:1], v[48:49] op_sel_hi:[1,0]
	v_pk_mul_f32 v[26:27], v[6:7], v[48:49] op_sel_hi:[1,0]
	v_pk_mul_f32 v[24:25], v[4:5], v[48:49] op_sel_hi:[1,0]
	v_pk_mul_f32 v[22:23], v[10:11], v[48:49] op_sel_hi:[1,0]
	v_pk_mul_f32 v[20:21], v[8:9], v[48:49] op_sel_hi:[1,0]
	v_pk_mul_f32 v[18:19], v[14:15], v[48:49] op_sel_hi:[1,0]
	v_pk_mul_f32 v[16:17], v[12:13], v[48:49] op_sel_hi:[1,0]
	s_mov_b64 s[2:3], 0

.LBB0_1322:
	s_andn2_b64 vcc, exec, s[74:75]
	s_cbranch_vccnz .LBB0_1328
	v_mad_u32_u24 v44, v185, s88, v184
	s_waitcnt lgkmcnt(0)
	ds_read_b128 v[16:19], v44
	ds_read_b128 v[24:27], v44 offset:64
	ds_read_b128 v[20:23], v44 offset:2304
	v_mad_u32_u24 v48, v183, s88, v184
	s_mov_b64 s[2:3], -1
	s_waitcnt lgkmcnt(2)
	v_mfma_f32_16x16x32_bf16 v[16:19], v[16:19], v[104:107], 0
	s_waitcnt lgkmcnt(1)
	v_mfma_f32_16x16x32_bf16 v[16:19], v[24:27], v[108:111], v[16:19]
	ds_read_b128 v[24:27], v44 offset:2368
	s_waitcnt lgkmcnt(1)
	v_mfma_f32_16x16x32_bf16 v[20:23], v[20:23], v[104:107], 0
	s_waitcnt lgkmcnt(0)
	v_mfma_f32_16x16x32_bf16 v[20:23], v[24:27], v[108:111], v[20:23]
	ds_read_b128 v[24:27], v44 offset:4608
	ds_read_b128 v[44:47], v44 offset:4672
	s_waitcnt lgkmcnt(1)
	v_mfma_f32_16x16x32_bf16 v[24:27], v[24:27], v[104:107], 0
	s_waitcnt lgkmcnt(0)
	v_mfma_f32_16x16x32_bf16 v[24:27], v[44:47], v[108:111], v[24:27]
	ds_read_b128 v[44:47], v48
	ds_read_b128 v[48:51], v48 offset:64
	s_waitcnt lgkmcnt(1)
	v_mfma_f32_16x16x32_bf16 v[44:47], v[44:47], v[104:107], 0
	s_waitcnt lgkmcnt(0)
	v_mfma_f32_16x16x32_bf16 v[44:47], v[48:51], v[108:111], v[44:47]
	s_nop 7
	s_nop 7
	s_nop 0
	v_max3_f32 v48, v158, v16, v17
	s_nop 0
	v_max3_f32 v48, v48, v18, v19
	s_nop 0
	v_max3_f32 v48, v48, v20, v21
	s_nop 0
	v_max3_f32 v48, v48, v22, v23
	s_nop 0
	v_max3_f32 v48, v48, v24, v25
	s_nop 0
	v_max3_f32 v48, v48, v26, v27
	s_nop 0
	v_max3_f32 v48, v48, v44, v45
	s_nop 0
	v_max3_f32 v48, v48, v46, v47
	v_mov_b32_e32 v49, v48
	s_nop 1
	v_permlane16_swap_b32_e32 v49, v48
	s_waitcnt lgkmcnt(0)
	v_max3_f32 v48, v48, v49, v158
	v_mov_b32_e32 v49, v48
	s_nop 1
	v_permlane32_swap_b32_e32 v49, v48
	s_waitcnt lgkmcnt(0)
	v_max3_f32 v48, v48, v49, v158
	s_nop 0
	v_max3_f32 v175, v153, v48, v158
	s_nop 0
	v_sub_f32_e32 v19, v19, v175
	v_sub_f32_e32 v18, v18, v175
	v_sub_f32_e32 v17, v17, v175
	v_sub_f32_e32 v16, v16, v175
	v_sub_f32_e32 v23, v23, v175
	v_sub_f32_e32 v22, v22, v175
	v_exp_f32_e32 v56, v16
	v_exp_f32_e32 v57, v17
	v_exp_f32_e32 v58, v18
	v_exp_f32_e32 v59, v19
	v_sub_f32_e32 v16, v21, v175
	v_sub_f32_e32 v17, v20, v175
	v_exp_f32_e32 v76, v17
	v_exp_f32_e32 v78, v22
	v_exp_f32_e32 v79, v23
	v_exp_f32_e32 v77, v16
	v_sub_f32_e32 v20, v27, v175
	v_sub_f32_e32 v21, v26, v175
	v_sub_f32_e32 v22, v25, v175
	v_sub_f32_e32 v23, v24, v175
	v_exp_f32_e32 v48, v23
	v_exp_f32_e32 v49, v22
	v_exp_f32_e32 v50, v21
	v_exp_f32_e32 v51, v20
	v_sub_f32_e32 v20, v47, v175
	v_sub_f32_e32 v21, v46, v175
	v_sub_f32_e32 v22, v45, v175
	v_sub_f32_e32 v23, v44, v175
	v_exp_f32_e32 v52, v23
	v_exp_f32_e32 v54, v21
	v_exp_f32_e32 v55, v20
	v_exp_f32_e32 v53, v22
	v_pk_add_f32 v[16:17], v[56:57], 0 op_sel_hi:[1,0]
	v_pk_add_f32 v[18:19], v[58:59], 0 op_sel_hi:[1,0]
	v_pk_add_f32 v[16:17], v[76:77], v[16:17]
	v_pk_add_f32 v[18:19], v[78:79], v[18:19]
	v_pk_add_f32 v[16:17], v[48:49], v[16:17]
	v_pk_add_f32 v[18:19], v[50:51], v[18:19]
	v_pk_add_f32 v[16:17], v[52:53], v[16:17]
	v_pk_add_f32 v[18:19], v[54:55], v[18:19]
	v_add_f32_e32 v16, v16, v17
	v_add_f32_e32 v17, v18, v19
	v_add_f32_e32 v16, v16, v17
	v_mov_b32_e32 v17, v16
	s_nop 1
	v_permlane16_swap_b32_e32 v17, v16
	v_sub_f32_e32 v18, v153, v175
	v_exp_f32_e32 v80, v18
	s_waitcnt lgkmcnt(0)
	v_add_f32_e32 v81, v16, v17
	ds_bpermute_b32 v82, v217, v81
	v_cmp_eq_f32_e32 vcc, 1.0, v80
	s_cmp_lg_u64 vcc, exec
	s_cbranch_scc0 .LBB0_1325
	v_pk_mul_f32 v[46:47], v[2:3], v[80:81] op_sel_hi:[1,0]
	v_pk_mul_f32 v[44:45], v[0:1], v[80:81] op_sel_hi:[1,0]
	v_pk_mul_f32 v[26:27], v[6:7], v[80:81] op_sel_hi:[1,0]
	v_pk_mul_f32 v[24:25], v[4:5], v[80:81] op_sel_hi:[1,0]
	v_pk_mul_f32 v[22:23], v[10:11], v[80:81] op_sel_hi:[1,0]
	v_pk_mul_f32 v[20:21], v[8:9], v[80:81] op_sel_hi:[1,0]
	v_pk_mul_f32 v[18:19], v[14:15], v[80:81] op_sel_hi:[1,0]
	v_pk_mul_f32 v[16:17], v[12:13], v[80:81] op_sel_hi:[1,0]
	s_mov_b64 s[2:3], 0

.LBB0_1331:
	s_lshl_b32 s13, s4, 6
	s_lshl_b32 s4, 1, s4
	v_and_b32_e32 v0, s4, v172
	v_cmp_ne_u32_e32 vcc, 0, v0
	s_cmp_eq_u64 vcc, 0
	s_cselect_b64 s[2:3], -1, 0
	s_cmp_gt_i32 s13, s76
	s_cselect_b64 s[14:15], -1, 0
	s_or_b64 s[2:3], s[2:3], s[14:15]
	v_mov_b32_e32 v222, v196
	s_and_b64 vcc, exec, s[2:3]
	s_cbranch_vccnz .LBB0_1353
	v_cmp_eq_u32_e32 vcc, 0, v0
	s_or_b32 s14, s13, 63
	v_cmp_le_i32_e64 s[74:75], s14, v152
	v_cndmask_b32_e32 v227, 0, v211, vcc
	v_cmp_ge_u32_e64 s[2:3], s13, v227
	s_and_b64 s[2:3], s[2:3], s[74:75]
	v_and_b32_e32 v228, 63, v222
	v_cndmask_b32_e64 v0, 0, 1, s[2:3]
	v_cmp_ne_u32_e64 s[2:3], 0, v0
	v_and_b32_e32 v226, 15, v222
	v_and_b32_e32 v0, 48, v222
	v_or_b32_e32 v224, 48, v228
	s_mov_b64 s[74:75], -1
	s_cmp_lg_u64 s[2:3], exec
	v_add_u32_e32 v225, s96, v0
	v_mul_u32_u24_e32 v223, 0x90, v226
	v_mul_u32_u24_e32 v153, 0x90, v224
	s_cbranch_scc0 .LBB0_1346
	v_mad_u32_u24 v0, v226, s88, v225
	ds_read_b128 v[4:7], v0 offset:9216
	ds_read_b128 v[8:11], v0 offset:9280
	ds_read_b128 v[56:59], v0 offset:11520
	ds_read_b128 v[128:131], v0 offset:11584
	ds_read_b128 v[132:135], v0 offset:13824
	ds_read_b128 v[136:139], v0 offset:13888
	v_mad_u32_u24 v0, v224, s88, v225
	ds_read_b128 v[140:143], v0 offset:9216
	ds_read_b128 v[0:3], v0 offset:9280
	s_cmp_gt_i32 s14, s78
	s_mov_b64 s[2:3], -1
	s_cbranch_scc1 .LBB0_1339
	s_waitcnt lgkmcnt(7)
	v_mfma_f32_16x16x32_bf16 v[16:19], v[4:7], v[96:99], 0
	s_waitcnt lgkmcnt(5)
	v_mfma_f32_16x16x32_bf16 v[20:23], v[56:59], v[96:99], 0
	s_waitcnt lgkmcnt(3)
	v_mfma_f32_16x16x32_bf16 v[24:27], v[132:135], v[96:99], 0
	s_waitcnt lgkmcnt(1)
	v_mfma_f32_16x16x32_bf16 v[144:147], v[140:143], v[96:99], 0
	v_mfma_f32_16x16x32_bf16 v[16:19], v[8:11], v[100:103], v[16:19]
	v_mfma_f32_16x16x32_bf16 v[20:23], v[128:131], v[100:103], v[20:23]
	v_mfma_f32_16x16x32_bf16 v[24:27], v[136:139], v[100:103], v[24:27]
	s_waitcnt lgkmcnt(0)
	v_mfma_f32_16x16x32_bf16 v[144:147], v[0:3], v[100:103], v[144:147]
	s_nop 7
	s_nop 7
	s_nop 0
	v_max3_f32 v92, v158, v16, v17
	s_nop 0
	v_max3_f32 v92, v92, v18, v19
	s_nop 0
	v_max3_f32 v92, v92, v20, v21
	s_nop 0
	v_max3_f32 v92, v92, v22, v23
	s_nop 0
	v_max3_f32 v92, v92, v24, v25
	s_nop 0
	v_max3_f32 v92, v92, v26, v27
	s_nop 0
	v_max3_f32 v92, v92, v144, v145
	s_nop 0
	v_max3_f32 v92, v92, v146, v147
	s_nop 0
	v_cndmask_b32_e32 v92, v92, v158, vcc
	v_mov_b32_e32 v155, v92
	s_nop 1
	v_permlane16_swap_b32_e32 v155, v92
	s_waitcnt lgkmcnt(0)
	v_max3_f32 v92, v92, v155, v158
	v_mov_b32_e32 v155, v92
	s_nop 1
	v_permlane32_swap_b32_e32 v155, v92
	s_waitcnt lgkmcnt(0)
	v_max3_f32 v92, v92, v155, v158
	s_nop 0
	v_max3_f32 v155, v163, v92, v158
	s_nop 0
	v_cndmask_b32_e32 v92, v155, v212, vcc
	v_sub_f32_e32 v19, v19, v92
	v_sub_f32_e32 v18, v18, v92
	v_sub_f32_e32 v17, v17, v92
	v_sub_f32_e32 v16, v16, v92
	v_sub_f32_e32 v23, v23, v92
	v_sub_f32_e32 v22, v22, v92
	v_exp_f32_e32 v188, v16
	v_exp_f32_e32 v189, v17
	v_exp_f32_e32 v190, v18
	v_exp_f32_e32 v191, v19
	v_sub_f32_e32 v16, v21, v92
	v_sub_f32_e32 v17, v20, v92
	v_exp_f32_e32 v192, v17
	v_exp_f32_e32 v194, v22
	v_exp_f32_e32 v195, v23
	v_exp_f32_e32 v193, v16
	v_sub_f32_e32 v20, v27, v92
	v_sub_f32_e32 v21, v26, v92
	v_sub_f32_e32 v22, v25, v92
	v_sub_f32_e32 v23, v24, v92
	v_exp_f32_e32 v180, v23
	v_exp_f32_e32 v181, v22
	v_exp_f32_e32 v182, v21
	v_exp_f32_e32 v183, v20
	v_sub_f32_e32 v20, v147, v92
	v_sub_f32_e32 v21, v146, v92
	v_sub_f32_e32 v22, v145, v92
	v_sub_f32_e32 v23, v144, v92
	v_exp_f32_e32 v184, v23
	v_exp_f32_e32 v186, v21
	v_exp_f32_e32 v187, v20
	v_exp_f32_e32 v185, v22
	v_pk_add_f32 v[16:17], v[188:189], 0 op_sel_hi:[1,0]
	v_pk_add_f32 v[18:19], v[190:191], 0 op_sel_hi:[1,0]
	v_pk_add_f32 v[16:17], v[192:193], v[16:17]
	v_pk_add_f32 v[18:19], v[194:195], v[18:19]
	v_pk_add_f32 v[16:17], v[180:181], v[16:17]
	v_pk_add_f32 v[18:19], v[182:183], v[18:19]
	v_pk_add_f32 v[16:17], v[184:185], v[16:17]
	v_pk_add_f32 v[18:19], v[186:187], v[18:19]
	v_add_f32_e32 v16, v16, v17
	v_add_f32_e32 v17, v18, v19
	v_add_f32_e32 v16, v16, v17
	v_mov_b32_e32 v17, v16
	s_nop 1
	v_permlane16_swap_b32_e32 v17, v16
	v_sub_f32_e32 v18, v163, v155
	v_exp_f32_e32 v92, v18
	s_waitcnt lgkmcnt(0)
	v_add_f32_e32 v219, v16, v17
	ds_bpermute_b32 v229, v217, v219
	v_cmp_eq_f32_e32 vcc, 1.0, v92
	s_cmp_lg_u64 vcc, exec
	s_cbranch_scc0 .LBB0_1336
	v_pk_mul_f32 v[146:147], v[62:63], v[92:93] op_sel_hi:[1,0]
	v_pk_mul_f32 v[144:145], v[60:61], v[92:93] op_sel_hi:[1,0]
	v_pk_mul_f32 v[26:27], v[66:67], v[92:93] op_sel_hi:[1,0]
	v_pk_mul_f32 v[24:25], v[64:65], v[92:93] op_sel_hi:[1,0]
	v_pk_mul_f32 v[22:23], v[70:71], v[92:93] op_sel_hi:[1,0]
	v_pk_mul_f32 v[20:21], v[68:69], v[92:93] op_sel_hi:[1,0]
	v_pk_mul_f32 v[18:19], v[74:75], v[92:93] op_sel_hi:[1,0]
	v_pk_mul_f32 v[16:17], v[72:73], v[92:93] op_sel_hi:[1,0]
	s_mov_b64 s[2:3], 0

.LBB0_1339:
	s_and_b64 vcc, exec, s[2:3]
	s_cbranch_vccz .LBB0_1345
	s_waitcnt lgkmcnt(7)
	v_mfma_f32_16x16x32_bf16 v[4:7], v[4:7], v[96:99], 0
	v_lshrrev_b32_e32 v21, 4, v228
	v_lshl_or_b32 v20, v21, 2, s13
	v_cmp_ge_u32_e32 vcc, v20, v227
	s_waitcnt lgkmcnt(6)
	v_mfma_f32_16x16x32_bf16 v[4:7], v[8:11], v[100:103], v[4:7]
	v_cmp_le_i32_e64 s[2:3], v20, v152
	s_and_b64 vcc, vcc, s[2:3]
	v_cmp_lt_i32_e64 s[2:3], v20, v152
	s_waitcnt lgkmcnt(5)
	v_mfma_f32_16x16x32_bf16 v[8:11], v[56:59], v[96:99], 0
	s_waitcnt lgkmcnt(3)
	v_mfma_f32_16x16x32_bf16 v[16:19], v[132:135], v[96:99], 0
	s_waitcnt lgkmcnt(1)
	v_mfma_f32_16x16x32_bf16 v[22:25], v[140:143], v[96:99], 0
	v_mfma_f32_16x16x32_bf16 v[8:11], v[128:131], v[100:103], v[8:11]
	v_mfma_f32_16x16x32_bf16 v[16:19], v[136:139], v[100:103], v[16:19]
	s_waitcnt lgkmcnt(0)
	v_mfma_f32_16x16x32_bf16 v[0:3], v[0:3], v[100:103], v[22:25]
	s_nop 7
	s_nop 7
	s_nop 0
	v_cndmask_b32_e32 v4, v158, v4, vcc
	s_nop 1
	v_or_b32_e32 v22, 1, v20
	v_cmp_ge_u32_e32 vcc, v22, v227
	s_and_b64 vcc, s[2:3], vcc
	v_or_b32_e32 v23, 2, v20
	v_cndmask_b32_e32 v5, v158, v5, vcc
	v_cmp_ge_u32_e32 vcc, v23, v227
	v_cmp_le_i32_e64 s[2:3], v23, v152
	s_and_b64 vcc, vcc, s[2:3]
	v_or_b32_e32 v23, 3, v20
	v_cndmask_b32_e32 v6, v158, v6, vcc
	v_cmp_ge_u32_e32 vcc, v23, v227
	v_cmp_le_i32_e64 s[2:3], v23, v152
	s_and_b64 vcc, vcc, s[2:3]
	v_or_b32_e32 v23, 16, v20
	v_cndmask_b32_e32 v7, v158, v7, vcc
	v_cmp_ge_u32_e32 vcc, v23, v227
	v_cmp_le_i32_e64 s[2:3], v23, v152
	s_and_b64 vcc, vcc, s[2:3]
	v_or_b32_e32 v23, 17, v20
	v_cndmask_b32_e32 v8, v158, v8, vcc
	v_cmp_ge_u32_e32 vcc, v23, v227
	v_cmp_le_i32_e64 s[2:3], v23, v152
	s_and_b64 vcc, vcc, s[2:3]
	v_or_b32_e32 v23, 18, v20
	v_cndmask_b32_e32 v9, v158, v9, vcc
	v_cmp_ge_u32_e32 vcc, v23, v227
	v_cmp_le_i32_e64 s[2:3], v23, v152
	s_and_b64 vcc, vcc, s[2:3]
	v_or_b32_e32 v23, 19, v20
	v_cndmask_b32_e32 v10, v158, v10, vcc
	v_cmp_ge_u32_e32 vcc, v23, v227
	v_cmp_le_i32_e64 s[2:3], v23, v152
	s_and_b64 vcc, vcc, s[2:3]
	v_or_b32_e32 v23, 32, v20
	v_cndmask_b32_e32 v11, v158, v11, vcc
	v_cmp_ge_u32_e32 vcc, v23, v227
	v_cmp_le_i32_e64 s[2:3], v23, v152
	s_and_b64 vcc, vcc, s[2:3]
	v_or_b32_e32 v23, 33, v20
	v_cndmask_b32_e32 v16, v158, v16, vcc
	v_cmp_ge_u32_e32 vcc, v23, v227
	v_cmp_le_i32_e64 s[2:3], v23, v152
	s_and_b64 vcc, vcc, s[2:3]
	v_or_b32_e32 v23, 34, v20
	v_cndmask_b32_e32 v17, v158, v17, vcc
	v_cmp_ge_u32_e32 vcc, v23, v227
	v_cmp_le_i32_e64 s[2:3], v23, v152
	s_and_b64 vcc, vcc, s[2:3]
	v_or_b32_e32 v23, 35, v20
	v_cndmask_b32_e32 v18, v158, v18, vcc
	v_cmp_ge_u32_e32 vcc, v23, v227
	v_cmp_le_i32_e64 s[2:3], v23, v152
	s_and_b64 vcc, vcc, s[2:3]
	v_or_b32_e32 v23, 48, v20
	v_cndmask_b32_e32 v19, v158, v19, vcc
	v_cmp_ge_u32_e32 vcc, v23, v227
	v_cmp_le_i32_e64 s[2:3], v23, v152
	s_and_b64 vcc, vcc, s[2:3]
	v_or_b32_e32 v23, 49, v20
	v_max3_f32 v22, v4, s87, v5
	v_cndmask_b32_e32 v0, v158, v0, vcc
	v_cmp_ge_u32_e32 vcc, v23, v227
	v_cmp_le_i32_e64 s[2:3], v23, v152
	v_max3_f32 v22, v22, v6, v7
	s_and_b64 vcc, vcc, s[2:3]
	v_or_b32_e32 v23, 50, v20
	v_max3_f32 v22, v22, v8, v9
	v_cndmask_b32_e32 v1, v158, v1, vcc
	v_cmp_ge_u32_e32 vcc, v23, v227
	v_cmp_le_i32_e64 s[2:3], v23, v152
	v_max3_f32 v22, v22, v10, v11
	s_and_b64 vcc, vcc, s[2:3]
	v_or_b32_e32 v20, 51, v20
	v_max3_f32 v22, v22, v16, v17
	v_cndmask_b32_e32 v2, v158, v2, vcc
	v_cmp_ge_u32_e32 vcc, v20, v227
	v_cmp_le_i32_e64 s[2:3], v20, v152
	v_max3_f32 v22, v22, v18, v19
	s_and_b64 vcc, vcc, s[2:3]
	v_max3_f32 v22, v22, v0, v1
	v_cndmask_b32_e32 v3, v158, v3, vcc
	v_max3_f32 v20, v22, v2, v3
	v_mov_b32_e32 v22, v20
	s_nop 1
	v_permlane16_swap_b32_e32 v22, v20
	s_waitcnt lgkmcnt(0)
	v_max3_f32 v20, v20, v22, v158
	v_mov_b32_e32 v22, v20
	s_nop 1
	v_permlane32_swap_b32_e32 v22, v20
	s_waitcnt lgkmcnt(0)
	v_max3_f32 v20, v20, v22, v158
	v_cmp_lt_f32_e32 vcc, s86, v4
	v_max3_f32 v155, v163, v20, v158
	s_mov_b64 s[2:3], -1
	v_sub_f32_e32 v20, v4, v155
	v_exp_f32_e32 v20, v20
	v_sub_f32_e32 v22, v5, v155
	v_exp_f32_e32 v22, v22
	v_cndmask_b32_e32 v56, 0, v20, vcc
	v_cmp_lt_f32_e32 vcc, s86, v5
	v_sub_f32_e32 v5, v6, v155
	v_exp_f32_e32 v5, v5
	v_cndmask_b32_e32 v57, 0, v22, vcc
	v_sub_f32_e32 v20, v7, v155
	v_cmp_lt_f32_e32 vcc, s86, v6
	v_exp_f32_e32 v20, v20
	v_sub_f32_e32 v6, v9, v155
	v_cndmask_b32_e32 v92, 0, v5, vcc
	v_sub_f32_e32 v5, v8, v155
	v_exp_f32_e32 v5, v5
	v_cmp_lt_f32_e32 vcc, s86, v7
	v_exp_f32_e32 v6, v6
	v_add_f32_e32 v4, 0, v56
	v_cndmask_b32_e32 v128, 0, v20, vcc
	v_cmp_lt_f32_e32 vcc, s86, v8
	v_add_f32_e32 v4, v57, v4
	v_add_f32_e32 v4, v92, v4
	v_cndmask_b32_e32 v129, 0, v5, vcc
	v_sub_f32_e32 v5, v10, v155
	v_exp_f32_e32 v5, v5
	v_cmp_lt_f32_e32 vcc, s86, v9
	v_add_f32_e32 v4, v128, v4
	v_add_f32_e32 v4, v129, v4
	v_cndmask_b32_e32 v130, 0, v6, vcc
	v_sub_f32_e32 v6, v11, v155
	v_cmp_lt_f32_e32 vcc, s86, v10
	v_exp_f32_e32 v6, v6
	v_add_f32_e32 v4, v130, v4
	v_cndmask_b32_e32 v131, 0, v5, vcc
	v_sub_f32_e32 v5, v16, v155
	v_exp_f32_e32 v5, v5
	v_cmp_lt_f32_e32 vcc, s86, v11
	v_add_f32_e32 v4, v131, v4
	s_nop 0
	v_cndmask_b32_e32 v132, 0, v6, vcc
	v_sub_f32_e32 v6, v17, v155
	v_cmp_lt_f32_e32 vcc, s86, v16
	v_exp_f32_e32 v6, v6
	v_add_f32_e32 v4, v132, v4
	v_cndmask_b32_e32 v22, 0, v5, vcc
	v_sub_f32_e32 v5, v18, v155
	v_exp_f32_e32 v5, v5
	v_cmp_lt_f32_e32 vcc, s86, v17
	v_add_f32_e32 v4, v22, v4
	s_nop 0
	v_cndmask_b32_e32 v23, 0, v6, vcc
	v_sub_f32_e32 v6, v19, v155
	v_cmp_lt_f32_e32 vcc, s86, v18
	v_exp_f32_e32 v6, v6
	v_add_f32_e32 v4, v23, v4
	v_cndmask_b32_e32 v24, 0, v5, vcc
	v_sub_f32_e32 v5, v0, v155
	v_exp_f32_e32 v5, v5
	v_cmp_lt_f32_e32 vcc, s86, v19
	v_add_f32_e32 v4, v24, v4
	s_nop 0
	v_cndmask_b32_e32 v25, 0, v6, vcc
	v_sub_f32_e32 v6, v1, v155
	v_cmp_lt_f32_e32 vcc, s86, v0
	v_add_f32_e32 v4, v25, v4
	v_exp_f32_e32 v6, v6
	v_cndmask_b32_e32 v26, 0, v5, vcc
	v_cmp_lt_f32_e32 vcc, s86, v1
	v_sub_f32_e32 v1, v2, v155
	v_add_f32_e32 v0, v26, v4
	v_exp_f32_e32 v1, v1
	v_sub_f32_e32 v4, v3, v155
	v_exp_f32_e32 v4, v4
	v_cndmask_b32_e32 v27, 0, v6, vcc
	v_cmp_lt_f32_e32 vcc, s86, v2
	v_add_f32_e32 v0, v27, v0
	v_sub_f32_e32 v2, v163, v155
	v_cndmask_b32_e32 v58, 0, v1, vcc
	v_cmp_lt_f32_e32 vcc, s86, v3
	v_add_f32_e32 v0, v58, v0
	v_exp_f32_e32 v20, v2
	v_cndmask_b32_e32 v59, 0, v4, vcc
	v_add_f32_e32 v0, v59, v0
	v_mov_b32_e32 v1, v0
	s_nop 1
	v_permlane16_swap_b32_e32 v1, v0
	v_cmp_eq_f32_e32 vcc, 1.0, v20
	s_cmp_lg_u64 vcc, exec
	s_waitcnt lgkmcnt(0)
	v_add_f32_e32 v133, v0, v1
	ds_bpermute_b32 v134, v217, v133
	s_cbranch_scc0 .LBB0_1342
	v_pk_mul_f32 v[18:19], v[62:63], v[20:21] op_sel_hi:[1,0]
	v_pk_mul_f32 v[16:17], v[60:61], v[20:21] op_sel_hi:[1,0]
	v_pk_mul_f32 v[10:11], v[66:67], v[20:21] op_sel_hi:[1,0]
	v_pk_mul_f32 v[8:9], v[64:65], v[20:21] op_sel_hi:[1,0]
	v_pk_mul_f32 v[6:7], v[70:71], v[20:21] op_sel_hi:[1,0]
	v_pk_mul_f32 v[4:5], v[68:69], v[20:21] op_sel_hi:[1,0]
	v_pk_mul_f32 v[2:3], v[74:75], v[20:21] op_sel_hi:[1,0]
	v_pk_mul_f32 v[0:1], v[72:73], v[20:21] op_sel_hi:[1,0]
	s_mov_b64 s[2:3], 0

.LBB0_1346:
	s_andn2_b64 vcc, exec, s[74:75]
	s_cbranch_vccnz .LBB0_1352
	v_mad_u32_u24 v16, v226, s88, v225
	s_waitcnt lgkmcnt(0)
	ds_read_b128 v[0:3], v16 offset:9216
	ds_read_b128 v[8:11], v16 offset:9280
	ds_read_b128 v[4:7], v16 offset:11520
	v_mad_u32_u24 v20, v224, s88, v225
	s_mov_b64 s[2:3], -1
	s_waitcnt lgkmcnt(2)
	v_mfma_f32_16x16x32_bf16 v[0:3], v[0:3], v[96:99], 0
	s_waitcnt lgkmcnt(1)
	v_mfma_f32_16x16x32_bf16 v[0:3], v[8:11], v[100:103], v[0:3]
	ds_read_b128 v[8:11], v16 offset:11584
	s_waitcnt lgkmcnt(1)
	v_mfma_f32_16x16x32_bf16 v[4:7], v[4:7], v[96:99], 0
	s_waitcnt lgkmcnt(0)
	v_mfma_f32_16x16x32_bf16 v[4:7], v[8:11], v[100:103], v[4:7]
	ds_read_b128 v[8:11], v16 offset:13824
	ds_read_b128 v[16:19], v16 offset:13888
	s_waitcnt lgkmcnt(1)
	v_mfma_f32_16x16x32_bf16 v[8:11], v[8:11], v[96:99], 0
	s_waitcnt lgkmcnt(0)
	v_mfma_f32_16x16x32_bf16 v[8:11], v[16:19], v[100:103], v[8:11]
	ds_read_b128 v[16:19], v20 offset:9216
	ds_read_b128 v[20:23], v20 offset:9280
	s_waitcnt lgkmcnt(1)
	v_mfma_f32_16x16x32_bf16 v[16:19], v[16:19], v[96:99], 0
	s_waitcnt lgkmcnt(0)
	v_mfma_f32_16x16x32_bf16 v[16:19], v[20:23], v[100:103], v[16:19]
	s_nop 7
	s_nop 7
	s_nop 0
	v_max3_f32 v20, v158, v0, v1
	s_nop 0
	v_max3_f32 v20, v20, v2, v3
	s_nop 0
	v_max3_f32 v20, v20, v4, v5
	s_nop 0
	v_max3_f32 v20, v20, v6, v7
	s_nop 0
	v_max3_f32 v20, v20, v8, v9
	s_nop 0
	v_max3_f32 v20, v20, v10, v11
	s_nop 0
	v_max3_f32 v20, v20, v16, v17
	s_nop 0
	v_max3_f32 v20, v20, v18, v19
	v_mov_b32_e32 v21, v20
	s_nop 1
	v_permlane16_swap_b32_e32 v21, v20
	s_waitcnt lgkmcnt(0)
	v_max3_f32 v20, v20, v21, v158
	v_mov_b32_e32 v21, v20
	s_nop 1
	v_permlane32_swap_b32_e32 v21, v20
	s_waitcnt lgkmcnt(0)
	v_max3_f32 v20, v20, v21, v158
	s_nop 0
	v_max3_f32 v155, v163, v20, v158
	s_nop 0
	v_sub_f32_e32 v3, v3, v155
	v_sub_f32_e32 v2, v2, v155
	v_sub_f32_e32 v1, v1, v155
	v_sub_f32_e32 v0, v0, v155
	v_sub_f32_e32 v7, v7, v155
	v_sub_f32_e32 v6, v6, v155
	v_exp_f32_e32 v56, v0
	v_exp_f32_e32 v57, v1
	v_exp_f32_e32 v58, v2
	v_exp_f32_e32 v59, v3
	v_sub_f32_e32 v0, v5, v155
	v_sub_f32_e32 v1, v4, v155
	v_exp_f32_e32 v128, v1
	v_exp_f32_e32 v130, v6
	v_exp_f32_e32 v131, v7
	v_exp_f32_e32 v129, v0
	v_sub_f32_e32 v4, v11, v155
	v_sub_f32_e32 v5, v10, v155
	v_sub_f32_e32 v6, v9, v155
	v_sub_f32_e32 v7, v8, v155
	v_exp_f32_e32 v20, v7
	v_exp_f32_e32 v21, v6
	v_exp_f32_e32 v22, v5
	v_exp_f32_e32 v23, v4
	v_sub_f32_e32 v4, v19, v155
	v_sub_f32_e32 v5, v18, v155
	v_sub_f32_e32 v6, v17, v155
	v_sub_f32_e32 v7, v16, v155
	v_exp_f32_e32 v24, v7
	v_exp_f32_e32 v26, v5
	v_exp_f32_e32 v27, v4
	v_exp_f32_e32 v25, v6
	v_pk_add_f32 v[0:1], v[56:57], 0 op_sel_hi:[1,0]
	v_pk_add_f32 v[2:3], v[58:59], 0 op_sel_hi:[1,0]
	v_pk_add_f32 v[0:1], v[128:129], v[0:1]
	v_pk_add_f32 v[2:3], v[130:131], v[2:3]
	v_pk_add_f32 v[0:1], v[20:21], v[0:1]
	v_pk_add_f32 v[2:3], v[22:23], v[2:3]
	v_pk_add_f32 v[0:1], v[24:25], v[0:1]
	v_pk_add_f32 v[2:3], v[26:27], v[2:3]
	v_add_f32_e32 v0, v0, v1
	v_add_f32_e32 v1, v2, v3
	v_add_f32_e32 v0, v0, v1
	v_mov_b32_e32 v1, v0
	s_nop 1
	v_permlane16_swap_b32_e32 v1, v0
	v_sub_f32_e32 v2, v163, v155
	v_exp_f32_e32 v92, v2
	s_waitcnt lgkmcnt(0)
	v_add_f32_e32 v132, v0, v1
	ds_bpermute_b32 v133, v217, v132
	v_cmp_eq_f32_e32 vcc, 1.0, v92
	s_cmp_lg_u64 vcc, exec
	s_cbranch_scc0 .LBB0_1349
	v_pk_mul_f32 v[18:19], v[62:63], v[92:93] op_sel_hi:[1,0]
	v_pk_mul_f32 v[16:17], v[60:61], v[92:93] op_sel_hi:[1,0]
	v_pk_mul_f32 v[10:11], v[66:67], v[92:93] op_sel_hi:[1,0]
	v_pk_mul_f32 v[8:9], v[64:65], v[92:93] op_sel_hi:[1,0]
	v_pk_mul_f32 v[6:7], v[70:71], v[92:93] op_sel_hi:[1,0]
	v_pk_mul_f32 v[4:5], v[68:69], v[92:93] op_sel_hi:[1,0]
	v_pk_mul_f32 v[2:3], v[74:75], v[92:93] op_sel_hi:[1,0]
	v_pk_mul_f32 v[0:1], v[72:73], v[92:93] op_sel_hi:[1,0]
	s_mov_b64 s[2:3], 0

.LBB0_1354:
	s_waitcnt lgkmcnt(0)
	v_and_b32_e32 v0, s4, v173
	v_cmp_ne_u32_e32 vcc, 0, v0
	s_cmp_eq_u64 vcc, 0
	s_cselect_b64 s[2:3], -1, 0
	s_cmp_gt_i32 s13, s77
	s_cselect_b64 s[14:15], -1, 0
	s_or_b64 s[2:3], s[2:3], s[14:15]
	v_mov_b32_e32 v181, v196
	s_and_b64 vcc, exec, s[2:3]
	s_cbranch_vccnz .LBB0_1376
	v_cmp_eq_u32_e32 vcc, 0, v0
	s_or_b32 s4, s13, 63
	v_cmp_le_i32_e64 s[74:75], s4, v154
	v_cndmask_b32_e32 v186, 0, v211, vcc
	v_cmp_ge_u32_e64 s[2:3], s13, v186
	s_and_b64 s[2:3], s[2:3], s[74:75]
	v_and_b32_e32 v187, 63, v181
	v_cndmask_b32_e64 v0, 0, 1, s[2:3]
	v_cmp_ne_u32_e64 s[2:3], 0, v0
	v_and_b32_e32 v185, 15, v181
	v_and_b32_e32 v0, 48, v181
	v_or_b32_e32 v183, 48, v187
	s_mov_b64 s[74:75], -1
	s_cmp_lg_u64 s[2:3], exec
	v_add_u32_e32 v184, s96, v0
	v_mul_u32_u24_e32 v182, 0x90, v185
	v_mul_u32_u24_e32 v163, 0x90, v183
	s_cbranch_scc0 .LBB0_1369
	v_mad_u32_u24 v0, v185, s88, v184
	ds_read_b128 v[36:39], v0 offset:9216
	ds_read_b128 v[40:43], v0 offset:9280
	ds_read_b128 v[56:59], v0 offset:11520
	ds_read_b128 v[60:63], v0 offset:11584
	ds_read_b128 v[64:67], v0 offset:13824
	ds_read_b128 v[68:71], v0 offset:13888
	v_mad_u32_u24 v0, v183, s88, v184
	ds_read_b128 v[72:75], v0 offset:9216
	ds_read_b128 v[32:35], v0 offset:9280
	s_cmp_gt_i32 s4, s93
	s_mov_b64 s[2:3], -1
	s_cbranch_scc1 .LBB0_1362
	s_waitcnt lgkmcnt(7)
	v_mfma_f32_16x16x32_bf16 v[0:3], v[36:39], v[104:107], 0
	s_waitcnt lgkmcnt(5)
	v_mfma_f32_16x16x32_bf16 v[4:7], v[56:59], v[104:107], 0
	s_waitcnt lgkmcnt(3)
	v_mfma_f32_16x16x32_bf16 v[8:11], v[64:67], v[104:107], 0
	s_waitcnt lgkmcnt(1)
	v_mfma_f32_16x16x32_bf16 v[128:131], v[72:75], v[104:107], 0
	v_mfma_f32_16x16x32_bf16 v[0:3], v[40:43], v[108:111], v[0:3]
	v_mfma_f32_16x16x32_bf16 v[4:7], v[60:63], v[108:111], v[4:7]
	v_mfma_f32_16x16x32_bf16 v[8:11], v[68:71], v[108:111], v[8:11]
	s_waitcnt lgkmcnt(0)
	v_mfma_f32_16x16x32_bf16 v[128:131], v[32:35], v[108:111], v[128:131]
	s_nop 7
	s_nop 7
	s_nop 0
	v_max3_f32 v92, v158, v0, v1
	s_nop 0
	v_max3_f32 v92, v92, v2, v3
	s_nop 0
	v_max3_f32 v92, v92, v4, v5
	s_nop 0
	v_max3_f32 v92, v92, v6, v7
	s_nop 0
	v_max3_f32 v92, v92, v8, v9
	s_nop 0
	v_max3_f32 v92, v92, v10, v11
	s_nop 0
	v_max3_f32 v92, v92, v128, v129
	s_nop 0
	v_max3_f32 v92, v92, v130, v131
	s_nop 0
	v_cndmask_b32_e32 v92, v92, v158, vcc
	v_mov_b32_e32 v132, v92
	s_nop 1
	v_permlane16_swap_b32_e32 v132, v92
	s_waitcnt lgkmcnt(0)
	v_max3_f32 v92, v92, v132, v158
	v_mov_b32_e32 v132, v92
	s_nop 1
	v_permlane32_swap_b32_e32 v132, v92
	s_waitcnt lgkmcnt(0)
	v_max3_f32 v92, v92, v132, v158
	s_nop 0
	v_max3_f32 v153, v175, v92, v158
	s_nop 0
	v_cndmask_b32_e32 v92, v153, v212, vcc
	v_sub_f32_e32 v3, v3, v92
	v_sub_f32_e32 v2, v2, v92
	v_sub_f32_e32 v1, v1, v92
	v_sub_f32_e32 v0, v0, v92
	v_sub_f32_e32 v7, v7, v92
	v_sub_f32_e32 v6, v6, v92
	v_exp_f32_e32 v140, v0
	v_exp_f32_e32 v141, v1
	v_exp_f32_e32 v142, v2
	v_exp_f32_e32 v143, v3
	v_sub_f32_e32 v0, v5, v92
	v_sub_f32_e32 v1, v4, v92
	v_exp_f32_e32 v144, v1
	v_exp_f32_e32 v146, v6
	v_exp_f32_e32 v147, v7
	v_exp_f32_e32 v145, v0
	v_sub_f32_e32 v4, v11, v92
	v_sub_f32_e32 v5, v10, v92
	v_sub_f32_e32 v6, v9, v92
	v_sub_f32_e32 v7, v8, v92
	v_exp_f32_e32 v132, v7
	v_exp_f32_e32 v133, v6
	v_exp_f32_e32 v134, v5
	v_exp_f32_e32 v135, v4
	v_sub_f32_e32 v4, v131, v92
	v_sub_f32_e32 v5, v130, v92
	v_sub_f32_e32 v6, v129, v92
	v_sub_f32_e32 v7, v128, v92
	v_exp_f32_e32 v136, v7
	v_exp_f32_e32 v138, v5
	v_exp_f32_e32 v139, v4
	v_exp_f32_e32 v137, v6
	v_pk_add_f32 v[0:1], v[140:141], 0 op_sel_hi:[1,0]
	v_pk_add_f32 v[2:3], v[142:143], 0 op_sel_hi:[1,0]
	v_pk_add_f32 v[0:1], v[144:145], v[0:1]
	v_pk_add_f32 v[2:3], v[146:147], v[2:3]
	v_pk_add_f32 v[0:1], v[132:133], v[0:1]
	v_pk_add_f32 v[2:3], v[134:135], v[2:3]
	v_pk_add_f32 v[0:1], v[136:137], v[0:1]
	v_pk_add_f32 v[2:3], v[138:139], v[2:3]
	v_add_f32_e32 v0, v0, v1
	v_add_f32_e32 v1, v2, v3
	v_add_f32_e32 v0, v0, v1
	v_mov_b32_e32 v1, v0
	s_nop 1
	v_permlane16_swap_b32_e32 v1, v0
	v_sub_f32_e32 v2, v175, v153
	v_exp_f32_e32 v92, v2
	s_waitcnt lgkmcnt(0)
	v_add_f32_e32 v180, v0, v1
	ds_bpermute_b32 v188, v217, v180
	v_cmp_eq_f32_e32 vcc, 1.0, v92
	s_cmp_lg_u64 vcc, exec
	s_cbranch_scc0 .LBB0_1359
	v_pk_mul_f32 v[130:131], v[78:79], v[92:93] op_sel_hi:[1,0]
	v_pk_mul_f32 v[128:129], v[76:77], v[92:93] op_sel_hi:[1,0]
	v_pk_mul_f32 v[10:11], v[82:83], v[92:93] op_sel_hi:[1,0]
	v_pk_mul_f32 v[8:9], v[80:81], v[92:93] op_sel_hi:[1,0]
	v_pk_mul_f32 v[6:7], v[86:87], v[92:93] op_sel_hi:[1,0]
	v_pk_mul_f32 v[4:5], v[84:85], v[92:93] op_sel_hi:[1,0]
	v_pk_mul_f32 v[2:3], v[90:91], v[92:93] op_sel_hi:[1,0]
	v_pk_mul_f32 v[0:1], v[88:89], v[92:93] op_sel_hi:[1,0]
	s_mov_b64 s[2:3], 0

.LBB0_1362:
	s_and_b64 vcc, exec, s[2:3]
	s_cbranch_vccz .LBB0_1368
	s_waitcnt lgkmcnt(7)
	v_mfma_f32_16x16x32_bf16 v[0:3], v[36:39], v[104:107], 0
	v_lshrrev_b32_e32 v37, 4, v187
	v_lshl_or_b32 v36, v37, 2, s13
	v_cmp_ge_u32_e32 vcc, v36, v186
	s_waitcnt lgkmcnt(6)
	v_mfma_f32_16x16x32_bf16 v[0:3], v[40:43], v[108:111], v[0:3]
	v_cmp_le_i32_e64 s[2:3], v36, v154
	s_and_b64 vcc, vcc, s[2:3]
	v_cmp_lt_i32_e64 s[2:3], v36, v154
	s_waitcnt lgkmcnt(5)
	v_mfma_f32_16x16x32_bf16 v[4:7], v[56:59], v[104:107], 0
	s_waitcnt lgkmcnt(3)
	v_mfma_f32_16x16x32_bf16 v[8:11], v[64:67], v[104:107], 0
	s_waitcnt lgkmcnt(1)
	v_mfma_f32_16x16x32_bf16 v[38:41], v[72:75], v[104:107], 0
	v_mfma_f32_16x16x32_bf16 v[4:7], v[60:63], v[108:111], v[4:7]
	v_mfma_f32_16x16x32_bf16 v[8:11], v[68:71], v[108:111], v[8:11]
	s_waitcnt lgkmcnt(0)
	v_mfma_f32_16x16x32_bf16 v[32:35], v[32:35], v[108:111], v[38:41]
	s_nop 7
	s_nop 7
	s_nop 0
	v_cndmask_b32_e32 v0, v158, v0, vcc
	s_nop 1
	v_or_b32_e32 v38, 1, v36
	v_cmp_ge_u32_e32 vcc, v38, v186
	s_and_b64 vcc, s[2:3], vcc
	v_or_b32_e32 v39, 2, v36
	v_cndmask_b32_e32 v1, v158, v1, vcc
	v_cmp_ge_u32_e32 vcc, v39, v186
	v_cmp_le_i32_e64 s[2:3], v36, v152
	s_and_b64 vcc, s[2:3], vcc
	v_or_b32_e32 v39, 3, v36
	v_cndmask_b32_e32 v2, v158, v2, vcc
	v_cmp_ge_u32_e32 vcc, v39, v186
	v_cmp_le_i32_e64 s[2:3], v39, v154
	s_and_b64 vcc, vcc, s[2:3]
	v_or_b32_e32 v39, 16, v36
	v_cndmask_b32_e32 v3, v158, v3, vcc
	v_cmp_ge_u32_e32 vcc, v39, v186
	v_cmp_le_i32_e64 s[2:3], v39, v154
	s_and_b64 vcc, vcc, s[2:3]
	v_or_b32_e32 v39, 17, v36
	v_cndmask_b32_e32 v4, v158, v4, vcc
	v_cmp_ge_u32_e32 vcc, v39, v186
	v_cmp_le_i32_e64 s[2:3], v39, v154
	s_and_b64 vcc, vcc, s[2:3]
	v_or_b32_e32 v39, 18, v36
	v_cndmask_b32_e32 v5, v158, v5, vcc
	v_cmp_ge_u32_e32 vcc, v39, v186
	v_cmp_le_i32_e64 s[2:3], v39, v154
	s_and_b64 vcc, vcc, s[2:3]
	v_or_b32_e32 v39, 19, v36
	v_cndmask_b32_e32 v6, v158, v6, vcc
	v_cmp_ge_u32_e32 vcc, v39, v186
	v_cmp_le_i32_e64 s[2:3], v39, v154
	s_and_b64 vcc, vcc, s[2:3]
	v_or_b32_e32 v39, 32, v36
	v_cndmask_b32_e32 v7, v158, v7, vcc
	v_cmp_ge_u32_e32 vcc, v39, v186
	v_cmp_le_i32_e64 s[2:3], v39, v154
	s_and_b64 vcc, vcc, s[2:3]
	v_or_b32_e32 v39, 33, v36
	v_cndmask_b32_e32 v8, v158, v8, vcc
	v_cmp_ge_u32_e32 vcc, v39, v186
	v_cmp_le_i32_e64 s[2:3], v39, v154
	s_and_b64 vcc, vcc, s[2:3]
	v_or_b32_e32 v39, 34, v36
	v_cndmask_b32_e32 v9, v158, v9, vcc
	v_cmp_ge_u32_e32 vcc, v39, v186
	v_cmp_le_i32_e64 s[2:3], v39, v154
	s_and_b64 vcc, vcc, s[2:3]
	v_or_b32_e32 v39, 35, v36
	v_cndmask_b32_e32 v10, v158, v10, vcc
	v_cmp_ge_u32_e32 vcc, v39, v186
	v_cmp_le_i32_e64 s[2:3], v39, v154
	s_and_b64 vcc, vcc, s[2:3]
	v_or_b32_e32 v39, 48, v36
	v_cndmask_b32_e32 v11, v158, v11, vcc
	v_cmp_ge_u32_e32 vcc, v39, v186
	v_cmp_le_i32_e64 s[2:3], v39, v154
	s_and_b64 vcc, vcc, s[2:3]
	v_or_b32_e32 v39, 49, v36
	v_max3_f32 v38, v0, s87, v1
	v_cndmask_b32_e32 v32, v158, v32, vcc
	v_cmp_ge_u32_e32 vcc, v39, v186
	v_cmp_le_i32_e64 s[2:3], v39, v154
	v_max3_f32 v38, v38, v2, v3
	s_and_b64 vcc, vcc, s[2:3]
	v_or_b32_e32 v39, 50, v36
	v_max3_f32 v38, v38, v4, v5
	v_cndmask_b32_e32 v33, v158, v33, vcc
	v_cmp_ge_u32_e32 vcc, v39, v186
	v_cmp_le_i32_e64 s[2:3], v39, v154
	v_max3_f32 v38, v38, v6, v7
	s_and_b64 vcc, vcc, s[2:3]
	v_or_b32_e32 v36, 51, v36
	v_max3_f32 v38, v38, v8, v9
	v_cndmask_b32_e32 v34, v158, v34, vcc
	v_cmp_ge_u32_e32 vcc, v36, v186
	v_cmp_le_i32_e64 s[2:3], v36, v154
	v_max3_f32 v38, v38, v10, v11
	s_and_b64 vcc, vcc, s[2:3]
	v_max3_f32 v38, v38, v32, v33
	v_cndmask_b32_e32 v35, v158, v35, vcc
	v_max3_f32 v36, v38, v34, v35
	v_mov_b32_e32 v38, v36
	s_nop 1
	v_permlane16_swap_b32_e32 v38, v36
	s_waitcnt lgkmcnt(0)
	v_max3_f32 v36, v36, v38, v158
	v_mov_b32_e32 v38, v36
	s_nop 1
	v_permlane32_swap_b32_e32 v38, v36
	s_waitcnt lgkmcnt(0)
	v_max3_f32 v36, v36, v38, v158
	v_cmp_lt_f32_e32 vcc, s86, v0
	v_max3_f32 v153, v175, v36, v158
	s_mov_b64 s[2:3], -1
	v_sub_f32_e32 v36, v0, v153
	v_exp_f32_e32 v36, v36
	v_sub_f32_e32 v38, v1, v153
	v_exp_f32_e32 v38, v38
	v_cndmask_b32_e32 v56, 0, v36, vcc
	v_cmp_lt_f32_e32 vcc, s86, v1
	v_sub_f32_e32 v1, v2, v153
	v_exp_f32_e32 v1, v1
	v_cndmask_b32_e32 v57, 0, v38, vcc
	v_sub_f32_e32 v36, v3, v153
	v_cmp_lt_f32_e32 vcc, s86, v2
	v_exp_f32_e32 v36, v36
	v_sub_f32_e32 v2, v5, v153
	v_cndmask_b32_e32 v60, 0, v1, vcc
	v_sub_f32_e32 v1, v4, v153
	v_exp_f32_e32 v1, v1
	v_exp_f32_e32 v2, v2
	v_cmp_lt_f32_e32 vcc, s86, v3
	v_add_f32_e32 v0, 0, v56
	v_add_f32_e32 v0, v57, v0
	v_cndmask_b32_e32 v61, 0, v36, vcc
	v_cmp_lt_f32_e32 vcc, s86, v4
	v_add_f32_e32 v0, v60, v0
	v_add_f32_e32 v0, v61, v0
	v_cndmask_b32_e32 v62, 0, v1, vcc
	v_cmp_lt_f32_e32 vcc, s86, v5
	v_sub_f32_e32 v1, v6, v153
	v_exp_f32_e32 v1, v1
	v_cndmask_b32_e32 v63, 0, v2, vcc
	v_sub_f32_e32 v2, v7, v153
	v_exp_f32_e32 v2, v2
	v_cmp_lt_f32_e32 vcc, s86, v6
	v_add_f32_e32 v0, v62, v0
	v_add_f32_e32 v0, v63, v0
	v_cndmask_b32_e32 v64, 0, v1, vcc
	v_cmp_lt_f32_e32 vcc, s86, v7
	v_sub_f32_e32 v1, v8, v153
	v_exp_f32_e32 v1, v1
	v_cndmask_b32_e32 v65, 0, v2, vcc
	v_sub_f32_e32 v2, v9, v153
	v_exp_f32_e32 v2, v2
	v_cmp_lt_f32_e32 vcc, s86, v8
	v_add_f32_e32 v0, v64, v0
	v_add_f32_e32 v0, v65, v0
	v_cndmask_b32_e32 v38, 0, v1, vcc
	v_cmp_lt_f32_e32 vcc, s86, v9
	v_sub_f32_e32 v1, v10, v153
	v_exp_f32_e32 v1, v1
	v_cndmask_b32_e32 v39, 0, v2, vcc
	v_sub_f32_e32 v2, v11, v153
	v_exp_f32_e32 v2, v2
	v_cmp_lt_f32_e32 vcc, s86, v10
	v_add_f32_e32 v0, v38, v0
	v_add_f32_e32 v0, v39, v0
	v_cndmask_b32_e32 v40, 0, v1, vcc
	v_cmp_lt_f32_e32 vcc, s86, v11
	v_sub_f32_e32 v1, v32, v153
	v_exp_f32_e32 v1, v1
	v_cndmask_b32_e32 v41, 0, v2, vcc
	v_sub_f32_e32 v2, v33, v153
	v_exp_f32_e32 v2, v2
	v_cmp_lt_f32_e32 vcc, s86, v32
	v_add_f32_e32 v0, v40, v0
	v_add_f32_e32 v0, v41, v0
	v_cndmask_b32_e32 v42, 0, v1, vcc
	v_cmp_lt_f32_e32 vcc, s86, v33
	v_sub_f32_e32 v1, v34, v153
	v_exp_f32_e32 v1, v1
	v_cndmask_b32_e32 v43, 0, v2, vcc
	v_sub_f32_e32 v2, v35, v153
	v_exp_f32_e32 v2, v2
	v_add_f32_e32 v0, v42, v0
	v_cmp_lt_f32_e32 vcc, s86, v34
	v_add_f32_e32 v0, v43, v0
	s_nop 0
	v_cndmask_b32_e32 v58, 0, v1, vcc
	v_cmp_lt_f32_e32 vcc, s86, v35
	v_add_f32_e32 v0, v58, v0
	s_nop 0
	v_cndmask_b32_e32 v59, 0, v2, vcc
	v_add_f32_e32 v0, v59, v0
	v_mov_b32_e32 v1, v0
	s_nop 1
	v_permlane16_swap_b32_e32 v1, v0
	v_sub_f32_e32 v2, v175, v153
	v_exp_f32_e32 v36, v2
	s_waitcnt lgkmcnt(0)
	v_add_f32_e32 v66, v0, v1
	ds_bpermute_b32 v67, v217, v66
	v_cmp_eq_f32_e32 vcc, 1.0, v36
	s_cmp_lg_u64 vcc, exec
	s_cbranch_scc0 .LBB0_1365
	v_pk_mul_f32 v[34:35], v[78:79], v[36:37] op_sel_hi:[1,0]
	v_pk_mul_f32 v[32:33], v[76:77], v[36:37] op_sel_hi:[1,0]
	v_pk_mul_f32 v[10:11], v[82:83], v[36:37] op_sel_hi:[1,0]
	v_pk_mul_f32 v[8:9], v[80:81], v[36:37] op_sel_hi:[1,0]
	v_pk_mul_f32 v[6:7], v[86:87], v[36:37] op_sel_hi:[1,0]
	v_pk_mul_f32 v[4:5], v[84:85], v[36:37] op_sel_hi:[1,0]
	v_pk_mul_f32 v[2:3], v[90:91], v[36:37] op_sel_hi:[1,0]
	v_pk_mul_f32 v[0:1], v[88:89], v[36:37] op_sel_hi:[1,0]
	s_mov_b64 s[2:3], 0

.LBB0_1369:
	s_andn2_b64 vcc, exec, s[74:75]
	s_cbranch_vccnz .LBB0_1375
	s_waitcnt lgkmcnt(0)
	v_mad_u32_u24 v32, v185, s88, v184
	ds_read_b128 v[0:3], v32 offset:9216
	s_nop 0
	ds_read_b128 v[8:11], v32 offset:9280
	ds_read_b128 v[4:7], v32 offset:11520
	v_mad_u32_u24 v36, v183, s88, v184
	s_mov_b64 s[2:3], -1
	s_waitcnt lgkmcnt(2)
	v_mfma_f32_16x16x32_bf16 v[0:3], v[0:3], v[104:107], 0
	s_waitcnt lgkmcnt(1)
	v_mfma_f32_16x16x32_bf16 v[0:3], v[8:11], v[108:111], v[0:3]
	ds_read_b128 v[8:11], v32 offset:11584
	s_waitcnt lgkmcnt(1)
	v_mfma_f32_16x16x32_bf16 v[4:7], v[4:7], v[104:107], 0
	s_waitcnt lgkmcnt(0)
	v_mfma_f32_16x16x32_bf16 v[4:7], v[8:11], v[108:111], v[4:7]
	ds_read_b128 v[8:11], v32 offset:13824
	ds_read_b128 v[32:35], v32 offset:13888
	s_waitcnt lgkmcnt(1)
	v_mfma_f32_16x16x32_bf16 v[8:11], v[8:11], v[104:107], 0
	s_waitcnt lgkmcnt(0)
	v_mfma_f32_16x16x32_bf16 v[8:11], v[32:35], v[108:111], v[8:11]
	ds_read_b128 v[32:35], v36 offset:9216
	ds_read_b128 v[36:39], v36 offset:9280
	s_waitcnt lgkmcnt(1)
	v_mfma_f32_16x16x32_bf16 v[32:35], v[32:35], v[104:107], 0
	s_waitcnt lgkmcnt(0)
	v_mfma_f32_16x16x32_bf16 v[32:35], v[36:39], v[108:111], v[32:35]
	s_nop 7
	s_nop 7
	s_nop 0
	v_max3_f32 v36, v158, v0, v1
	s_nop 0
	v_max3_f32 v36, v36, v2, v3
	s_nop 0
	v_max3_f32 v36, v36, v4, v5
	s_nop 0
	v_max3_f32 v36, v36, v6, v7
	s_nop 0
	v_max3_f32 v36, v36, v8, v9
	s_nop 0
	v_max3_f32 v36, v36, v10, v11
	s_nop 0
	v_max3_f32 v36, v36, v32, v33
	s_nop 0
	v_max3_f32 v36, v36, v34, v35
	v_mov_b32_e32 v37, v36
	s_nop 1
	v_permlane16_swap_b32_e32 v37, v36
	s_waitcnt lgkmcnt(0)
	v_max3_f32 v36, v36, v37, v158
	v_mov_b32_e32 v37, v36
	s_nop 1
	v_permlane32_swap_b32_e32 v37, v36
	s_waitcnt lgkmcnt(0)
	v_max3_f32 v36, v36, v37, v158
	s_nop 0
	v_max3_f32 v153, v175, v36, v158
	s_nop 0
	v_sub_f32_e32 v3, v3, v153
	v_sub_f32_e32 v2, v2, v153
	v_sub_f32_e32 v1, v1, v153
	v_sub_f32_e32 v0, v0, v153
	v_sub_f32_e32 v7, v7, v153
	v_sub_f32_e32 v6, v6, v153
	v_exp_f32_e32 v56, v0
	v_exp_f32_e32 v57, v1
	v_exp_f32_e32 v58, v2
	v_exp_f32_e32 v59, v3
	v_sub_f32_e32 v0, v5, v153
	v_sub_f32_e32 v1, v4, v153
	v_exp_f32_e32 v60, v1
	v_exp_f32_e32 v62, v6
	v_exp_f32_e32 v63, v7
	v_exp_f32_e32 v61, v0
	v_sub_f32_e32 v4, v11, v153
	v_sub_f32_e32 v5, v10, v153
	v_sub_f32_e32 v6, v9, v153
	v_sub_f32_e32 v7, v8, v153
	v_exp_f32_e32 v36, v7
	v_exp_f32_e32 v37, v6
	v_exp_f32_e32 v38, v5
	v_exp_f32_e32 v39, v4
	v_sub_f32_e32 v4, v35, v153
	v_sub_f32_e32 v5, v34, v153
	v_sub_f32_e32 v6, v33, v153
	v_sub_f32_e32 v7, v32, v153
	v_exp_f32_e32 v40, v7
	v_exp_f32_e32 v42, v5
	v_exp_f32_e32 v43, v4
	v_exp_f32_e32 v41, v6
	v_pk_add_f32 v[0:1], v[56:57], 0 op_sel_hi:[1,0]
	v_pk_add_f32 v[2:3], v[58:59], 0 op_sel_hi:[1,0]
	v_pk_add_f32 v[0:1], v[60:61], v[0:1]
	v_pk_add_f32 v[2:3], v[62:63], v[2:3]
	v_pk_add_f32 v[0:1], v[36:37], v[0:1]
	v_pk_add_f32 v[2:3], v[38:39], v[2:3]
	v_pk_add_f32 v[0:1], v[40:41], v[0:1]
	v_pk_add_f32 v[2:3], v[42:43], v[2:3]
	v_add_f32_e32 v0, v0, v1
	v_add_f32_e32 v1, v2, v3
	v_add_f32_e32 v0, v0, v1
	v_mov_b32_e32 v1, v0
	s_nop 1
	v_permlane16_swap_b32_e32 v1, v0
	v_sub_f32_e32 v2, v175, v153
	v_exp_f32_e32 v64, v2
	s_waitcnt lgkmcnt(0)
	v_add_f32_e32 v65, v0, v1
	ds_bpermute_b32 v66, v217, v65
	v_cmp_eq_f32_e32 vcc, 1.0, v64
	s_cmp_lg_u64 vcc, exec
	s_cbranch_scc0 .LBB0_1372
	v_pk_mul_f32 v[34:35], v[78:79], v[64:65] op_sel_hi:[1,0]
	v_pk_mul_f32 v[32:33], v[76:77], v[64:65] op_sel_hi:[1,0]
	v_pk_mul_f32 v[10:11], v[82:83], v[64:65] op_sel_hi:[1,0]
	v_pk_mul_f32 v[8:9], v[80:81], v[64:65] op_sel_hi:[1,0]
	v_pk_mul_f32 v[6:7], v[86:87], v[64:65] op_sel_hi:[1,0]
	v_pk_mul_f32 v[4:5], v[84:85], v[64:65] op_sel_hi:[1,0]
	v_pk_mul_f32 v[2:3], v[90:91], v[64:65] op_sel_hi:[1,0]
	v_pk_mul_f32 v[0:1], v[88:89], v[64:65] op_sel_hi:[1,0]
	s_mov_b64 s[2:3], 0

.LBB0_1395:
	s_mul_i32 s2, s1, 0x4800
	s_lshl_b32 s14, s14, 6
	s_add_i32 s13, s2, 0
	s_or_b32 s15, s14, 63
	s_cmp_lt_i32 s15, s0
	s_cselect_b64 s[2:3], -1, 0
	s_cmp_gt_i32 s14, s76
	s_cselect_b64 s[92:93], -1, 0
	s_or_b64 s[2:3], s[92:93], s[2:3]
	v_mov_b32_e32 v136, v196
	s_and_b64 vcc, exec, s[2:3]
	s_cbranch_vccnz .LBB0_1405
	v_cmp_ge_i32_e32 vcc, s14, v130
	v_cmp_le_i32_e64 s[2:3], s15, v152
	s_and_b64 s[2:3], vcc, s[2:3]
	v_and_b32_e32 v80, 15, v136
	v_cndmask_b32_e64 v48, 0, 1, s[2:3]
	v_cmp_ne_u32_e32 vcc, 0, v48
	v_and_b32_e32 v48, 48, v136
	v_add_u32_e32 v72, s13, v48
	v_mad_u32_u24 v68, v80, s88, v72
	ds_read_b128 v[48:51], v68
	ds_read_b128 v[52:55], v68 offset:64
	ds_read_b128 v[56:59], v68 offset:2304
	ds_read_b128 v[60:63], v68 offset:2368
	ds_read_b128 v[64:67], v68 offset:4608
	ds_read_b128 v[68:71], v68 offset:4672
	v_and_b32_e32 v92, 63, v136
	v_or_b32_e32 v81, 48, v92
	v_mad_u32_u24 v76, v81, s88, v72
	ds_read_b128 v[72:75], v76
	ds_read_b128 v[76:79], v76 offset:64
	s_cmp_lg_u64 vcc, exec
	v_mul_u32_u24_e32 v137, 0x90, v80
	v_mul_u32_u24_e32 v134, 0x90, v81
	s_mov_b64 s[2:3], -1
	s_cbranch_scc0 .LBB0_1400
	s_waitcnt lgkmcnt(7)
	v_mfma_f32_16x16x32_bf16 v[80:83], v[48:51], v[96:99], 0
	v_lshrrev_b32_e32 v139, 4, v92
	v_lshl_or_b32 v92, v139, 2, s14
	v_cmp_ge_i32_e32 vcc, v92, v130
	s_waitcnt lgkmcnt(5)
	v_mfma_f32_16x16x32_bf16 v[84:87], v[56:59], v[96:99], 0
	v_cmp_le_i32_e64 s[2:3], v92, v152
	s_and_b64 vcc, vcc, s[2:3]
	v_or_b32_e32 v135, 1, v92
	s_waitcnt lgkmcnt(3)
	v_mfma_f32_16x16x32_bf16 v[88:91], v[64:67], v[96:99], 0
	v_cmp_lt_i32_e64 s[2:3], v92, v152
	v_or_b32_e32 v138, 2, v92
	s_waitcnt lgkmcnt(1)
	v_mfma_f32_16x16x32_bf16 v[112:115], v[72:75], v[96:99], 0
	v_mfma_f32_16x16x32_bf16 v[80:83], v[52:55], v[100:103], v[80:83]
	v_mfma_f32_16x16x32_bf16 v[84:87], v[60:63], v[100:103], v[84:87]
	v_mfma_f32_16x16x32_bf16 v[88:91], v[68:71], v[100:103], v[88:91]
	s_waitcnt lgkmcnt(0)
	v_mfma_f32_16x16x32_bf16 v[112:115], v[76:79], v[100:103], v[112:115]
	s_nop 7
	s_nop 7
	s_nop 3
	v_cndmask_b32_e32 v80, v158, v80, vcc
	v_cmp_ge_i32_e32 vcc, v135, v130
	s_and_b64 vcc, s[2:3], vcc
	v_cmp_le_i32_e64 s[2:3], v138, v152
	v_cndmask_b32_e32 v81, v158, v81, vcc
	v_cmp_ge_i32_e32 vcc, v138, v130
	s_and_b64 vcc, vcc, s[2:3]
	v_or_b32_e32 v138, 3, v92
	v_cndmask_b32_e32 v82, v158, v82, vcc
	v_cmp_ge_i32_e32 vcc, v138, v130
	v_cmp_le_i32_e64 s[2:3], v138, v152
	s_and_b64 vcc, vcc, s[2:3]
	v_or_b32_e32 v138, 16, v92
	v_cndmask_b32_e32 v83, v158, v83, vcc
	v_cmp_ge_i32_e32 vcc, v138, v130
	v_cmp_le_i32_e64 s[2:3], v138, v152
	s_and_b64 vcc, vcc, s[2:3]
	v_or_b32_e32 v138, 17, v92
	v_cndmask_b32_e32 v84, v158, v84, vcc
	v_cmp_ge_i32_e32 vcc, v138, v130
	v_cmp_le_i32_e64 s[2:3], v138, v152
	s_and_b64 vcc, vcc, s[2:3]
	v_or_b32_e32 v138, 18, v92
	v_cndmask_b32_e32 v85, v158, v85, vcc
	v_cmp_ge_i32_e32 vcc, v138, v130
	v_cmp_le_i32_e64 s[2:3], v138, v152
	s_and_b64 vcc, vcc, s[2:3]
	v_or_b32_e32 v138, 19, v92
	v_cndmask_b32_e32 v86, v158, v86, vcc
	v_cmp_ge_i32_e32 vcc, v138, v130
	v_cmp_le_i32_e64 s[2:3], v138, v152
	s_and_b64 vcc, vcc, s[2:3]
	v_or_b32_e32 v138, 32, v92
	v_cndmask_b32_e32 v87, v158, v87, vcc
	v_cmp_ge_i32_e32 vcc, v138, v130
	v_cmp_le_i32_e64 s[2:3], v138, v152
	s_and_b64 vcc, vcc, s[2:3]
	v_or_b32_e32 v138, 33, v92
	v_cndmask_b32_e32 v88, v158, v88, vcc
	v_cmp_ge_i32_e32 vcc, v138, v130
	v_cmp_le_i32_e64 s[2:3], v138, v152
	s_and_b64 vcc, vcc, s[2:3]
	v_or_b32_e32 v138, 34, v92
	v_cndmask_b32_e32 v89, v158, v89, vcc
	v_cmp_ge_i32_e32 vcc, v138, v130
	v_cmp_le_i32_e64 s[2:3], v138, v152
	s_and_b64 vcc, vcc, s[2:3]
	v_or_b32_e32 v138, 35, v92
	v_cndmask_b32_e32 v90, v158, v90, vcc
	v_cmp_ge_i32_e32 vcc, v138, v130
	v_cmp_le_i32_e64 s[2:3], v138, v152
	s_and_b64 vcc, vcc, s[2:3]
	v_or_b32_e32 v138, 48, v92
	v_cndmask_b32_e32 v91, v158, v91, vcc
	v_cmp_ge_i32_e32 vcc, v138, v130
	v_cmp_le_i32_e64 s[2:3], v138, v152
	s_and_b64 vcc, vcc, s[2:3]
	v_or_b32_e32 v138, 49, v92
	v_max3_f32 v135, v80, s87, v81
	v_cndmask_b32_e32 v112, v158, v112, vcc
	v_cmp_ge_i32_e32 vcc, v138, v130
	v_cmp_le_i32_e64 s[2:3], v138, v152
	v_max3_f32 v135, v135, v82, v83
	s_and_b64 vcc, vcc, s[2:3]
	v_or_b32_e32 v138, 50, v92
	v_max3_f32 v135, v135, v84, v85
	v_cndmask_b32_e32 v113, v158, v113, vcc
	v_cmp_ge_i32_e32 vcc, v138, v130
	v_cmp_le_i32_e64 s[2:3], v138, v152
	v_max3_f32 v135, v135, v86, v87
	s_and_b64 vcc, vcc, s[2:3]
	v_or_b32_e32 v92, 51, v92
	v_max3_f32 v135, v135, v88, v89
	v_cndmask_b32_e32 v114, v158, v114, vcc
	v_cmp_ge_i32_e32 vcc, v92, v130
	v_cmp_le_i32_e64 s[2:3], v92, v152
	v_max3_f32 v135, v135, v90, v91
	s_and_b64 vcc, vcc, s[2:3]
	v_max3_f32 v135, v135, v112, v113
	v_cndmask_b32_e32 v92, v158, v115, vcc
	v_max3_f32 v115, v135, v114, v92
	v_mov_b32_e32 v135, v115
	s_nop 1
	v_permlane16_swap_b32_e32 v135, v115
	s_waitcnt lgkmcnt(0)
	v_max3_f32 v115, v115, v135, v158
	v_mov_b32_e32 v135, v115
	s_nop 1
	v_permlane32_swap_b32_e32 v135, v115
	s_waitcnt lgkmcnt(0)
	v_max3_f32 v115, v115, v135, v158
	v_cmp_lt_f32_e32 vcc, s86, v80
	v_max3_f32 v135, v133, v115, v158
	s_nop 0
	v_sub_f32_e32 v115, v80, v135
	v_exp_f32_e32 v115, v115
	v_sub_f32_e32 v138, v81, v135
	v_exp_f32_e32 v138, v138
	v_cndmask_b32_e32 v146, 0, v115, vcc
	v_cmp_lt_f32_e32 vcc, s86, v81
	v_sub_f32_e32 v81, v82, v135
	v_exp_f32_e32 v81, v81
	v_cndmask_b32_e32 v153, 0, v138, vcc
	v_sub_f32_e32 v115, v83, v135
	v_cmp_lt_f32_e32 vcc, s86, v82
	v_exp_f32_e32 v115, v115
	v_sub_f32_e32 v82, v85, v135
	v_cndmask_b32_e32 v162, 0, v81, vcc
	v_sub_f32_e32 v81, v84, v135
	v_exp_f32_e32 v81, v81
	v_exp_f32_e32 v82, v82
	v_cmp_lt_f32_e32 vcc, s86, v83
	v_add_f32_e32 v80, 0, v146
	v_add_f32_e32 v80, v153, v80
	v_cndmask_b32_e32 v163, 0, v115, vcc
	v_cmp_lt_f32_e32 vcc, s86, v84
	v_add_f32_e32 v80, v162, v80
	v_add_f32_e32 v80, v163, v80
	v_cndmask_b32_e32 v164, 0, v81, vcc
	v_cmp_lt_f32_e32 vcc, s86, v85
	v_sub_f32_e32 v81, v86, v135
	v_exp_f32_e32 v81, v81
	v_cndmask_b32_e32 v165, 0, v82, vcc
	v_sub_f32_e32 v82, v87, v135
	v_exp_f32_e32 v82, v82
	v_cmp_lt_f32_e32 vcc, s86, v86
	v_add_f32_e32 v80, v164, v80
	v_add_f32_e32 v80, v165, v80
	v_cndmask_b32_e32 v166, 0, v81, vcc
	v_cmp_lt_f32_e32 vcc, s86, v87
	v_sub_f32_e32 v81, v88, v135
	v_exp_f32_e32 v81, v81
	v_cndmask_b32_e32 v167, 0, v82, vcc
	v_sub_f32_e32 v82, v89, v135
	v_exp_f32_e32 v82, v82
	v_cmp_lt_f32_e32 vcc, s86, v88
	v_add_f32_e32 v80, v166, v80
	v_add_f32_e32 v80, v167, v80
	v_cndmask_b32_e32 v140, 0, v81, vcc
	v_cmp_lt_f32_e32 vcc, s86, v89
	v_sub_f32_e32 v81, v90, v135
	v_exp_f32_e32 v81, v81
	v_cndmask_b32_e32 v141, 0, v82, vcc
	v_sub_f32_e32 v82, v91, v135
	v_exp_f32_e32 v82, v82
	v_cmp_lt_f32_e32 vcc, s86, v90
	v_add_f32_e32 v80, v140, v80
	v_add_f32_e32 v80, v141, v80
	v_cndmask_b32_e32 v142, 0, v81, vcc
	v_cmp_lt_f32_e32 vcc, s86, v91
	v_sub_f32_e32 v81, v112, v135
	v_exp_f32_e32 v81, v81
	v_cndmask_b32_e32 v143, 0, v82, vcc
	v_sub_f32_e32 v82, v113, v135
	v_exp_f32_e32 v82, v82
	v_cmp_lt_f32_e32 vcc, s86, v112
	v_add_f32_e32 v80, v142, v80
	v_add_f32_e32 v80, v143, v80
	v_cndmask_b32_e32 v144, 0, v81, vcc
	v_cmp_lt_f32_e32 vcc, s86, v113
	v_sub_f32_e32 v81, v114, v135
	v_exp_f32_e32 v81, v81
	v_cndmask_b32_e32 v145, 0, v82, vcc
	v_sub_f32_e32 v82, v92, v135
	v_exp_f32_e32 v82, v82
	v_add_f32_e32 v80, v144, v80
	v_cmp_lt_f32_e32 vcc, s86, v114
	v_add_f32_e32 v80, v145, v80
	v_mov_b64_e32 v[86:87], v[14:15]
	v_cndmask_b32_e32 v147, 0, v81, vcc
	v_cmp_lt_f32_e32 vcc, s86, v92
	v_add_f32_e32 v80, v147, v80
	v_mov_b64_e32 v[90:91], v[22:23]
	v_cndmask_b32_e32 v155, 0, v82, vcc
	v_add_f32_e32 v80, v155, v80
	v_mov_b32_e32 v81, v80
	s_nop 1
	v_permlane16_swap_b32_e32 v81, v80
	v_sub_f32_e32 v82, v133, v135
	v_exp_f32_e32 v92, v82
	v_mov_b64_e32 v[114:115], v[46:47]
	v_mov_b64_e32 v[84:85], v[12:13]
	s_waitcnt lgkmcnt(0)
	v_add_f32_e32 v138, v80, v81
	ds_bpermute_b32 v168, v217, v138
	v_cmp_eq_f32_e32 vcc, 1.0, v92
	v_mov_b64_e32 v[82:83], v[6:7]
	s_cmp_eq_u64 vcc, exec
	v_mov_b64_e32 v[80:81], v[4:5]
	v_mov_b64_e32 v[88:89], v[20:21]
	v_mov_b64_e32 v[112:113], v[44:45]
	s_cbranch_scc1 .LBB0_1399
	v_pk_mul_f32 v[114:115], v[46:47], v[92:93] op_sel_hi:[1,0]
	v_pk_mul_f32 v[112:113], v[44:45], v[92:93] op_sel_hi:[1,0]
	v_pk_mul_f32 v[90:91], v[22:23], v[92:93] op_sel_hi:[1,0]
	v_pk_mul_f32 v[88:89], v[20:21], v[92:93] op_sel_hi:[1,0]
	v_pk_mul_f32 v[86:87], v[14:15], v[92:93] op_sel_hi:[1,0]
	v_pk_mul_f32 v[84:85], v[12:13], v[92:93] op_sel_hi:[1,0]
	v_pk_mul_f32 v[82:83], v[6:7], v[92:93] op_sel_hi:[1,0]
	v_pk_mul_f32 v[80:81], v[4:5], v[92:93] op_sel_hi:[1,0]

.LBB0_1400:
	s_and_b64 vcc, exec, s[2:3]
	s_cbranch_vccz .LBB0_1404
	s_waitcnt lgkmcnt(7)
	v_mfma_f32_16x16x32_bf16 v[48:51], v[48:51], v[96:99], 0
	s_waitcnt lgkmcnt(6)
	v_mfma_f32_16x16x32_bf16 v[48:51], v[52:55], v[100:103], v[48:51]
	s_waitcnt lgkmcnt(5)
	v_mfma_f32_16x16x32_bf16 v[52:55], v[56:59], v[96:99], 0
	s_waitcnt lgkmcnt(3)
	v_mfma_f32_16x16x32_bf16 v[56:59], v[64:67], v[96:99], 0
	s_waitcnt lgkmcnt(2)
	v_mfma_f32_16x16x32_bf16 v[64:67], v[68:71], v[100:103], v[56:59]
	s_waitcnt lgkmcnt(1)
	v_mfma_f32_16x16x32_bf16 v[56:59], v[72:75], v[96:99], 0
	v_mfma_f32_16x16x32_bf16 v[52:55], v[60:63], v[100:103], v[52:55]
	s_waitcnt lgkmcnt(0)
	v_mfma_f32_16x16x32_bf16 v[68:71], v[76:79], v[100:103], v[56:59]
	s_nop 7
	s_nop 7
	s_nop 0
	v_max3_f32 v56, v158, v48, v49
	s_nop 0
	v_max3_f32 v56, v56, v50, v51
	s_nop 0
	v_max3_f32 v56, v56, v52, v53
	s_nop 0
	v_max3_f32 v56, v56, v54, v55
	s_nop 0
	v_max3_f32 v56, v56, v64, v65
	s_nop 0
	v_max3_f32 v56, v56, v66, v67
	s_nop 0
	v_max3_f32 v56, v56, v68, v69
	s_nop 0
	v_max3_f32 v56, v56, v70, v71
	v_mov_b32_e32 v57, v56
	s_nop 1
	v_permlane16_swap_b32_e32 v57, v56
	s_waitcnt lgkmcnt(0)
	v_max3_f32 v56, v56, v57, v158
	v_mov_b32_e32 v57, v56
	s_nop 1
	v_permlane32_swap_b32_e32 v57, v56
	s_waitcnt lgkmcnt(0)
	v_max3_f32 v56, v56, v57, v158
	s_nop 0
	v_max3_f32 v135, v133, v56, v158
	s_nop 0
	v_sub_f32_e32 v51, v51, v135
	v_sub_f32_e32 v50, v50, v135
	v_sub_f32_e32 v49, v49, v135
	v_sub_f32_e32 v48, v48, v135
	v_sub_f32_e32 v55, v55, v135
	v_sub_f32_e32 v54, v54, v135
	v_exp_f32_e32 v56, v48
	v_exp_f32_e32 v57, v49
	v_exp_f32_e32 v58, v50
	v_exp_f32_e32 v59, v51
	v_sub_f32_e32 v48, v53, v135
	v_sub_f32_e32 v49, v52, v135
	v_exp_f32_e32 v60, v49
	v_exp_f32_e32 v62, v54
	v_exp_f32_e32 v63, v55
	v_exp_f32_e32 v61, v48
	v_pk_add_f32 v[48:49], v[56:57], 0 op_sel_hi:[1,0]
	v_pk_add_f32 v[50:51], v[58:59], 0 op_sel_hi:[1,0]
	v_sub_f32_e32 v53, v71, v135
	v_pk_add_f32 v[72:73], v[62:63], v[50:51]
	v_pk_add_f32 v[74:75], v[60:61], v[48:49]
	v_sub_f32_e32 v51, v67, v135
	v_sub_f32_e32 v50, v66, v135
	v_sub_f32_e32 v49, v65, v135
	v_sub_f32_e32 v48, v64, v135
	v_exp_f32_e32 v48, v48
	v_exp_f32_e32 v49, v49
	v_exp_f32_e32 v50, v50
	v_exp_f32_e32 v51, v51
	v_sub_f32_e32 v54, v70, v135
	v_sub_f32_e32 v64, v69, v135
	v_sub_f32_e32 v52, v68, v135
	v_exp_f32_e32 v52, v52
	v_exp_f32_e32 v54, v54
	v_exp_f32_e32 v55, v53
	v_exp_f32_e32 v53, v64
	v_pk_add_f32 v[64:65], v[48:49], v[74:75]
	v_pk_add_f32 v[66:67], v[50:51], v[72:73]
	v_pk_add_f32 v[64:65], v[52:53], v[64:65]
	v_pk_add_f32 v[66:67], v[54:55], v[66:67]
	v_add_f32_e32 v64, v64, v65
	v_add_f32_e32 v65, v66, v67
	v_add_f32_e32 v65, v64, v65
	v_mov_b32_e32 v66, v65
	s_nop 1
	v_permlane16_swap_b32_e32 v66, v65
	v_sub_f32_e32 v64, v133, v135
	v_exp_f32_e32 v64, v64
	s_waitcnt lgkmcnt(0)
	v_add_f32_e32 v65, v65, v66
	ds_bpermute_b32 v66, v217, v65
	v_cmp_eq_f32_e32 vcc, 1.0, v64
	s_cmp_eq_u64 vcc, exec
	s_cbranch_scc1 .LBB0_1403
	v_pk_mul_f32 v[46:47], v[46:47], v[64:65] op_sel_hi:[1,0]
	v_pk_mul_f32 v[44:45], v[44:45], v[64:65] op_sel_hi:[1,0]
	v_pk_mul_f32 v[22:23], v[22:23], v[64:65] op_sel_hi:[1,0]
	v_pk_mul_f32 v[20:21], v[20:21], v[64:65] op_sel_hi:[1,0]
	v_pk_mul_f32 v[14:15], v[14:15], v[64:65] op_sel_hi:[1,0]
	v_pk_mul_f32 v[12:13], v[12:13], v[64:65] op_sel_hi:[1,0]
	v_pk_mul_f32 v[6:7], v[6:7], v[64:65] op_sel_hi:[1,0]
	v_pk_mul_f32 v[4:5], v[4:5], v[64:65] op_sel_hi:[1,0]

.LBB0_1405:
	s_cmp_lt_i32 s15, s78
	s_cselect_b64 s[2:3], -1, 0
	s_cmp_gt_i32 s14, s77
	s_cselect_b64 s[92:93], -1, 0
	s_or_b64 s[2:3], s[92:93], s[2:3]
	v_mov_b32_e32 v136, v196
	s_and_b64 vcc, exec, s[2:3]
	s_cbranch_vccnz .LBB0_1415
	v_cmp_ge_i32_e32 vcc, s14, v131
	v_cmp_le_i32_e64 s[2:3], s15, v154
	s_and_b64 s[2:3], vcc, s[2:3]
	v_and_b32_e32 v80, 15, v136
	s_waitcnt lgkmcnt(7)
	v_cndmask_b32_e64 v48, 0, 1, s[2:3]
	v_cmp_ne_u32_e32 vcc, 0, v48
	v_and_b32_e32 v48, 48, v136
	s_waitcnt lgkmcnt(1)
	v_add_u32_e32 v72, s13, v48
	v_mad_u32_u24 v68, v80, s88, v72
	ds_read_b128 v[48:51], v68
	ds_read_b128 v[52:55], v68 offset:64
	ds_read_b128 v[56:59], v68 offset:2304
	ds_read_b128 v[60:63], v68 offset:2368
	ds_read_b128 v[64:67], v68 offset:4608
	ds_read_b128 v[68:71], v68 offset:4672
	v_and_b32_e32 v92, 63, v136
	v_or_b32_e32 v81, 48, v92
	s_waitcnt lgkmcnt(6)
	v_mad_u32_u24 v76, v81, s88, v72
	ds_read_b128 v[72:75], v76
	ds_read_b128 v[76:79], v76 offset:64
	s_cmp_lg_u64 vcc, exec
	v_mul_u32_u24_e32 v137, 0x90, v80
	v_mul_u32_u24_e32 v134, 0x90, v81
	s_mov_b64 s[2:3], -1
	s_cbranch_scc0 .LBB0_1410
	s_waitcnt lgkmcnt(7)
	v_mfma_f32_16x16x32_bf16 v[80:83], v[48:51], v[104:107], 0
	v_lshrrev_b32_e32 v139, 4, v92
	v_lshl_or_b32 v92, v139, 2, s14
	v_cmp_ge_i32_e32 vcc, v92, v131
	s_waitcnt lgkmcnt(5)
	v_mfma_f32_16x16x32_bf16 v[84:87], v[56:59], v[104:107], 0
	v_cmp_le_i32_e64 s[2:3], v92, v154
	s_and_b64 vcc, vcc, s[2:3]
	v_or_b32_e32 v135, 1, v92
	s_waitcnt lgkmcnt(3)
	v_mfma_f32_16x16x32_bf16 v[88:91], v[64:67], v[104:107], 0
	v_cmp_lt_i32_e64 s[2:3], v92, v154
	v_or_b32_e32 v138, 2, v92
	s_waitcnt lgkmcnt(1)
	v_mfma_f32_16x16x32_bf16 v[112:115], v[72:75], v[104:107], 0
	v_mfma_f32_16x16x32_bf16 v[80:83], v[52:55], v[108:111], v[80:83]
	v_mfma_f32_16x16x32_bf16 v[84:87], v[60:63], v[108:111], v[84:87]
	v_mfma_f32_16x16x32_bf16 v[88:91], v[68:71], v[108:111], v[88:91]
	s_waitcnt lgkmcnt(0)
	v_mfma_f32_16x16x32_bf16 v[112:115], v[76:79], v[108:111], v[112:115]
	s_nop 7
	s_nop 7
	s_nop 3
	v_cndmask_b32_e32 v80, v158, v80, vcc
	v_cmp_ge_i32_e32 vcc, v135, v131
	s_and_b64 vcc, s[2:3], vcc
	v_cmp_le_i32_e64 s[2:3], v92, v152
	v_cndmask_b32_e32 v81, v158, v81, vcc
	v_cmp_ge_i32_e32 vcc, v138, v131
	s_and_b64 vcc, s[2:3], vcc
	v_or_b32_e32 v138, 3, v92
	v_cndmask_b32_e32 v82, v158, v82, vcc
	v_cmp_ge_i32_e32 vcc, v138, v131
	v_cmp_le_i32_e64 s[2:3], v138, v154
	s_and_b64 vcc, vcc, s[2:3]
	v_or_b32_e32 v138, 16, v92
	v_cndmask_b32_e32 v83, v158, v83, vcc
	v_cmp_ge_i32_e32 vcc, v138, v131
	v_cmp_le_i32_e64 s[2:3], v138, v154
	s_and_b64 vcc, vcc, s[2:3]
	v_or_b32_e32 v138, 17, v92
	v_cndmask_b32_e32 v84, v158, v84, vcc
	v_cmp_ge_i32_e32 vcc, v138, v131
	v_cmp_le_i32_e64 s[2:3], v138, v154
	s_and_b64 vcc, vcc, s[2:3]
	v_or_b32_e32 v138, 18, v92
	v_cndmask_b32_e32 v85, v158, v85, vcc
	v_cmp_ge_i32_e32 vcc, v138, v131
	v_cmp_le_i32_e64 s[2:3], v138, v154
	s_and_b64 vcc, vcc, s[2:3]
	v_or_b32_e32 v138, 19, v92
	v_cndmask_b32_e32 v86, v158, v86, vcc
	v_cmp_ge_i32_e32 vcc, v138, v131
	v_cmp_le_i32_e64 s[2:3], v138, v154
	s_and_b64 vcc, vcc, s[2:3]
	v_or_b32_e32 v138, 32, v92
	v_cndmask_b32_e32 v87, v158, v87, vcc
	v_cmp_ge_i32_e32 vcc, v138, v131
	v_cmp_le_i32_e64 s[2:3], v138, v154
	s_and_b64 vcc, vcc, s[2:3]
	v_or_b32_e32 v138, 33, v92
	v_cndmask_b32_e32 v88, v158, v88, vcc
	v_cmp_ge_i32_e32 vcc, v138, v131
	v_cmp_le_i32_e64 s[2:3], v138, v154
	s_and_b64 vcc, vcc, s[2:3]
	v_or_b32_e32 v138, 34, v92
	v_cndmask_b32_e32 v89, v158, v89, vcc
	v_cmp_ge_i32_e32 vcc, v138, v131
	v_cmp_le_i32_e64 s[2:3], v138, v154
	s_and_b64 vcc, vcc, s[2:3]
	v_or_b32_e32 v138, 35, v92
	v_cndmask_b32_e32 v90, v158, v90, vcc
	v_cmp_ge_i32_e32 vcc, v138, v131
	v_cmp_le_i32_e64 s[2:3], v138, v154
	s_and_b64 vcc, vcc, s[2:3]
	v_or_b32_e32 v138, 48, v92
	v_cndmask_b32_e32 v91, v158, v91, vcc
	v_cmp_ge_i32_e32 vcc, v138, v131
	v_cmp_le_i32_e64 s[2:3], v138, v154
	s_and_b64 vcc, vcc, s[2:3]
	v_or_b32_e32 v138, 49, v92
	v_max3_f32 v135, v80, s87, v81
	v_cndmask_b32_e32 v112, v158, v112, vcc
	v_cmp_ge_i32_e32 vcc, v138, v131
	v_cmp_le_i32_e64 s[2:3], v138, v154
	v_max3_f32 v135, v135, v82, v83
	s_and_b64 vcc, vcc, s[2:3]
	v_or_b32_e32 v138, 50, v92
	v_max3_f32 v135, v135, v84, v85
	v_cndmask_b32_e32 v113, v158, v113, vcc
	v_cmp_ge_i32_e32 vcc, v138, v131
	v_cmp_le_i32_e64 s[2:3], v138, v154
	v_max3_f32 v135, v135, v86, v87
	s_and_b64 vcc, vcc, s[2:3]
	v_or_b32_e32 v92, 51, v92
	v_max3_f32 v135, v135, v88, v89
	v_cndmask_b32_e32 v114, v158, v114, vcc
	v_cmp_ge_i32_e32 vcc, v92, v131
	v_cmp_le_i32_e64 s[2:3], v92, v154
	v_max3_f32 v135, v135, v90, v91
	s_and_b64 vcc, vcc, s[2:3]
	v_max3_f32 v135, v135, v112, v113
	v_cndmask_b32_e32 v92, v158, v115, vcc
	v_max3_f32 v115, v135, v114, v92
	v_mov_b32_e32 v135, v115
	s_nop 1
	v_permlane16_swap_b32_e32 v135, v115
	s_waitcnt lgkmcnt(0)
	v_max3_f32 v115, v115, v135, v158
	v_mov_b32_e32 v135, v115
	s_nop 1
	v_permlane32_swap_b32_e32 v135, v115
	s_waitcnt lgkmcnt(0)
	v_max3_f32 v115, v115, v135, v158
	v_cmp_lt_f32_e32 vcc, s86, v80
	v_max3_f32 v135, v95, v115, v158
	s_nop 0
	v_sub_f32_e32 v115, v80, v135
	v_exp_f32_e32 v115, v115
	v_sub_f32_e32 v138, v81, v135
	v_exp_f32_e32 v138, v138
	v_cndmask_b32_e32 v146, 0, v115, vcc
	v_cmp_lt_f32_e32 vcc, s86, v81
	v_sub_f32_e32 v81, v82, v135
	v_exp_f32_e32 v81, v81
	v_cndmask_b32_e32 v153, 0, v138, vcc
	v_sub_f32_e32 v115, v83, v135
	v_cmp_lt_f32_e32 vcc, s86, v82
	v_exp_f32_e32 v115, v115
	v_sub_f32_e32 v82, v85, v135
	v_cndmask_b32_e32 v162, 0, v81, vcc
	v_sub_f32_e32 v81, v84, v135
	v_exp_f32_e32 v81, v81
	v_exp_f32_e32 v82, v82
	v_cmp_lt_f32_e32 vcc, s86, v83
	v_add_f32_e32 v80, 0, v146
	v_add_f32_e32 v80, v153, v80
	v_cndmask_b32_e32 v163, 0, v115, vcc
	v_cmp_lt_f32_e32 vcc, s86, v84
	v_add_f32_e32 v80, v162, v80
	v_add_f32_e32 v80, v163, v80
	v_cndmask_b32_e32 v164, 0, v81, vcc
	v_cmp_lt_f32_e32 vcc, s86, v85
	v_sub_f32_e32 v81, v86, v135
	v_exp_f32_e32 v81, v81
	v_cndmask_b32_e32 v165, 0, v82, vcc
	v_sub_f32_e32 v82, v87, v135
	v_exp_f32_e32 v82, v82
	v_cmp_lt_f32_e32 vcc, s86, v86
	v_add_f32_e32 v80, v164, v80
	v_add_f32_e32 v80, v165, v80
	v_cndmask_b32_e32 v166, 0, v81, vcc
	v_cmp_lt_f32_e32 vcc, s86, v87
	v_sub_f32_e32 v81, v88, v135
	v_exp_f32_e32 v81, v81
	v_cndmask_b32_e32 v167, 0, v82, vcc
	v_sub_f32_e32 v82, v89, v135
	v_exp_f32_e32 v82, v82
	v_cmp_lt_f32_e32 vcc, s86, v88
	v_add_f32_e32 v80, v166, v80
	v_add_f32_e32 v80, v167, v80
	v_cndmask_b32_e32 v140, 0, v81, vcc
	v_cmp_lt_f32_e32 vcc, s86, v89
	v_sub_f32_e32 v81, v90, v135
	v_exp_f32_e32 v81, v81
	v_cndmask_b32_e32 v141, 0, v82, vcc
	v_sub_f32_e32 v82, v91, v135
	v_exp_f32_e32 v82, v82
	v_cmp_lt_f32_e32 vcc, s86, v90
	v_add_f32_e32 v80, v140, v80
	v_add_f32_e32 v80, v141, v80
	v_cndmask_b32_e32 v142, 0, v81, vcc
	v_cmp_lt_f32_e32 vcc, s86, v91
	v_sub_f32_e32 v81, v112, v135
	v_exp_f32_e32 v81, v81
	v_cndmask_b32_e32 v143, 0, v82, vcc
	v_sub_f32_e32 v82, v113, v135
	v_exp_f32_e32 v82, v82
	v_cmp_lt_f32_e32 vcc, s86, v112
	v_add_f32_e32 v80, v142, v80
	v_add_f32_e32 v80, v143, v80
	v_cndmask_b32_e32 v144, 0, v81, vcc
	v_cmp_lt_f32_e32 vcc, s86, v113
	v_sub_f32_e32 v81, v114, v135
	v_exp_f32_e32 v81, v81
	v_cndmask_b32_e32 v145, 0, v82, vcc
	v_sub_f32_e32 v82, v92, v135
	v_exp_f32_e32 v82, v82
	v_add_f32_e32 v80, v144, v80
	v_cmp_lt_f32_e32 vcc, s86, v114
	v_add_f32_e32 v80, v145, v80
	v_mov_b64_e32 v[86:87], v[10:11]
	v_cndmask_b32_e32 v147, 0, v81, vcc
	v_cmp_lt_f32_e32 vcc, s86, v92
	v_add_f32_e32 v80, v147, v80
	v_mov_b64_e32 v[90:91], v[18:19]
	v_cndmask_b32_e32 v155, 0, v82, vcc
	v_add_f32_e32 v80, v155, v80
	v_mov_b32_e32 v81, v80
	s_nop 1
	v_permlane16_swap_b32_e32 v81, v80
	v_sub_f32_e32 v82, v95, v135
	v_exp_f32_e32 v92, v82
	v_mov_b64_e32 v[114:115], v[42:43]
	v_mov_b64_e32 v[84:85], v[8:9]
	s_waitcnt lgkmcnt(0)
	v_add_f32_e32 v138, v80, v81
	ds_bpermute_b32 v168, v217, v138
	v_cmp_eq_f32_e32 vcc, 1.0, v92
	v_mov_b64_e32 v[82:83], v[2:3]
	s_cmp_eq_u64 vcc, exec
	v_mov_b64_e32 v[80:81], v[0:1]
	v_mov_b64_e32 v[88:89], v[16:17]
	v_mov_b64_e32 v[112:113], v[40:41]
	s_cbranch_scc1 .LBB0_1409
	v_pk_mul_f32 v[114:115], v[42:43], v[92:93] op_sel_hi:[1,0]
	v_pk_mul_f32 v[112:113], v[40:41], v[92:93] op_sel_hi:[1,0]
	v_pk_mul_f32 v[90:91], v[18:19], v[92:93] op_sel_hi:[1,0]
	v_pk_mul_f32 v[88:89], v[16:17], v[92:93] op_sel_hi:[1,0]
	v_pk_mul_f32 v[86:87], v[10:11], v[92:93] op_sel_hi:[1,0]
	v_pk_mul_f32 v[84:85], v[8:9], v[92:93] op_sel_hi:[1,0]
	v_pk_mul_f32 v[82:83], v[2:3], v[92:93] op_sel_hi:[1,0]
	v_pk_mul_f32 v[80:81], v[0:1], v[92:93] op_sel_hi:[1,0]

.LBB0_1410:
	s_and_b64 vcc, exec, s[2:3]
	s_cbranch_vccz .LBB0_1414
	s_waitcnt lgkmcnt(7)
	v_mfma_f32_16x16x32_bf16 v[48:51], v[48:51], v[104:107], 0
	s_waitcnt lgkmcnt(6)
	v_mfma_f32_16x16x32_bf16 v[48:51], v[52:55], v[108:111], v[48:51]
	s_waitcnt lgkmcnt(5)
	v_mfma_f32_16x16x32_bf16 v[52:55], v[56:59], v[104:107], 0
	s_waitcnt lgkmcnt(3)
	v_mfma_f32_16x16x32_bf16 v[56:59], v[64:67], v[104:107], 0
	s_waitcnt lgkmcnt(2)
	v_mfma_f32_16x16x32_bf16 v[64:67], v[68:71], v[108:111], v[56:59]
	s_waitcnt lgkmcnt(1)
	v_mfma_f32_16x16x32_bf16 v[56:59], v[72:75], v[104:107], 0
	v_mfma_f32_16x16x32_bf16 v[52:55], v[60:63], v[108:111], v[52:55]
	s_waitcnt lgkmcnt(0)
	v_mfma_f32_16x16x32_bf16 v[68:71], v[76:79], v[108:111], v[56:59]
	s_nop 7
	s_nop 7
	s_nop 0
	v_max3_f32 v56, v158, v48, v49
	s_nop 0
	v_max3_f32 v56, v56, v50, v51
	s_nop 0
	v_max3_f32 v56, v56, v52, v53
	s_nop 0
	v_max3_f32 v56, v56, v54, v55
	s_nop 0
	v_max3_f32 v56, v56, v64, v65
	s_nop 0
	v_max3_f32 v56, v56, v66, v67
	s_nop 0
	v_max3_f32 v56, v56, v68, v69
	s_nop 0
	v_max3_f32 v56, v56, v70, v71
	v_mov_b32_e32 v57, v56
	s_nop 1
	v_permlane16_swap_b32_e32 v57, v56
	s_waitcnt lgkmcnt(0)
	v_max3_f32 v56, v56, v57, v158
	v_mov_b32_e32 v57, v56
	s_nop 1
	v_permlane32_swap_b32_e32 v57, v56
	s_waitcnt lgkmcnt(0)
	v_max3_f32 v56, v56, v57, v158
	s_nop 0
	v_max3_f32 v135, v95, v56, v158
	s_nop 0
	v_sub_f32_e32 v51, v51, v135
	v_sub_f32_e32 v50, v50, v135
	v_sub_f32_e32 v49, v49, v135
	v_sub_f32_e32 v48, v48, v135
	v_sub_f32_e32 v55, v55, v135
	v_sub_f32_e32 v54, v54, v135
	v_exp_f32_e32 v56, v48
	v_exp_f32_e32 v57, v49
	v_exp_f32_e32 v58, v50
	v_exp_f32_e32 v59, v51
	v_sub_f32_e32 v48, v53, v135
	v_sub_f32_e32 v49, v52, v135
	v_exp_f32_e32 v60, v49
	v_exp_f32_e32 v62, v54
	v_exp_f32_e32 v63, v55
	v_exp_f32_e32 v61, v48
	v_pk_add_f32 v[48:49], v[56:57], 0 op_sel_hi:[1,0]
	v_pk_add_f32 v[50:51], v[58:59], 0 op_sel_hi:[1,0]
	v_sub_f32_e32 v53, v71, v135
	v_pk_add_f32 v[72:73], v[62:63], v[50:51]
	v_pk_add_f32 v[74:75], v[60:61], v[48:49]
	v_sub_f32_e32 v51, v67, v135
	v_sub_f32_e32 v50, v66, v135
	v_sub_f32_e32 v49, v65, v135
	v_sub_f32_e32 v48, v64, v135
	v_exp_f32_e32 v48, v48
	v_exp_f32_e32 v49, v49
	v_exp_f32_e32 v50, v50
	v_exp_f32_e32 v51, v51
	v_sub_f32_e32 v54, v70, v135
	v_sub_f32_e32 v64, v69, v135
	v_sub_f32_e32 v52, v68, v135
	v_exp_f32_e32 v52, v52
	v_exp_f32_e32 v54, v54
	v_exp_f32_e32 v55, v53
	v_exp_f32_e32 v53, v64
	v_pk_add_f32 v[64:65], v[48:49], v[74:75]
	v_pk_add_f32 v[66:67], v[50:51], v[72:73]
	v_pk_add_f32 v[64:65], v[52:53], v[64:65]
	v_pk_add_f32 v[66:67], v[54:55], v[66:67]
	v_add_f32_e32 v64, v64, v65
	v_add_f32_e32 v65, v66, v67
	v_add_f32_e32 v65, v64, v65
	v_mov_b32_e32 v66, v65
	s_nop 1
	v_permlane16_swap_b32_e32 v66, v65
	v_sub_f32_e32 v64, v95, v135
	v_exp_f32_e32 v64, v64
	s_waitcnt lgkmcnt(0)
	v_add_f32_e32 v65, v65, v66
	ds_bpermute_b32 v66, v217, v65
	v_cmp_eq_f32_e32 vcc, 1.0, v64
	s_cmp_eq_u64 vcc, exec
	s_cbranch_scc1 .LBB0_1413
	v_pk_mul_f32 v[42:43], v[42:43], v[64:65] op_sel_hi:[1,0]
	v_pk_mul_f32 v[40:41], v[40:41], v[64:65] op_sel_hi:[1,0]
	v_pk_mul_f32 v[18:19], v[18:19], v[64:65] op_sel_hi:[1,0]
	v_pk_mul_f32 v[16:17], v[16:17], v[64:65] op_sel_hi:[1,0]
	v_pk_mul_f32 v[10:11], v[10:11], v[64:65] op_sel_hi:[1,0]
	v_pk_mul_f32 v[8:9], v[8:9], v[64:65] op_sel_hi:[1,0]
	v_pk_mul_f32 v[2:3], v[2:3], v[64:65] op_sel_hi:[1,0]
	v_pk_mul_f32 v[0:1], v[0:1], v[64:65] op_sel_hi:[1,0]

.LBB0_1415:
	s_cmp_lt_i32 s74, 0
	s_cbranch_scc1 .LBB0_1436
	s_lshl_b32 s14, s74, 6
	s_or_b32 s15, s14, 63
	s_cmp_lt_i32 s15, s0
	s_cselect_b64 s[2:3], -1, 0
	s_cmp_gt_i32 s14, s76
	s_cselect_b64 s[74:75], -1, 0
	s_or_b64 s[2:3], s[74:75], s[2:3]
	v_mov_b32_e32 v136, v196
	s_and_b64 vcc, exec, s[2:3]
	s_cbranch_vccnz .LBB0_1426
	v_cmp_ge_i32_e32 vcc, s14, v130
	v_cmp_le_i32_e64 s[2:3], s15, v152
	s_and_b64 s[2:3], vcc, s[2:3]
	v_and_b32_e32 v80, 15, v136
	s_waitcnt lgkmcnt(7)
	v_cndmask_b32_e64 v48, 0, 1, s[2:3]
	v_cmp_ne_u32_e32 vcc, 0, v48
	v_and_b32_e32 v48, 48, v136
	s_waitcnt lgkmcnt(1)
	v_add_u32_e32 v72, s13, v48
	v_mad_u32_u24 v68, v80, s88, v72
	ds_read_b128 v[48:51], v68 offset:9216
	ds_read_b128 v[52:55], v68 offset:9280
	ds_read_b128 v[56:59], v68 offset:11520
	ds_read_b128 v[60:63], v68 offset:11584
	ds_read_b128 v[64:67], v68 offset:13824
	ds_read_b128 v[68:71], v68 offset:13888
	v_and_b32_e32 v92, 63, v136
	v_or_b32_e32 v81, 48, v92
	s_waitcnt lgkmcnt(6)
	v_mad_u32_u24 v76, v81, s88, v72
	ds_read_b128 v[72:75], v76 offset:9216
	ds_read_b128 v[76:79], v76 offset:9280
	s_cmp_lg_u64 vcc, exec
	v_mul_u32_u24_e32 v137, 0x90, v80
	v_mul_u32_u24_e32 v134, 0x90, v81
	s_mov_b64 s[2:3], -1
	s_cbranch_scc0 .LBB0_1421
	s_waitcnt lgkmcnt(7)
	v_mfma_f32_16x16x32_bf16 v[80:83], v[48:51], v[96:99], 0
	v_lshrrev_b32_e32 v139, 4, v92
	v_lshl_or_b32 v92, v139, 2, s14
	v_cmp_ge_i32_e32 vcc, v92, v130
	s_waitcnt lgkmcnt(5)
	v_mfma_f32_16x16x32_bf16 v[84:87], v[56:59], v[96:99], 0
	v_cmp_le_i32_e64 s[2:3], v92, v152
	s_and_b64 vcc, vcc, s[2:3]
	v_or_b32_e32 v135, 1, v92
	s_waitcnt lgkmcnt(3)
	v_mfma_f32_16x16x32_bf16 v[88:91], v[64:67], v[96:99], 0
	v_cmp_lt_i32_e64 s[2:3], v92, v152
	v_or_b32_e32 v138, 2, v92
	s_waitcnt lgkmcnt(1)
	v_mfma_f32_16x16x32_bf16 v[112:115], v[72:75], v[96:99], 0
	v_mfma_f32_16x16x32_bf16 v[80:83], v[52:55], v[100:103], v[80:83]
	v_mfma_f32_16x16x32_bf16 v[84:87], v[60:63], v[100:103], v[84:87]
	v_mfma_f32_16x16x32_bf16 v[88:91], v[68:71], v[100:103], v[88:91]
	s_waitcnt lgkmcnt(0)
	v_mfma_f32_16x16x32_bf16 v[112:115], v[76:79], v[100:103], v[112:115]
	s_nop 7
	s_nop 7
	s_nop 3
	v_cndmask_b32_e32 v80, v158, v80, vcc
	v_cmp_ge_i32_e32 vcc, v135, v130
	s_and_b64 vcc, s[2:3], vcc
	v_cmp_le_i32_e64 s[2:3], v138, v152
	v_cndmask_b32_e32 v81, v158, v81, vcc
	v_cmp_ge_i32_e32 vcc, v138, v130
	s_and_b64 vcc, vcc, s[2:3]
	v_or_b32_e32 v138, 3, v92
	v_cndmask_b32_e32 v82, v158, v82, vcc
	v_cmp_ge_i32_e32 vcc, v138, v130
	v_cmp_le_i32_e64 s[2:3], v138, v152
	s_and_b64 vcc, vcc, s[2:3]
	v_or_b32_e32 v138, 16, v92
	v_cndmask_b32_e32 v83, v158, v83, vcc
	v_cmp_ge_i32_e32 vcc, v138, v130
	v_cmp_le_i32_e64 s[2:3], v138, v152
	s_and_b64 vcc, vcc, s[2:3]
	v_or_b32_e32 v138, 17, v92
	v_cndmask_b32_e32 v84, v158, v84, vcc
	v_cmp_ge_i32_e32 vcc, v138, v130
	v_cmp_le_i32_e64 s[2:3], v138, v152
	s_and_b64 vcc, vcc, s[2:3]
	v_or_b32_e32 v138, 18, v92
	v_cndmask_b32_e32 v85, v158, v85, vcc
	v_cmp_ge_i32_e32 vcc, v138, v130
	v_cmp_le_i32_e64 s[2:3], v138, v152
	s_and_b64 vcc, vcc, s[2:3]
	v_or_b32_e32 v138, 19, v92
	v_cndmask_b32_e32 v86, v158, v86, vcc
	v_cmp_ge_i32_e32 vcc, v138, v130
	v_cmp_le_i32_e64 s[2:3], v138, v152
	s_and_b64 vcc, vcc, s[2:3]
	v_or_b32_e32 v138, 32, v92
	v_cndmask_b32_e32 v87, v158, v87, vcc
	v_cmp_ge_i32_e32 vcc, v138, v130
	v_cmp_le_i32_e64 s[2:3], v138, v152
	s_and_b64 vcc, vcc, s[2:3]
	v_or_b32_e32 v138, 33, v92
	v_cndmask_b32_e32 v88, v158, v88, vcc
	v_cmp_ge_i32_e32 vcc, v138, v130
	v_cmp_le_i32_e64 s[2:3], v138, v152
	s_and_b64 vcc, vcc, s[2:3]
	v_or_b32_e32 v138, 34, v92
	v_cndmask_b32_e32 v89, v158, v89, vcc
	v_cmp_ge_i32_e32 vcc, v138, v130
	v_cmp_le_i32_e64 s[2:3], v138, v152
	s_and_b64 vcc, vcc, s[2:3]
	v_or_b32_e32 v138, 35, v92
	v_cndmask_b32_e32 v90, v158, v90, vcc
	v_cmp_ge_i32_e32 vcc, v138, v130
	v_cmp_le_i32_e64 s[2:3], v138, v152
	s_and_b64 vcc, vcc, s[2:3]
	v_or_b32_e32 v138, 48, v92
	v_cndmask_b32_e32 v91, v158, v91, vcc
	v_cmp_ge_i32_e32 vcc, v138, v130
	v_cmp_le_i32_e64 s[2:3], v138, v152
	s_and_b64 vcc, vcc, s[2:3]
	v_or_b32_e32 v138, 49, v92
	v_max3_f32 v135, v80, s87, v81
	v_cndmask_b32_e32 v112, v158, v112, vcc
	v_cmp_ge_i32_e32 vcc, v138, v130
	v_cmp_le_i32_e64 s[2:3], v138, v152
	v_max3_f32 v135, v135, v82, v83
	s_and_b64 vcc, vcc, s[2:3]
	v_or_b32_e32 v138, 50, v92
	v_max3_f32 v135, v135, v84, v85
	v_cndmask_b32_e32 v113, v158, v113, vcc
	v_cmp_ge_i32_e32 vcc, v138, v130
	v_cmp_le_i32_e64 s[2:3], v138, v152
	v_max3_f32 v135, v135, v86, v87
	s_and_b64 vcc, vcc, s[2:3]
	v_or_b32_e32 v92, 51, v92
	v_max3_f32 v135, v135, v88, v89
	v_cndmask_b32_e32 v114, v158, v114, vcc
	v_cmp_ge_i32_e32 vcc, v92, v130
	v_cmp_le_i32_e64 s[2:3], v92, v152
	v_max3_f32 v135, v135, v90, v91
	s_and_b64 vcc, vcc, s[2:3]
	v_max3_f32 v135, v135, v112, v113
	v_cndmask_b32_e32 v92, v158, v115, vcc
	v_max3_f32 v115, v135, v114, v92
	v_mov_b32_e32 v135, v115
	s_nop 1
	v_permlane16_swap_b32_e32 v135, v115
	s_waitcnt lgkmcnt(0)
	v_max3_f32 v115, v115, v135, v158
	v_mov_b32_e32 v135, v115
	s_nop 1
	v_permlane32_swap_b32_e32 v135, v115
	s_waitcnt lgkmcnt(0)
	v_max3_f32 v115, v115, v135, v158
	v_cmp_lt_f32_e32 vcc, s86, v80
	v_max3_f32 v135, v133, v115, v158
	s_nop 0
	v_sub_f32_e32 v115, v80, v135
	v_exp_f32_e32 v115, v115
	v_sub_f32_e32 v138, v81, v135
	v_exp_f32_e32 v138, v138
	v_cndmask_b32_e32 v146, 0, v115, vcc
	v_cmp_lt_f32_e32 vcc, s86, v81
	v_sub_f32_e32 v81, v82, v135
	v_exp_f32_e32 v81, v81
	v_cndmask_b32_e32 v153, 0, v138, vcc
	v_sub_f32_e32 v115, v83, v135
	v_cmp_lt_f32_e32 vcc, s86, v82
	v_exp_f32_e32 v115, v115
	v_sub_f32_e32 v82, v85, v135
	v_cndmask_b32_e32 v162, 0, v81, vcc
	v_sub_f32_e32 v81, v84, v135
	v_exp_f32_e32 v81, v81
	v_exp_f32_e32 v82, v82
	v_cmp_lt_f32_e32 vcc, s86, v83
	v_add_f32_e32 v80, 0, v146
	v_add_f32_e32 v80, v153, v80
	v_cndmask_b32_e32 v163, 0, v115, vcc
	v_cmp_lt_f32_e32 vcc, s86, v84
	v_add_f32_e32 v80, v162, v80
	v_add_f32_e32 v80, v163, v80
	v_cndmask_b32_e32 v164, 0, v81, vcc
	v_cmp_lt_f32_e32 vcc, s86, v85
	v_sub_f32_e32 v81, v86, v135
	v_exp_f32_e32 v81, v81
	v_cndmask_b32_e32 v165, 0, v82, vcc
	v_sub_f32_e32 v82, v87, v135
	v_exp_f32_e32 v82, v82
	v_cmp_lt_f32_e32 vcc, s86, v86
	v_add_f32_e32 v80, v164, v80
	v_add_f32_e32 v80, v165, v80
	v_cndmask_b32_e32 v166, 0, v81, vcc
	v_cmp_lt_f32_e32 vcc, s86, v87
	v_sub_f32_e32 v81, v88, v135
	v_exp_f32_e32 v81, v81
	v_cndmask_b32_e32 v167, 0, v82, vcc
	v_sub_f32_e32 v82, v89, v135
	v_exp_f32_e32 v82, v82
	v_cmp_lt_f32_e32 vcc, s86, v88
	v_add_f32_e32 v80, v166, v80
	v_add_f32_e32 v80, v167, v80
	v_cndmask_b32_e32 v140, 0, v81, vcc
	v_cmp_lt_f32_e32 vcc, s86, v89
	v_sub_f32_e32 v81, v90, v135
	v_exp_f32_e32 v81, v81
	v_cndmask_b32_e32 v141, 0, v82, vcc
	v_sub_f32_e32 v82, v91, v135
	v_exp_f32_e32 v82, v82
	v_cmp_lt_f32_e32 vcc, s86, v90
	v_add_f32_e32 v80, v140, v80
	v_add_f32_e32 v80, v141, v80
	v_cndmask_b32_e32 v142, 0, v81, vcc
	v_cmp_lt_f32_e32 vcc, s86, v91
	v_sub_f32_e32 v81, v112, v135
	v_exp_f32_e32 v81, v81
	v_cndmask_b32_e32 v143, 0, v82, vcc
	v_sub_f32_e32 v82, v113, v135
	v_exp_f32_e32 v82, v82
	v_cmp_lt_f32_e32 vcc, s86, v112
	v_add_f32_e32 v80, v142, v80
	v_add_f32_e32 v80, v143, v80
	v_cndmask_b32_e32 v144, 0, v81, vcc
	v_cmp_lt_f32_e32 vcc, s86, v113
	v_sub_f32_e32 v81, v114, v135
	v_exp_f32_e32 v81, v81
	v_cndmask_b32_e32 v145, 0, v82, vcc
	v_sub_f32_e32 v82, v92, v135
	v_exp_f32_e32 v82, v82
	v_add_f32_e32 v80, v144, v80
	v_cmp_lt_f32_e32 vcc, s86, v114
	v_add_f32_e32 v80, v145, v80
	v_mov_b64_e32 v[86:87], v[14:15]
	v_cndmask_b32_e32 v147, 0, v81, vcc
	v_cmp_lt_f32_e32 vcc, s86, v92
	v_add_f32_e32 v80, v147, v80
	v_mov_b64_e32 v[90:91], v[22:23]
	v_cndmask_b32_e32 v155, 0, v82, vcc
	v_add_f32_e32 v80, v155, v80
	v_mov_b32_e32 v81, v80
	s_nop 1
	v_permlane16_swap_b32_e32 v81, v80
	v_sub_f32_e32 v82, v133, v135
	v_exp_f32_e32 v92, v82
	v_mov_b64_e32 v[114:115], v[46:47]
	v_mov_b64_e32 v[84:85], v[12:13]
	s_waitcnt lgkmcnt(0)
	v_add_f32_e32 v138, v80, v81
	ds_bpermute_b32 v168, v217, v138
	v_cmp_eq_f32_e32 vcc, 1.0, v92
	v_mov_b64_e32 v[82:83], v[6:7]
	s_cmp_eq_u64 vcc, exec
	v_mov_b64_e32 v[80:81], v[4:5]
	v_mov_b64_e32 v[88:89], v[20:21]
	v_mov_b64_e32 v[112:113], v[44:45]
	s_cbranch_scc1 .LBB0_1420
	v_pk_mul_f32 v[114:115], v[46:47], v[92:93] op_sel_hi:[1,0]
	v_pk_mul_f32 v[112:113], v[44:45], v[92:93] op_sel_hi:[1,0]
	v_pk_mul_f32 v[90:91], v[22:23], v[92:93] op_sel_hi:[1,0]
	v_pk_mul_f32 v[88:89], v[20:21], v[92:93] op_sel_hi:[1,0]
	v_pk_mul_f32 v[86:87], v[14:15], v[92:93] op_sel_hi:[1,0]
	v_pk_mul_f32 v[84:85], v[12:13], v[92:93] op_sel_hi:[1,0]
	v_pk_mul_f32 v[82:83], v[6:7], v[92:93] op_sel_hi:[1,0]
	v_pk_mul_f32 v[80:81], v[4:5], v[92:93] op_sel_hi:[1,0]

.LBB0_1426:
	s_cmp_lt_i32 s15, s78
	s_cselect_b64 s[2:3], -1, 0
	s_cmp_gt_i32 s14, s77
	s_cselect_b64 s[74:75], -1, 0
	s_or_b64 s[2:3], s[74:75], s[2:3]
	v_mov_b32_e32 v136, v196
	s_and_b64 vcc, exec, s[2:3]
	s_cbranch_vccnz .LBB0_1436
	v_cmp_ge_i32_e32 vcc, s14, v131
	v_cmp_le_i32_e64 s[2:3], s15, v154
	s_and_b64 s[2:3], vcc, s[2:3]
	v_and_b32_e32 v80, 15, v136
	s_waitcnt lgkmcnt(7)
	v_cndmask_b32_e64 v48, 0, 1, s[2:3]
	v_cmp_ne_u32_e32 vcc, 0, v48
	v_and_b32_e32 v48, 48, v136
	s_waitcnt lgkmcnt(1)
	v_add_u32_e32 v72, s13, v48
	v_mad_u32_u24 v68, v80, s88, v72
	ds_read_b128 v[48:51], v68 offset:9216
	ds_read_b128 v[52:55], v68 offset:9280
	ds_read_b128 v[56:59], v68 offset:11520
	ds_read_b128 v[60:63], v68 offset:11584
	ds_read_b128 v[64:67], v68 offset:13824
	ds_read_b128 v[68:71], v68 offset:13888
	v_and_b32_e32 v92, 63, v136
	v_or_b32_e32 v81, 48, v92
	s_waitcnt lgkmcnt(6)
	v_mad_u32_u24 v76, v81, s88, v72
	ds_read_b128 v[72:75], v76 offset:9216
	ds_read_b128 v[76:79], v76 offset:9280
	s_cmp_lg_u64 vcc, exec
	v_mul_u32_u24_e32 v137, 0x90, v80
	v_mul_u32_u24_e32 v134, 0x90, v81
	s_mov_b64 s[2:3], -1
	s_cbranch_scc0 .LBB0_1431
	s_waitcnt lgkmcnt(7)
	v_mfma_f32_16x16x32_bf16 v[80:83], v[48:51], v[104:107], 0
	v_lshrrev_b32_e32 v139, 4, v92
	v_lshl_or_b32 v92, v139, 2, s14
	v_cmp_ge_i32_e32 vcc, v92, v131
	s_waitcnt lgkmcnt(5)
	v_mfma_f32_16x16x32_bf16 v[84:87], v[56:59], v[104:107], 0
	v_cmp_le_i32_e64 s[2:3], v92, v154
	s_and_b64 vcc, vcc, s[2:3]
	v_or_b32_e32 v135, 1, v92
	s_waitcnt lgkmcnt(3)
	v_mfma_f32_16x16x32_bf16 v[88:91], v[64:67], v[104:107], 0
	v_cmp_lt_i32_e64 s[2:3], v92, v154
	v_or_b32_e32 v138, 2, v92
	s_waitcnt lgkmcnt(1)
	v_mfma_f32_16x16x32_bf16 v[112:115], v[72:75], v[104:107], 0
	v_mfma_f32_16x16x32_bf16 v[80:83], v[52:55], v[108:111], v[80:83]
	v_mfma_f32_16x16x32_bf16 v[84:87], v[60:63], v[108:111], v[84:87]
	v_mfma_f32_16x16x32_bf16 v[88:91], v[68:71], v[108:111], v[88:91]
	s_waitcnt lgkmcnt(0)
	v_mfma_f32_16x16x32_bf16 v[112:115], v[76:79], v[108:111], v[112:115]
	s_nop 7
	s_nop 7
	s_nop 3
	v_cndmask_b32_e32 v80, v158, v80, vcc
	v_cmp_ge_i32_e32 vcc, v135, v131
	s_and_b64 vcc, s[2:3], vcc
	v_cmp_le_i32_e64 s[2:3], v92, v152
	v_cndmask_b32_e32 v81, v158, v81, vcc
	v_cmp_ge_i32_e32 vcc, v138, v131
	s_and_b64 vcc, s[2:3], vcc
	v_or_b32_e32 v138, 3, v92
	v_cndmask_b32_e32 v82, v158, v82, vcc
	v_cmp_ge_i32_e32 vcc, v138, v131
	v_cmp_le_i32_e64 s[2:3], v138, v154
	s_and_b64 vcc, vcc, s[2:3]
	v_or_b32_e32 v138, 16, v92
	v_cndmask_b32_e32 v83, v158, v83, vcc
	v_cmp_ge_i32_e32 vcc, v138, v131
	v_cmp_le_i32_e64 s[2:3], v138, v154
	s_and_b64 vcc, vcc, s[2:3]
	v_or_b32_e32 v138, 17, v92
	v_cndmask_b32_e32 v84, v158, v84, vcc
	v_cmp_ge_i32_e32 vcc, v138, v131
	v_cmp_le_i32_e64 s[2:3], v138, v154
	s_and_b64 vcc, vcc, s[2:3]
	v_or_b32_e32 v138, 18, v92
	v_cndmask_b32_e32 v85, v158, v85, vcc
	v_cmp_ge_i32_e32 vcc, v138, v131
	v_cmp_le_i32_e64 s[2:3], v138, v154
	s_and_b64 vcc, vcc, s[2:3]
	v_or_b32_e32 v138, 19, v92
	v_cndmask_b32_e32 v86, v158, v86, vcc
	v_cmp_ge_i32_e32 vcc, v138, v131
	v_cmp_le_i32_e64 s[2:3], v138, v154
	s_and_b64 vcc, vcc, s[2:3]
	v_or_b32_e32 v138, 32, v92
	v_cndmask_b32_e32 v87, v158, v87, vcc
	v_cmp_ge_i32_e32 vcc, v138, v131
	v_cmp_le_i32_e64 s[2:3], v138, v154
	s_and_b64 vcc, vcc, s[2:3]
	v_or_b32_e32 v138, 33, v92
	v_cndmask_b32_e32 v88, v158, v88, vcc
	v_cmp_ge_i32_e32 vcc, v138, v131
	v_cmp_le_i32_e64 s[2:3], v138, v154
	s_and_b64 vcc, vcc, s[2:3]
	v_or_b32_e32 v138, 34, v92
	v_cndmask_b32_e32 v89, v158, v89, vcc
	v_cmp_ge_i32_e32 vcc, v138, v131
	v_cmp_le_i32_e64 s[2:3], v138, v154
	s_and_b64 vcc, vcc, s[2:3]
	v_or_b32_e32 v138, 35, v92
	v_cndmask_b32_e32 v90, v158, v90, vcc
	v_cmp_ge_i32_e32 vcc, v138, v131
	v_cmp_le_i32_e64 s[2:3], v138, v154
	s_and_b64 vcc, vcc, s[2:3]
	v_or_b32_e32 v138, 48, v92
	v_cndmask_b32_e32 v91, v158, v91, vcc
	v_cmp_ge_i32_e32 vcc, v138, v131
	v_cmp_le_i32_e64 s[2:3], v138, v154
	s_and_b64 vcc, vcc, s[2:3]
	v_or_b32_e32 v138, 49, v92
	v_max3_f32 v135, v80, s87, v81
	v_cndmask_b32_e32 v112, v158, v112, vcc
	v_cmp_ge_i32_e32 vcc, v138, v131
	v_cmp_le_i32_e64 s[2:3], v138, v154
	v_max3_f32 v135, v135, v82, v83
	s_and_b64 vcc, vcc, s[2:3]
	v_or_b32_e32 v138, 50, v92
	v_max3_f32 v135, v135, v84, v85
	v_cndmask_b32_e32 v113, v158, v113, vcc
	v_cmp_ge_i32_e32 vcc, v138, v131
	v_cmp_le_i32_e64 s[2:3], v138, v154
	v_max3_f32 v135, v135, v86, v87
	s_and_b64 vcc, vcc, s[2:3]
	v_or_b32_e32 v92, 51, v92
	v_max3_f32 v135, v135, v88, v89
	v_cndmask_b32_e32 v114, v158, v114, vcc
	v_cmp_ge_i32_e32 vcc, v92, v131
	v_cmp_le_i32_e64 s[2:3], v92, v154
	v_max3_f32 v135, v135, v90, v91
	s_and_b64 vcc, vcc, s[2:3]
	v_max3_f32 v135, v135, v112, v113
	v_cndmask_b32_e32 v92, v158, v115, vcc
	v_max3_f32 v115, v135, v114, v92
	v_mov_b32_e32 v135, v115
	s_nop 1
	v_permlane16_swap_b32_e32 v135, v115
	s_waitcnt lgkmcnt(0)
	v_max3_f32 v115, v115, v135, v158
	v_mov_b32_e32 v135, v115
	s_nop 1
	v_permlane32_swap_b32_e32 v135, v115
	s_waitcnt lgkmcnt(0)
	v_max3_f32 v115, v115, v135, v158
	v_cmp_lt_f32_e32 vcc, s86, v80
	v_max3_f32 v135, v95, v115, v158
	s_nop 0
	v_sub_f32_e32 v115, v80, v135
	v_exp_f32_e32 v115, v115
	v_sub_f32_e32 v138, v81, v135
	v_exp_f32_e32 v138, v138
	v_cndmask_b32_e32 v146, 0, v115, vcc
	v_cmp_lt_f32_e32 vcc, s86, v81
	v_sub_f32_e32 v81, v82, v135
	v_exp_f32_e32 v81, v81
	v_cndmask_b32_e32 v153, 0, v138, vcc
	v_sub_f32_e32 v115, v83, v135
	v_cmp_lt_f32_e32 vcc, s86, v82
	v_exp_f32_e32 v115, v115
	v_sub_f32_e32 v82, v85, v135
	v_cndmask_b32_e32 v162, 0, v81, vcc
	v_sub_f32_e32 v81, v84, v135
	v_exp_f32_e32 v81, v81
	v_exp_f32_e32 v82, v82
	v_cmp_lt_f32_e32 vcc, s86, v83
	v_add_f32_e32 v80, 0, v146
	v_add_f32_e32 v80, v153, v80
	v_cndmask_b32_e32 v163, 0, v115, vcc
	v_cmp_lt_f32_e32 vcc, s86, v84
	v_add_f32_e32 v80, v162, v80
	v_add_f32_e32 v80, v163, v80
	v_cndmask_b32_e32 v164, 0, v81, vcc
	v_cmp_lt_f32_e32 vcc, s86, v85
	v_sub_f32_e32 v81, v86, v135
	v_exp_f32_e32 v81, v81
	v_cndmask_b32_e32 v165, 0, v82, vcc
	v_sub_f32_e32 v82, v87, v135
	v_exp_f32_e32 v82, v82
	v_cmp_lt_f32_e32 vcc, s86, v86
	v_add_f32_e32 v80, v164, v80
	v_add_f32_e32 v80, v165, v80
	v_cndmask_b32_e32 v166, 0, v81, vcc
	v_cmp_lt_f32_e32 vcc, s86, v87
	v_sub_f32_e32 v81, v88, v135
	v_exp_f32_e32 v81, v81
	v_cndmask_b32_e32 v167, 0, v82, vcc
	v_sub_f32_e32 v82, v89, v135
	v_exp_f32_e32 v82, v82
	v_cmp_lt_f32_e32 vcc, s86, v88
	v_add_f32_e32 v80, v166, v80
	v_add_f32_e32 v80, v167, v80
	v_cndmask_b32_e32 v140, 0, v81, vcc
	v_cmp_lt_f32_e32 vcc, s86, v89
	v_sub_f32_e32 v81, v90, v135
	v_exp_f32_e32 v81, v81
	v_cndmask_b32_e32 v141, 0, v82, vcc
	v_sub_f32_e32 v82, v91, v135
	v_exp_f32_e32 v82, v82
	v_cmp_lt_f32_e32 vcc, s86, v90
	v_add_f32_e32 v80, v140, v80
	v_add_f32_e32 v80, v141, v80
	v_cndmask_b32_e32 v142, 0, v81, vcc
	v_cmp_lt_f32_e32 vcc, s86, v91
	v_sub_f32_e32 v81, v112, v135
	v_exp_f32_e32 v81, v81
	v_cndmask_b32_e32 v143, 0, v82, vcc
	v_sub_f32_e32 v82, v113, v135
	v_exp_f32_e32 v82, v82
	v_cmp_lt_f32_e32 vcc, s86, v112
	v_add_f32_e32 v80, v142, v80
	v_add_f32_e32 v80, v143, v80
	v_cndmask_b32_e32 v144, 0, v81, vcc
	v_cmp_lt_f32_e32 vcc, s86, v113
	v_sub_f32_e32 v81, v114, v135
	v_exp_f32_e32 v81, v81
	v_cndmask_b32_e32 v145, 0, v82, vcc
	v_sub_f32_e32 v82, v92, v135
	v_exp_f32_e32 v82, v82
	v_add_f32_e32 v80, v144, v80
	v_cmp_lt_f32_e32 vcc, s86, v114
	v_add_f32_e32 v80, v145, v80
	v_mov_b64_e32 v[86:87], v[10:11]
	v_cndmask_b32_e32 v147, 0, v81, vcc
	v_cmp_lt_f32_e32 vcc, s86, v92
	v_add_f32_e32 v80, v147, v80
	v_mov_b64_e32 v[90:91], v[18:19]
	v_cndmask_b32_e32 v155, 0, v82, vcc
	v_add_f32_e32 v80, v155, v80
	v_mov_b32_e32 v81, v80
	s_nop 1
	v_permlane16_swap_b32_e32 v81, v80
	v_sub_f32_e32 v82, v95, v135
	v_exp_f32_e32 v92, v82
	v_mov_b64_e32 v[114:115], v[42:43]
	v_mov_b64_e32 v[84:85], v[8:9]
	s_waitcnt lgkmcnt(0)
	v_add_f32_e32 v138, v80, v81
	ds_bpermute_b32 v168, v217, v138
	v_cmp_eq_f32_e32 vcc, 1.0, v92
	v_mov_b64_e32 v[82:83], v[2:3]
	s_cmp_eq_u64 vcc, exec
	v_mov_b64_e32 v[80:81], v[0:1]
	v_mov_b64_e32 v[88:89], v[16:17]
	v_mov_b64_e32 v[112:113], v[40:41]
	s_cbranch_scc1 .LBB0_1430
	v_pk_mul_f32 v[114:115], v[42:43], v[92:93] op_sel_hi:[1,0]
	v_pk_mul_f32 v[112:113], v[40:41], v[92:93] op_sel_hi:[1,0]
	v_pk_mul_f32 v[90:91], v[18:19], v[92:93] op_sel_hi:[1,0]
	v_pk_mul_f32 v[88:89], v[16:17], v[92:93] op_sel_hi:[1,0]
	v_pk_mul_f32 v[86:87], v[10:11], v[92:93] op_sel_hi:[1,0]
	v_pk_mul_f32 v[84:85], v[8:9], v[92:93] op_sel_hi:[1,0]
	v_pk_mul_f32 v[82:83], v[2:3], v[92:93] op_sel_hi:[1,0]
	v_pk_mul_f32 v[80:81], v[0:1], v[92:93] op_sel_hi:[1,0]

.LBB0_1443:
	v_readlane_b32 s68, v251, 44
	v_readlane_b32 s69, v251, 45
	s_mov_b64 s[4:5], s[68:69]
	s_waitcnt vmcnt(0)
	v_readlane_b32 s70, v251, 46
	v_readlane_b32 s71, v251, 47
	s_barrier
	s_and_saveexec_b64 s[0:1], s[70:71]
	v_readlane_b32 s34, v251, 37
	v_readlane_b32 s40, v251, 42
	s_xor_b64 s[2:3], exec, s[0:1]
	v_readlane_b32 s72, v251, 48
	v_readlane_b32 s30, v251, 34
	v_readlane_b32 s73, v251, 36
	v_readlane_b32 s35, v251, 38
	v_readlane_b32 s51, v251, 39
	v_readlane_b32 s36, v251, 40
	v_readlane_b32 s37, v251, 41
	s_movk_i32 s67, 0x4000
	s_mov_b32 s38, 0x800000
	s_mov_b32 s39, 0x2aaaaaab
	v_readlane_b32 s41, v251, 43
	v_readlane_b32 s31, v251, 35
	s_cbranch_execz .LBB0_1496
	v_writelane_b32 v250, s8, 44
	v_writelane_b32 v250, s9, 45
	v_writelane_b32 v250, s10, 46
	v_writelane_b32 v250, s11, 47
	v_writelane_b32 v250, s12, 48
	v_writelane_b32 v250, s13, 49
	v_writelane_b32 v250, s14, 50
	v_writelane_b32 v250, s15, 51
	s_load_dwordx2 s[8:9], s[68:69], 0xb8
	v_readfirstlane_b32 s12, v0
	v_readfirstlane_b32 s13, v1
	v_readlane_b32 s10, v250, 63
	v_readlane_b32 s11, v250, 61
	v_readlane_b32 s14, v250, 59
	v_mov_b32_e32 v0, 0
	s_mov_b32 s15, 0
	s_waitcnt lgkmcnt(0)
	s_add_u32 s8, s8, s10
	s_addc_u32 s9, s9, 0
	s_cmp_lg_u32 s11, 0
	s_cbranch_scc1 .Lgb7_known
	global_load_dword v1, v0, s[8:9] offset:128 sc1
	s_waitcnt vmcnt(0)
	v_readfirstlane_b32 s10, v1
	s_sub_u32 s11, s10, 1
	s_and_b32 s11, s11, s10
	s_cmp_eq_u32 s11, 0
	s_cselect_b32 s11, 2, 1
	s_cmp_eq_u32 s10, 0
	s_cselect_b32 s11, 1, s11
	v_writelane_b32 v250, s11, 61
	s_nop 0

.LBB0_1610:
	s_mov_b64 s[4:5], s[68:69]
	s_waitcnt vmcnt(0)
	s_waitcnt vmcnt(0) lgkmcnt(0)
	s_barrier
	s_and_saveexec_b64 s[0:1], s[70:71]
	s_xor_b64 s[2:3], exec, s[0:1]
	s_cbranch_execz .LBB0_1663
	v_writelane_b32 v250, s8, 44
	v_writelane_b32 v250, s9, 45
	v_writelane_b32 v250, s10, 46
	v_writelane_b32 v250, s11, 47
	v_writelane_b32 v250, s12, 48
	v_writelane_b32 v250, s13, 49
	v_writelane_b32 v250, s14, 50
	v_writelane_b32 v250, s15, 51
	s_load_dwordx2 s[8:9], s[68:69], 0xb8
	v_readfirstlane_b32 s12, v0
	v_readfirstlane_b32 s13, v1
	v_readlane_b32 s10, v250, 63
	v_readlane_b32 s11, v250, 61
	v_readlane_b32 s14, v250, 59
	v_mov_b32_e32 v0, 0
	s_mov_b32 s15, 0
	s_waitcnt lgkmcnt(0)
	s_add_u32 s8, s8, s10
	s_addc_u32 s9, s9, 0
	s_cmp_lg_u32 s11, 0
	s_cbranch_scc1 .Lgb9_known
	global_load_dword v1, v0, s[8:9] offset:128 sc1
	s_waitcnt vmcnt(0)
	v_readfirstlane_b32 s10, v1
	s_sub_u32 s11, s10, 1
	s_and_b32 s11, s11, s10
	s_cmp_eq_u32 s11, 0
	s_cselect_b32 s11, 2, 1
	s_cmp_eq_u32 s10, 0
	s_cselect_b32 s11, 1, s11
	v_writelane_b32 v250, s11, 61
	s_nop 0

.LBB0_1672:
	s_or_b64 exec, exec, s[2:3]
	s_mov_b64 s[4:5], s[68:69]
	s_waitcnt vmcnt(0)
	s_barrier
	s_and_saveexec_b64 s[0:1], s[70:71]
	s_xor_b64 s[2:3], exec, s[0:1]
	s_cbranch_execz .LBB0_1725
	v_writelane_b32 v250, s8, 44
	v_writelane_b32 v250, s9, 45
	v_writelane_b32 v250, s10, 46
	v_writelane_b32 v250, s11, 47
	v_writelane_b32 v250, s12, 48
	v_writelane_b32 v250, s13, 49
	v_writelane_b32 v250, s14, 50
	v_writelane_b32 v250, s15, 51
	s_load_dwordx2 s[8:9], s[68:69], 0xb8
	v_readfirstlane_b32 s12, v0
	v_readfirstlane_b32 s13, v1
	v_readlane_b32 s10, v250, 63
	v_readlane_b32 s11, v250, 61
	v_readlane_b32 s14, v250, 59
	v_mov_b32_e32 v0, 0
	s_mov_b32 s15, 0
	s_waitcnt lgkmcnt(0)
	s_add_u32 s8, s8, s10
	s_addc_u32 s9, s9, 0
	s_cmp_lg_u32 s11, 0
	s_cbranch_scc1 .Lgb10_known
	global_load_dword v1, v0, s[8:9] offset:128 sc1
	s_waitcnt vmcnt(0)
	v_readfirstlane_b32 s10, v1
	s_sub_u32 s11, s10, 1
	s_and_b32 s11, s11, s10
	s_cmp_eq_u32 s11, 0
	s_cselect_b32 s11, 2, 1
	s_cmp_eq_u32 s10, 0
	s_cselect_b32 s11, 1, s11
	v_writelane_b32 v250, s11, 61
	s_nop 0

.LBB0_1975:
	s_lshl_b32 s12, s11, 6
	v_mov_b32_e32 v189, v196
	s_cmp_gt_i32 s12, s20
	s_cbranch_scc1 .LBB0_1989
	s_mul_i32 s2, s21, 0x4800
	s_add_i32 s11, s2, 0
	s_mul_i32 s2, s21, 0x6800
	s_add_i32 s2, s2, 0
	v_and_b32_e32 v80, 48, v189
	v_and_b32_e32 v188, 15, v189
	v_add_u32_e32 v126, s2, v80
	v_mad_u32_u24 v80, v188, s84, v126
	ds_read_b128 v[122:125], v80
	ds_read_b128 v[118:121], v80 offset:64
	ds_read_b128 v[114:117], v80 offset:128
	ds_read_b128 v[110:113], v80 offset:3328
	ds_read_b128 v[106:109], v80 offset:3392
	ds_read_b128 v[102:105], v80 offset:3456
	ds_read_b128 v[98:101], v80 offset:6656
	ds_read_b128 v[94:97], v80 offset:6720
	v_and_b32_e32 v92, 63, v189
	v_or_b32_e32 v159, 48, v92
	v_mad_u32_u24 v81, v159, s84, v126
	ds_read_b128 v[88:91], v80 offset:6784
	ds_read_b128 v[84:87], v81
	ds_read_b128 v[80:83], v81 offset:64
	s_or_b32 s3, s12, 63
	v_cmp_le_i32_e32 vcc, s3, v184
	v_mul_u32_u24_e32 v127, 0xd0, v159
	s_cmp_lg_u64 vcc, exec
	s_mov_b64 s[2:3], -1
	v_add_u32_e32 v190, v126, v127
	s_cbranch_scc0 .LBB0_1982
	ds_read_b128 v[154:157], v190 offset:128
	s_waitcnt lgkmcnt(11)
	v_mfma_f32_16x16x32_bf16 v[126:129], v[122:125], v[32:35], 0
	v_lshrrev_b32_e32 v191, 4, v92
	v_lshl_or_b32 v175, v191, 2, s12
	v_cmp_lt_i32_e64 s[2:3], v175, v184
	s_waitcnt lgkmcnt(8)
	v_mfma_f32_16x16x32_bf16 v[130:133], v[110:113], v[32:35], 0
	v_or_b32_e32 v178, 2, v175
	v_or_b32_e32 v227, 3, v175
	v_cmp_lt_i32_e32 vcc, v205, v198
	s_waitcnt lgkmcnt(5)
	v_mfma_f32_16x16x32_bf16 v[134:137], v[98:101], v[32:35], 0
	v_or_b32_e32 v228, 17, v175
	v_cndmask_b32_e32 v92, v197, v205, vcc
	v_cmp_gt_i32_e32 vcc, v175, v184
	s_waitcnt lgkmcnt(2)
	v_mfma_f32_16x16x32_bf16 v[138:141], v[84:87], v[32:35], 0
	v_lshlrev_b32_e32 v176, 2, v92
	v_or_b32_e32 v229, 18, v175
	v_or_b32_e32 v230, 19, v175
	v_mfma_f32_16x16x32_bf16 v[126:129], v[118:121], v[36:39], v[126:129]
	v_or_b32_e32 v231, 32, v175
	v_or_b32_e32 v232, 33, v175
	v_or_b32_e32 v233, 34, v175
	v_mfma_f32_16x16x32_bf16 v[130:133], v[106:109], v[36:39], v[130:133]
	v_or_b32_e32 v234, 35, v175
	v_or_b32_e32 v235, 48, v175
	v_or_b32_e32 v236, 49, v175
	v_mfma_f32_16x16x32_bf16 v[134:137], v[94:97], v[36:39], v[134:137]
	v_or_b32_e32 v237, 50, v175
	v_or_b32_e32 v238, 51, v175
	s_waitcnt lgkmcnt(1)
	v_mfma_f32_16x16x32_bf16 v[138:141], v[80:83], v[36:39], v[138:141]
	v_mfma_f32_16x16x32_bf16 v[126:129], v[114:117], v[40:43], v[126:129]
	v_mfma_f32_16x16x32_bf16 v[130:133], v[102:105], v[40:43], v[130:133]
	v_mfma_f32_16x16x32_bf16 v[134:137], v[88:91], v[40:43], v[134:137]
	s_waitcnt lgkmcnt(0)
	v_mfma_f32_16x16x32_bf16 v[138:141], v[154:157], v[40:43], v[138:141]
	s_nop 7
	s_nop 7
	s_nop 3
	v_cndmask_b32_e64 v192, v158, v127, s[2:3]
	v_cmp_le_i32_e64 s[2:3], v178, v184
	v_or_b32_e32 v127, 16, v175
	v_cndmask_b32_e32 v92, v126, v158, vcc
	v_cndmask_b32_e64 v193, v158, v128, s[2:3]
	v_cmp_le_i32_e64 s[2:3], v227, v184
	v_max3_f32 v126, v92, s87, v192
	s_nop 0
	v_cndmask_b32_e64 v194, v158, v129, s[2:3]
	v_cmp_le_i32_e64 s[2:3], v127, v184
	v_max3_f32 v126, v126, v193, v194
	s_nop 0
	v_cndmask_b32_e64 v130, v158, v130, s[2:3]
	v_cmp_le_i32_e64 s[2:3], v228, v184
	s_nop 1
	v_cndmask_b32_e64 v131, v158, v131, s[2:3]
	v_cmp_le_i32_e64 s[2:3], v229, v184
	v_max3_f32 v126, v126, v130, v131
	s_nop 0
	v_cndmask_b32_e64 v132, v158, v132, s[2:3]
	v_cmp_le_i32_e64 s[2:3], v230, v184
	s_nop 1
	v_cndmask_b32_e64 v133, v158, v133, s[2:3]
	v_max3_f32 v142, v126, v132, v133
	v_mfma_f32_16x16x32_bf16 v[126:129], v[122:125], v[44:47], 0
	v_cmp_le_i32_e64 s[2:3], v231, v184
	v_mfma_f32_16x16x32_bf16 v[126:129], v[118:121], v[48:51], v[126:129]
	s_nop 0
	v_cndmask_b32_e64 v134, v158, v134, s[2:3]
	v_cmp_le_i32_e64 s[2:3], v232, v184
	s_nop 1
	v_cndmask_b32_e64 v135, v158, v135, s[2:3]
	v_max3_f32 v146, v142, v134, v135
	v_mfma_f32_16x16x32_bf16 v[142:145], v[114:117], v[52:55], v[126:129]
	v_cmp_le_i32_e64 s[2:3], v233, v184
	v_mfma_f32_16x16x32_bf16 v[126:129], v[110:113], v[44:47], 0
	s_nop 0
	v_cndmask_b32_e64 v136, v158, v136, s[2:3]
	v_cmp_le_i32_e64 s[2:3], v234, v184
	v_mfma_f32_16x16x32_bf16 v[126:129], v[106:109], v[48:51], v[126:129]
	s_nop 0
	v_cndmask_b32_e64 v137, v158, v137, s[2:3]
	v_max3_f32 v150, v146, v136, v137
	v_cmp_le_i32_e64 s[2:3], v235, v184
	v_mfma_f32_16x16x32_bf16 v[146:149], v[102:105], v[52:55], v[126:129]
	s_nop 0
	v_cndmask_b32_e64 v138, v158, v138, s[2:3]
	v_cmp_le_i32_e64 s[2:3], v236, v184
	v_mfma_f32_16x16x32_bf16 v[126:129], v[98:101], v[44:47], 0
	s_nop 0
	v_cndmask_b32_e64 v139, v158, v139, s[2:3]
	v_cmp_le_i32_e64 s[2:3], v237, v184
	v_mfma_f32_16x16x32_bf16 v[126:129], v[94:97], v[48:51], v[126:129]
	v_max3_f32 v150, v150, v138, v139
	v_cndmask_b32_e64 v140, v158, v140, s[2:3]
	v_cmp_le_i32_e64 s[2:3], v238, v184
	s_nop 1
	v_cndmask_b32_e64 v141, v158, v141, s[2:3]
	v_cmp_lt_i32_e64 s[2:3], v204, v198
	v_max3_f32 v174, v150, v140, v141
	v_mfma_f32_16x16x32_bf16 v[150:153], v[88:91], v[52:55], v[126:129]
	v_mov_b32_e32 v195, v174
	s_nop 1
	v_permlane16_swap_b32_e32 v195, v174
	s_waitcnt lgkmcnt(0)
	v_max3_f32 v174, v174, v195, v158
	s_nop 0
	v_cndmask_b32_e64 v126, v197, v204, s[2:3]
	v_lshlrev_b32_e32 v177, 2, v126
	v_mov_b32_e32 v195, v174
	s_nop 1
	v_permlane32_swap_b32_e32 v195, v174
	s_waitcnt lgkmcnt(0)
	v_max3_f32 v174, v174, v195, v158
	v_cmp_lt_f32_e64 s[2:3], s86, v92
	v_max3_f32 v174, v172, v174, v158
	v_mfma_f32_16x16x32_bf16 v[126:129], v[84:87], v[44:47], 0
	v_sub_f32_e32 v195, v92, v174
	v_exp_f32_e32 v195, v195
	v_sub_f32_e32 v213, v192, v174
	v_exp_f32_e32 v213, v213
	v_mfma_f32_16x16x32_bf16 v[126:129], v[80:83], v[48:51], v[126:129]
	v_cndmask_b32_e64 v217, 0, v195, s[2:3]
	v_cmp_lt_f32_e64 s[2:3], s86, v192
	v_sub_f32_e32 v192, v193, v174
	v_exp_f32_e32 v192, v192
	v_cndmask_b32_e64 v218, 0, v213, s[2:3]
	v_sub_f32_e32 v195, v194, v174
	v_cmp_lt_f32_e64 s[2:3], s86, v193
	v_exp_f32_e32 v195, v195
	v_sub_f32_e32 v193, v131, v174
	v_cndmask_b32_e64 v219, 0, v192, s[2:3]
	v_sub_f32_e32 v192, v130, v174
	v_exp_f32_e32 v192, v192
	v_cmp_lt_f32_e64 s[2:3], s86, v194
	v_exp_f32_e32 v193, v193
	v_add_f32_e32 v92, 0, v217
	v_cndmask_b32_e64 v220, 0, v195, s[2:3]
	v_cmp_lt_f32_e64 s[2:3], s86, v130
	v_sub_f32_e32 v130, v132, v174
	v_exp_f32_e32 v130, v130
	v_cndmask_b32_e64 v221, 0, v192, s[2:3]
	v_cmp_lt_f32_e64 s[2:3], s86, v131
	v_sub_f32_e32 v131, v133, v174
	v_exp_f32_e32 v131, v131
	v_cndmask_b32_e64 v222, 0, v193, s[2:3]
	v_cmp_lt_f32_e64 s[2:3], s86, v132
	v_add_f32_e32 v92, v218, v92
	v_add_f32_e32 v92, v219, v92
	v_cndmask_b32_e64 v223, 0, v130, s[2:3]
	v_cmp_lt_f32_e64 s[2:3], s86, v133
	v_sub_f32_e32 v130, v134, v174
	v_exp_f32_e32 v130, v130
	v_cndmask_b32_e64 v224, 0, v131, s[2:3]
	v_sub_f32_e32 v131, v135, v174
	v_exp_f32_e32 v131, v131
	v_cmp_lt_f32_e64 s[2:3], s86, v134
	v_add_f32_e32 v92, v220, v92
	v_add_f32_e32 v92, v221, v92
	v_cndmask_b32_e64 v192, 0, v130, s[2:3]
	v_cmp_lt_f32_e64 s[2:3], s86, v135
	v_sub_f32_e32 v130, v136, v174
	v_exp_f32_e32 v130, v130
	v_cndmask_b32_e64 v193, 0, v131, s[2:3]
	v_sub_f32_e32 v131, v137, v174
	v_exp_f32_e32 v131, v131
	v_cmp_lt_f32_e64 s[2:3], s86, v136
	v_add_f32_e32 v92, v222, v92
	v_add_f32_e32 v92, v223, v92
	v_cndmask_b32_e64 v194, 0, v130, s[2:3]
	v_cmp_lt_f32_e64 s[2:3], s86, v137
	v_sub_f32_e32 v130, v138, v174
	v_exp_f32_e32 v130, v130
	v_cndmask_b32_e64 v195, 0, v131, s[2:3]
	v_sub_f32_e32 v131, v139, v174
	v_exp_f32_e32 v131, v131
	v_add_f32_e32 v92, v224, v92
	v_cmp_lt_f32_e64 s[2:3], s86, v138
	v_add_f32_e32 v92, v192, v92
	v_add_f32_e32 v92, v193, v92
	v_cndmask_b32_e64 v213, 0, v130, s[2:3]
	v_cmp_lt_f32_e64 s[2:3], s86, v139
	v_sub_f32_e32 v130, v140, v174
	v_exp_f32_e32 v130, v130
	v_cndmask_b32_e64 v214, 0, v131, s[2:3]
	v_sub_f32_e32 v131, v141, v174
	v_add_f32_e32 v92, v194, v92
	v_exp_f32_e32 v131, v131
	v_add_f32_e32 v92, v195, v92
	v_add_f32_e32 v92, v213, v92
	v_cmp_lt_f32_e64 s[2:3], s86, v140
	v_add_f32_e32 v92, v214, v92
	v_mfma_f32_16x16x32_bf16 v[154:157], v[154:157], v[52:55], v[126:129]
	v_cndmask_b32_e64 v215, 0, v130, s[2:3]
	v_cmp_lt_f32_e64 s[2:3], s86, v141
	v_add_f32_e32 v92, v215, v92
	v_mov_b64_e32 v[128:129], v[30:31]
	v_cndmask_b32_e64 v216, 0, v131, s[2:3]
	v_add_f32_e32 v130, v216, v92
	v_mov_b32_e32 v131, v130
	s_nop 1
	v_permlane16_swap_b32_e32 v131, v130
	v_sub_f32_e32 v92, v172, v174
	v_exp_f32_e32 v92, v92
	v_mov_b64_e32 v[136:137], v[74:75]
	v_mov_b64_e32 v[140:141], v[78:79]
	s_waitcnt lgkmcnt(0)
	v_add_f32_e32 v225, v130, v131
	ds_bpermute_b32 v226, v177, v225
	v_cmp_eq_f32_e64 s[2:3], 1.0, v92
	v_mov_b64_e32 v[132:133], v[70:71]
	s_cmp_eq_u64 s[2:3], exec
	v_mov_b64_e32 v[126:127], v[28:29]
	v_mov_b64_e32 v[130:131], v[68:69]
	v_mov_b64_e32 v[134:135], v[72:73]
	v_mov_b64_e32 v[138:139], v[76:77]
	s_cbranch_scc1 .LBB0_1979
	v_pk_mul_f32 v[140:141], v[78:79], v[92:93] op_sel_hi:[1,0]
	v_pk_mul_f32 v[138:139], v[76:77], v[92:93] op_sel_hi:[1,0]
	v_pk_mul_f32 v[136:137], v[74:75], v[92:93] op_sel_hi:[1,0]
	v_pk_mul_f32 v[134:135], v[72:73], v[92:93] op_sel_hi:[1,0]
	v_pk_mul_f32 v[132:133], v[70:71], v[92:93] op_sel_hi:[1,0]
	v_pk_mul_f32 v[130:131], v[68:69], v[92:93] op_sel_hi:[1,0]
	v_pk_mul_f32 v[128:129], v[30:31], v[92:93] op_sel_hi:[1,0]
	v_pk_mul_f32 v[126:127], v[28:29], v[92:93] op_sel_hi:[1,0]
.LBB0_1979:
	v_cndmask_b32_e32 v146, v146, v158, vcc
	v_cmp_le_i32_e32 vcc, v228, v180
	v_cmp_le_i32_e64 s[2:3], v175, v180
	s_nop 0
	v_cndmask_b32_e32 v147, v158, v147, vcc
	v_cmp_le_i32_e32 vcc, v229, v180
	v_cndmask_b32_e64 v142, v158, v142, s[2:3]
	v_cmp_lt_i32_e64 s[2:3], v175, v180
	v_cndmask_b32_e32 v148, v158, v148, vcc
	v_cmp_le_i32_e32 vcc, v230, v180
	v_cndmask_b32_e64 v143, v158, v143, s[2:3]
	v_cmp_le_i32_e64 s[2:3], v178, v180
	v_cndmask_b32_e32 v149, v158, v149, vcc
	v_cmp_le_i32_e32 vcc, v231, v180
	v_cndmask_b32_e64 v144, v158, v144, s[2:3]
	v_cmp_le_i32_e64 s[2:3], v227, v180
	v_cndmask_b32_e32 v150, v158, v150, vcc
	v_cmp_le_i32_e32 vcc, v232, v180
	v_max3_f32 v175, v142, s87, v143
	v_cndmask_b32_e64 v145, v158, v145, s[2:3]
	v_cndmask_b32_e32 v151, v158, v151, vcc
	v_cmp_le_i32_e32 vcc, v233, v180
	v_max3_f32 v175, v175, v144, v145
	v_max3_f32 v175, v175, v146, v147
	v_cndmask_b32_e32 v152, v158, v152, vcc
	v_cmp_le_i32_e32 vcc, v234, v180
	v_max3_f32 v175, v175, v148, v149
	v_max3_f32 v175, v175, v150, v151
	v_cndmask_b32_e32 v153, v158, v153, vcc
	v_cmp_le_i32_e32 vcc, v235, v180
	v_max3_f32 v175, v175, v152, v153
	s_nop 0
	v_cndmask_b32_e32 v154, v158, v154, vcc
	v_cmp_le_i32_e32 vcc, v236, v180
	s_nop 1
	v_cndmask_b32_e32 v155, v158, v155, vcc
	v_cmp_le_i32_e32 vcc, v237, v180
	v_max3_f32 v175, v175, v154, v155
	s_nop 0
	v_cndmask_b32_e32 v156, v158, v156, vcc
	v_cmp_le_i32_e32 vcc, v238, v180
	s_nop 1
	v_cndmask_b32_e32 v157, v158, v157, vcc
	v_max3_f32 v175, v175, v156, v157
	v_mov_b32_e32 v178, v175
	s_nop 1
	v_permlane16_swap_b32_e32 v178, v175
	s_waitcnt lgkmcnt(0)
	v_max3_f32 v175, v175, v178, v158
	v_mov_b32_e32 v178, v175
	s_nop 1
	v_permlane32_swap_b32_e32 v178, v175
	s_waitcnt lgkmcnt(0)
	v_max3_f32 v175, v175, v178, v158
	v_cmp_lt_f32_e32 vcc, s86, v142
	v_max3_f32 v175, v173, v175, v158
	s_nop 0
	v_sub_f32_e32 v178, v142, v175
	v_exp_f32_e32 v178, v178
	v_sub_f32_e32 v227, v143, v175
	v_exp_f32_e32 v227, v227
	v_cndmask_b32_e32 v235, 0, v178, vcc
	v_cmp_lt_f32_e32 vcc, s86, v143
	v_sub_f32_e32 v143, v144, v175
	v_exp_f32_e32 v143, v143
	v_cndmask_b32_e32 v236, 0, v227, vcc
	v_sub_f32_e32 v178, v145, v175
	v_cmp_lt_f32_e32 vcc, s86, v144
	v_exp_f32_e32 v178, v178
	v_sub_f32_e32 v144, v147, v175
	v_cndmask_b32_e32 v237, 0, v143, vcc
	v_sub_f32_e32 v143, v146, v175
	v_exp_f32_e32 v143, v143
	v_exp_f32_e32 v144, v144
	v_cmp_lt_f32_e32 vcc, s86, v145
	v_add_f32_e32 v142, 0, v235
	v_add_f32_e32 v142, v236, v142
	v_cndmask_b32_e32 v238, 0, v178, vcc
	v_cmp_lt_f32_e32 vcc, s86, v146
	v_add_f32_e32 v142, v237, v142
	v_add_f32_e32 v142, v238, v142
	v_cndmask_b32_e32 v239, 0, v143, vcc
	v_cmp_lt_f32_e32 vcc, s86, v147
	v_sub_f32_e32 v143, v148, v175
	v_exp_f32_e32 v143, v143
	v_cndmask_b32_e32 v240, 0, v144, vcc
	v_sub_f32_e32 v144, v149, v175
	v_exp_f32_e32 v144, v144
	v_cmp_lt_f32_e32 vcc, s86, v148
	v_add_f32_e32 v142, v239, v142
	v_add_f32_e32 v142, v240, v142
	v_cndmask_b32_e32 v241, 0, v143, vcc
	v_cmp_lt_f32_e32 vcc, s86, v149
	v_sub_f32_e32 v143, v150, v175
	v_exp_f32_e32 v143, v143
	v_cndmask_b32_e32 v242, 0, v144, vcc
	v_sub_f32_e32 v144, v151, v175
	v_exp_f32_e32 v144, v144
	v_cmp_lt_f32_e32 vcc, s86, v150
	v_add_f32_e32 v142, v241, v142
	v_add_f32_e32 v142, v242, v142
	v_cndmask_b32_e32 v227, 0, v143, vcc
	v_cmp_lt_f32_e32 vcc, s86, v151
	v_sub_f32_e32 v143, v152, v175
	v_exp_f32_e32 v143, v143
	v_cndmask_b32_e32 v228, 0, v144, vcc
	v_sub_f32_e32 v144, v153, v175
	v_exp_f32_e32 v144, v144
	v_cmp_lt_f32_e32 vcc, s86, v152
	v_add_f32_e32 v142, v227, v142
	v_add_f32_e32 v142, v228, v142
	v_cndmask_b32_e32 v229, 0, v143, vcc
	v_cmp_lt_f32_e32 vcc, s86, v153
	v_sub_f32_e32 v143, v154, v175
	v_exp_f32_e32 v143, v143
	v_cndmask_b32_e32 v230, 0, v144, vcc
	v_sub_f32_e32 v144, v155, v175
	v_exp_f32_e32 v144, v144
	v_cmp_lt_f32_e32 vcc, s86, v154
	v_add_f32_e32 v142, v229, v142
	v_add_f32_e32 v142, v230, v142
	v_cndmask_b32_e32 v231, 0, v143, vcc
	v_cmp_lt_f32_e32 vcc, s86, v155
	v_sub_f32_e32 v143, v156, v175
	v_exp_f32_e32 v143, v143
	v_cndmask_b32_e32 v232, 0, v144, vcc
	v_sub_f32_e32 v144, v157, v175
	v_exp_f32_e32 v144, v144
	v_add_f32_e32 v142, v231, v142
	v_cmp_lt_f32_e32 vcc, s86, v156
	v_add_f32_e32 v142, v232, v142
	v_mov_b64_e32 v[148:149], v[22:23]
	v_cndmask_b32_e32 v233, 0, v143, vcc
	v_cmp_lt_f32_e32 vcc, s86, v157
	v_add_f32_e32 v142, v233, v142
	v_mov_b64_e32 v[152:153], v[26:27]
	v_cndmask_b32_e32 v234, 0, v144, vcc
	v_add_f32_e32 v142, v234, v142
	v_mov_b32_e32 v143, v142
	s_nop 1
	v_permlane16_swap_b32_e32 v143, v142
	v_sub_f32_e32 v144, v173, v175
	v_exp_f32_e32 v178, v144
	v_mov_b64_e32 v[156:157], v[66:67]
	v_mov_b64_e32 v[146:147], v[20:21]
	s_waitcnt lgkmcnt(0)
	v_add_f32_e32 v243, v142, v143
	ds_bpermute_b32 v177, v177, v243
	v_cmp_eq_f32_e32 vcc, 1.0, v178
	v_mov_b64_e32 v[144:145], v[18:19]
	s_cmp_eq_u64 vcc, exec
	v_mov_b64_e32 v[142:143], v[16:17]
	v_mov_b64_e32 v[150:151], v[24:25]
	v_mov_b64_e32 v[154:155], v[64:65]
	s_cbranch_scc1 .LBB0_1981
	v_pk_mul_f32 v[156:157], v[66:67], v[178:179] op_sel_hi:[1,0]
	v_pk_mul_f32 v[154:155], v[64:65], v[178:179] op_sel_hi:[1,0]
	v_pk_mul_f32 v[152:153], v[26:27], v[178:179] op_sel_hi:[1,0]
	v_pk_mul_f32 v[150:151], v[24:25], v[178:179] op_sel_hi:[1,0]
	v_pk_mul_f32 v[148:149], v[22:23], v[178:179] op_sel_hi:[1,0]
	v_pk_mul_f32 v[146:147], v[20:21], v[178:179] op_sel_hi:[1,0]
	v_pk_mul_f32 v[144:145], v[18:19], v[178:179] op_sel_hi:[1,0]
	v_pk_mul_f32 v[142:143], v[16:17], v[178:179] op_sel_hi:[1,0]

.LBB0_1982:
	s_and_b64 vcc, exec, s[2:3]
	s_cbranch_vccz .LBB0_1988
	s_waitcnt lgkmcnt(10)
	v_mfma_f32_16x16x32_bf16 v[126:129], v[122:125], v[32:35], 0
	v_cmp_lt_i32_e32 vcc, v205, v198
	v_mfma_f32_16x16x32_bf16 v[122:125], v[122:125], v[44:47], 0
	s_waitcnt lgkmcnt(9)
	v_mfma_f32_16x16x32_bf16 v[126:129], v[118:121], v[36:39], v[126:129]
	v_mfma_f32_16x16x32_bf16 v[118:121], v[118:121], v[48:51], v[122:125]
	s_waitcnt lgkmcnt(8)
	v_mfma_f32_16x16x32_bf16 v[122:125], v[114:117], v[40:43], v[126:129]
	v_mfma_f32_16x16x32_bf16 v[114:117], v[114:117], v[52:55], v[118:121]
	s_waitcnt lgkmcnt(7)
	v_mfma_f32_16x16x32_bf16 v[118:121], v[110:113], v[32:35], 0
	v_mfma_f32_16x16x32_bf16 v[110:113], v[110:113], v[44:47], 0
	s_waitcnt lgkmcnt(6)
	v_mfma_f32_16x16x32_bf16 v[118:121], v[106:109], v[36:39], v[118:121]
	v_mfma_f32_16x16x32_bf16 v[106:109], v[106:109], v[48:51], v[110:113]
	s_waitcnt lgkmcnt(5)
	v_mfma_f32_16x16x32_bf16 v[110:113], v[102:105], v[40:43], v[118:121]
	v_mfma_f32_16x16x32_bf16 v[102:105], v[102:105], v[52:55], v[106:109]
	s_waitcnt lgkmcnt(4)
	v_mfma_f32_16x16x32_bf16 v[106:109], v[98:101], v[32:35], 0
	v_mfma_f32_16x16x32_bf16 v[98:101], v[98:101], v[44:47], 0
	s_waitcnt lgkmcnt(3)
	v_mfma_f32_16x16x32_bf16 v[106:109], v[94:97], v[36:39], v[106:109]
	v_mfma_f32_16x16x32_bf16 v[94:97], v[94:97], v[48:51], v[98:101]
	s_waitcnt lgkmcnt(2)
	v_mfma_f32_16x16x32_bf16 v[126:129], v[88:91], v[40:43], v[106:109]
	v_mfma_f32_16x16x32_bf16 v[88:91], v[88:91], v[52:55], v[94:97]
	s_waitcnt lgkmcnt(1)
	v_mfma_f32_16x16x32_bf16 v[94:97], v[84:87], v[32:35], 0
	v_mfma_f32_16x16x32_bf16 v[84:87], v[84:87], v[44:47], 0
	s_waitcnt lgkmcnt(0)
	v_mfma_f32_16x16x32_bf16 v[94:97], v[80:83], v[36:39], v[94:97]
	v_mfma_f32_16x16x32_bf16 v[80:83], v[80:83], v[48:51], v[84:87]
	s_nop 4
	ds_read_b128 v[84:87], v190 offset:128
	s_waitcnt lgkmcnt(0)
	v_mfma_f32_16x16x32_bf16 v[94:97], v[84:87], v[40:43], v[94:97]
	s_nop 7
	s_nop 7
	v_mfma_f32_16x16x32_bf16 v[80:83], v[84:87], v[52:55], v[80:83]
	v_max3_f32 v84, v158, v122, v123
	v_cndmask_b32_e32 v85, v197, v205, vcc
	v_max3_f32 v84, v84, v124, v125
	v_lshlrev_b32_e32 v118, 2, v85
	v_max3_f32 v84, v84, v110, v111
	v_cmp_lt_i32_e32 vcc, v204, v198
	v_max3_f32 v84, v84, v112, v113
	s_nop 0
	v_max3_f32 v84, v84, v126, v127
	s_nop 0
	v_max3_f32 v84, v84, v128, v129
	s_nop 0
	v_max3_f32 v84, v84, v94, v95
	s_nop 0
	v_max3_f32 v84, v84, v96, v97
	v_mov_b32_e32 v85, v84
	s_nop 1
	v_permlane16_swap_b32_e32 v85, v84
	s_waitcnt lgkmcnt(0)
	v_max3_f32 v84, v84, v85, v158
	v_cndmask_b32_e32 v85, v197, v204, vcc
	v_lshlrev_b32_e32 v119, 2, v85
	v_mov_b32_e32 v85, v84
	s_nop 1
	v_permlane32_swap_b32_e32 v85, v84
	s_waitcnt lgkmcnt(0)
	v_max3_f32 v84, v84, v85, v158
	s_nop 0
	v_max3_f32 v174, v172, v84, v158
	s_nop 0
	v_sub_f32_e32 v84, v125, v174
	v_sub_f32_e32 v85, v124, v174
	v_sub_f32_e32 v86, v123, v174
	v_sub_f32_e32 v87, v122, v174
	v_exp_f32_e32 v98, v87
	v_exp_f32_e32 v99, v86
	v_exp_f32_e32 v100, v85
	v_exp_f32_e32 v101, v84
	v_sub_f32_e32 v109, v113, v174
	v_sub_f32_e32 v108, v112, v174
	v_sub_f32_e32 v107, v111, v174
	v_sub_f32_e32 v106, v110, v174
	v_exp_f32_e32 v106, v106
	v_exp_f32_e32 v107, v107
	v_exp_f32_e32 v108, v108
	v_exp_f32_e32 v109, v109
	v_pk_add_f32 v[84:85], v[98:99], 0 op_sel_hi:[1,0]
	v_pk_add_f32 v[86:87], v[100:101], 0 op_sel_hi:[1,0]
	v_pk_add_f32 v[112:113], v[106:107], v[84:85]
	v_pk_add_f32 v[110:111], v[108:109], v[86:87]
	v_sub_f32_e32 v87, v129, v174
	v_sub_f32_e32 v86, v128, v174
	v_sub_f32_e32 v85, v127, v174
	v_sub_f32_e32 v84, v126, v174
	v_exp_f32_e32 v84, v84
	v_exp_f32_e32 v85, v85
	v_exp_f32_e32 v86, v86
	v_exp_f32_e32 v87, v87
	v_sub_f32_e32 v97, v97, v174
	v_sub_f32_e32 v96, v96, v174
	v_sub_f32_e32 v95, v95, v174
	v_sub_f32_e32 v94, v94, v174
	v_exp_f32_e32 v94, v94
	v_exp_f32_e32 v95, v95
	v_exp_f32_e32 v96, v96
	v_exp_f32_e32 v97, v97
	v_pk_add_f32 v[112:113], v[84:85], v[112:113]
	v_pk_add_f32 v[110:111], v[86:87], v[110:111]
	v_pk_add_f32 v[112:113], v[94:95], v[112:113]
	v_pk_add_f32 v[110:111], v[96:97], v[110:111]
	v_sub_f32_e32 v92, v172, v174
	v_pk_mov_b32 v[120:121], v[112:113], v[110:111] op_sel:[1,0]
	v_mov_b32_e32 v113, v111
	v_pk_add_f32 v[110:111], v[120:121], v[112:113]
	v_exp_f32_e32 v92, v92
	v_add_f32_e32 v110, v110, v111
	v_mov_b32_e32 v111, v110
	s_nop 1
	v_permlane16_swap_b32_e32 v111, v110
	v_cmp_eq_f32_e32 vcc, 1.0, v92
	s_cmp_eq_u64 vcc, exec
	s_waitcnt lgkmcnt(0)
	v_add_f32_e32 v120, v110, v111
	ds_bpermute_b32 v121, v119, v120
	s_cbranch_scc1 .LBB0_1985
	v_pk_mul_f32 v[78:79], v[78:79], v[92:93] op_sel_hi:[1,0]
	v_pk_mul_f32 v[76:77], v[76:77], v[92:93] op_sel_hi:[1,0]
	v_pk_mul_f32 v[74:75], v[74:75], v[92:93] op_sel_hi:[1,0]
	v_pk_mul_f32 v[72:73], v[72:73], v[92:93] op_sel_hi:[1,0]
	v_pk_mul_f32 v[70:71], v[70:71], v[92:93] op_sel_hi:[1,0]
	v_pk_mul_f32 v[68:69], v[68:69], v[92:93] op_sel_hi:[1,0]
	v_pk_mul_f32 v[30:31], v[30:31], v[92:93] op_sel_hi:[1,0]
	v_pk_mul_f32 v[28:29], v[28:29], v[92:93] op_sel_hi:[1,0]
.LBB0_1985:
	v_max3_f32 v110, v158, v114, v115
	s_nop 0
	v_max3_f32 v110, v110, v116, v117
	s_nop 0
	v_max3_f32 v110, v110, v102, v103
	s_nop 0
	v_max3_f32 v110, v110, v104, v105
	s_nop 0
	v_max3_f32 v110, v110, v88, v89
	s_nop 0
	v_max3_f32 v110, v110, v90, v91
	s_nop 0
	v_max3_f32 v110, v110, v80, v81
	s_nop 0
	v_max3_f32 v110, v110, v82, v83
	v_mov_b32_e32 v111, v110
	s_nop 1
	v_permlane16_swap_b32_e32 v111, v110
	s_waitcnt lgkmcnt(0)
	v_max3_f32 v110, v110, v111, v158
	v_mov_b32_e32 v111, v110
	s_nop 1
	v_permlane32_swap_b32_e32 v111, v110
	s_waitcnt lgkmcnt(0)
	v_max3_f32 v110, v110, v111, v158
	s_nop 0
	v_max3_f32 v175, v173, v110, v158
	s_nop 0
	v_sub_f32_e32 v111, v117, v175
	v_sub_f32_e32 v110, v116, v175
	v_sub_f32_e32 v112, v115, v175
	v_sub_f32_e32 v113, v114, v175
	v_sub_f32_e32 v114, v105, v175
	v_sub_f32_e32 v115, v104, v175
	v_exp_f32_e32 v104, v113
	v_exp_f32_e32 v105, v112
	v_exp_f32_e32 v110, v110
	v_exp_f32_e32 v111, v111
	v_sub_f32_e32 v103, v103, v175
	v_sub_f32_e32 v102, v102, v175
	v_exp_f32_e32 v102, v102
	v_exp_f32_e32 v112, v115
	v_exp_f32_e32 v113, v114
	v_exp_f32_e32 v103, v103
	v_sub_f32_e32 v91, v91, v175
	v_sub_f32_e32 v90, v90, v175
	v_sub_f32_e32 v89, v89, v175
	v_sub_f32_e32 v88, v88, v175
	v_exp_f32_e32 v88, v88
	v_exp_f32_e32 v89, v89
	v_exp_f32_e32 v90, v90
	v_exp_f32_e32 v91, v91
	v_sub_f32_e32 v83, v83, v175
	v_sub_f32_e32 v82, v82, v175
	v_sub_f32_e32 v81, v81, v175
	v_sub_f32_e32 v80, v80, v175
	v_exp_f32_e32 v80, v80
	v_exp_f32_e32 v82, v82
	v_exp_f32_e32 v83, v83
	v_exp_f32_e32 v81, v81
	v_pk_add_f32 v[114:115], v[104:105], 0 op_sel_hi:[1,0]
	v_pk_add_f32 v[116:117], v[110:111], 0 op_sel_hi:[1,0]
	v_pk_add_f32 v[114:115], v[102:103], v[114:115]
	v_pk_add_f32 v[116:117], v[112:113], v[116:117]
	v_pk_add_f32 v[114:115], v[88:89], v[114:115]
	v_pk_add_f32 v[116:117], v[90:91], v[116:117]
	v_pk_add_f32 v[114:115], v[80:81], v[114:115]
	v_pk_add_f32 v[116:117], v[82:83], v[116:117]
	s_nop 0
	v_pk_mov_b32 v[122:123], v[114:115], v[116:117] op_sel:[1,0]
	v_mov_b32_e32 v115, v117
	v_pk_add_f32 v[114:115], v[122:123], v[114:115]
	s_nop 0
	v_add_f32_e32 v115, v114, v115
	v_mov_b32_e32 v116, v115
	s_nop 1
	v_permlane16_swap_b32_e32 v116, v115
	v_sub_f32_e32 v114, v173, v175
	v_exp_f32_e32 v114, v114
	s_waitcnt lgkmcnt(0)
	v_add_f32_e32 v115, v115, v116
	ds_bpermute_b32 v116, v119, v115
	v_cmp_eq_f32_e32 vcc, 1.0, v114
	s_cmp_eq_u64 vcc, exec
	s_cbranch_scc1 .LBB0_1987
	v_pk_mul_f32 v[66:67], v[66:67], v[114:115] op_sel_hi:[1,0]
	v_pk_mul_f32 v[64:65], v[64:65], v[114:115] op_sel_hi:[1,0]
	v_pk_mul_f32 v[26:27], v[26:27], v[114:115] op_sel_hi:[1,0]
	v_pk_mul_f32 v[24:25], v[24:25], v[114:115] op_sel_hi:[1,0]
	v_pk_mul_f32 v[22:23], v[22:23], v[114:115] op_sel_hi:[1,0]
	v_pk_mul_f32 v[20:21], v[20:21], v[114:115] op_sel_hi:[1,0]
	v_pk_mul_f32 v[18:19], v[18:19], v[114:115] op_sel_hi:[1,0]
	v_pk_mul_f32 v[16:17], v[16:17], v[114:115] op_sel_hi:[1,0]

.LBB0_1989:
	s_cmp_lt_i32 s10, 0
	s_cbranch_scc1 .LBB0_2004
	s_lshl_b32 s11, s10, 6
	v_mov_b32_e32 v189, v196
	s_cmp_gt_i32 s11, s20
	s_cbranch_scc1 .LBB0_2004
	s_lshl_b32 s2, s21, 1
	s_or_b32 s2, s2, 1
	s_mul_i32 s3, s2, 0x2400
	s_add_i32 s10, s3, 0
	s_lshl_b32 s2, s2, 12
	s_add_i32 s2, s10, s2
	s_waitcnt lgkmcnt(0)
	v_and_b32_e32 v80, 48, v189
	v_and_b32_e32 v188, 15, v189
	v_add_u32_e32 v126, s2, v80
	v_mad_u32_u24 v80, v188, s84, v126
	ds_read_b128 v[122:125], v80
	ds_read_b128 v[118:121], v80 offset:64
	ds_read_b128 v[114:117], v80 offset:128
	ds_read_b128 v[110:113], v80 offset:3328
	ds_read_b128 v[106:109], v80 offset:3392
	ds_read_b128 v[102:105], v80 offset:3456
	ds_read_b128 v[98:101], v80 offset:6656
	ds_read_b128 v[94:97], v80 offset:6720
	v_and_b32_e32 v92, 63, v189
	v_or_b32_e32 v159, 48, v92
	v_mad_u32_u24 v81, v159, s84, v126
	ds_read_b128 v[88:91], v80 offset:6784
	ds_read_b128 v[84:87], v81
	ds_read_b128 v[80:83], v81 offset:64
	s_or_b32 s3, s11, 63
	v_cmp_le_i32_e32 vcc, s3, v184
	v_mul_u32_u24_e32 v127, 0xd0, v159
	s_cmp_lg_u64 vcc, exec
	s_mov_b64 s[2:3], -1
	v_add_u32_e32 v190, v126, v127
	s_cbranch_scc0 .LBB0_1997
	ds_read_b128 v[154:157], v190 offset:128
	s_waitcnt lgkmcnt(11)
	v_mfma_f32_16x16x32_bf16 v[126:129], v[122:125], v[32:35], 0
	v_lshrrev_b32_e32 v191, 4, v92
	v_lshl_or_b32 v175, v191, 2, s11
	v_cmp_lt_i32_e64 s[2:3], v175, v184
	s_waitcnt lgkmcnt(8)
	v_mfma_f32_16x16x32_bf16 v[130:133], v[110:113], v[32:35], 0
	v_or_b32_e32 v178, 2, v175
	v_or_b32_e32 v227, 3, v175
	v_cmp_lt_i32_e32 vcc, v205, v198
	s_waitcnt lgkmcnt(5)
	v_mfma_f32_16x16x32_bf16 v[134:137], v[98:101], v[32:35], 0
	v_or_b32_e32 v228, 17, v175
	v_cndmask_b32_e32 v92, v197, v205, vcc
	v_cmp_gt_i32_e32 vcc, v175, v184
	s_waitcnt lgkmcnt(2)
	v_mfma_f32_16x16x32_bf16 v[138:141], v[84:87], v[32:35], 0
	v_lshlrev_b32_e32 v176, 2, v92
	v_or_b32_e32 v229, 18, v175
	v_or_b32_e32 v230, 19, v175
	v_mfma_f32_16x16x32_bf16 v[126:129], v[118:121], v[36:39], v[126:129]
	v_or_b32_e32 v231, 32, v175
	v_or_b32_e32 v232, 33, v175
	v_or_b32_e32 v233, 34, v175
	v_mfma_f32_16x16x32_bf16 v[130:133], v[106:109], v[36:39], v[130:133]
	v_or_b32_e32 v234, 35, v175
	v_or_b32_e32 v235, 48, v175
	v_or_b32_e32 v236, 49, v175
	v_mfma_f32_16x16x32_bf16 v[134:137], v[94:97], v[36:39], v[134:137]
	v_or_b32_e32 v237, 50, v175
	v_or_b32_e32 v238, 51, v175
	s_waitcnt lgkmcnt(1)
	v_mfma_f32_16x16x32_bf16 v[138:141], v[80:83], v[36:39], v[138:141]
	v_mfma_f32_16x16x32_bf16 v[126:129], v[114:117], v[40:43], v[126:129]
	v_mfma_f32_16x16x32_bf16 v[130:133], v[102:105], v[40:43], v[130:133]
	v_mfma_f32_16x16x32_bf16 v[134:137], v[88:91], v[40:43], v[134:137]
	s_waitcnt lgkmcnt(0)
	v_mfma_f32_16x16x32_bf16 v[138:141], v[154:157], v[40:43], v[138:141]
	s_nop 7
	s_nop 7
	s_nop 3
	v_cndmask_b32_e64 v192, v158, v127, s[2:3]
	v_cmp_le_i32_e64 s[2:3], v178, v184
	v_or_b32_e32 v127, 16, v175
	v_cndmask_b32_e32 v92, v126, v158, vcc
	v_cndmask_b32_e64 v193, v158, v128, s[2:3]
	v_cmp_le_i32_e64 s[2:3], v227, v184
	v_max3_f32 v126, v92, s87, v192
	s_nop 0
	v_cndmask_b32_e64 v194, v158, v129, s[2:3]
	v_cmp_le_i32_e64 s[2:3], v127, v184
	v_max3_f32 v126, v126, v193, v194
	s_nop 0
	v_cndmask_b32_e64 v130, v158, v130, s[2:3]
	v_cmp_le_i32_e64 s[2:3], v228, v184
	s_nop 1
	v_cndmask_b32_e64 v131, v158, v131, s[2:3]
	v_cmp_le_i32_e64 s[2:3], v229, v184
	v_max3_f32 v126, v126, v130, v131
	s_nop 0
	v_cndmask_b32_e64 v132, v158, v132, s[2:3]
	v_cmp_le_i32_e64 s[2:3], v230, v184
	s_nop 1
	v_cndmask_b32_e64 v133, v158, v133, s[2:3]
	v_max3_f32 v142, v126, v132, v133
	v_mfma_f32_16x16x32_bf16 v[126:129], v[122:125], v[44:47], 0
	v_cmp_le_i32_e64 s[2:3], v231, v184
	v_mfma_f32_16x16x32_bf16 v[126:129], v[118:121], v[48:51], v[126:129]
	s_nop 0
	v_cndmask_b32_e64 v134, v158, v134, s[2:3]
	v_cmp_le_i32_e64 s[2:3], v232, v184
	s_nop 1
	v_cndmask_b32_e64 v135, v158, v135, s[2:3]
	v_max3_f32 v146, v142, v134, v135
	v_mfma_f32_16x16x32_bf16 v[142:145], v[114:117], v[52:55], v[126:129]
	v_cmp_le_i32_e64 s[2:3], v233, v184
	v_mfma_f32_16x16x32_bf16 v[126:129], v[110:113], v[44:47], 0
	s_nop 0
	v_cndmask_b32_e64 v136, v158, v136, s[2:3]
	v_cmp_le_i32_e64 s[2:3], v234, v184
	v_mfma_f32_16x16x32_bf16 v[126:129], v[106:109], v[48:51], v[126:129]
	s_nop 0
	v_cndmask_b32_e64 v137, v158, v137, s[2:3]
	v_max3_f32 v150, v146, v136, v137
	v_cmp_le_i32_e64 s[2:3], v235, v184
	v_mfma_f32_16x16x32_bf16 v[146:149], v[102:105], v[52:55], v[126:129]
	s_nop 0
	v_cndmask_b32_e64 v138, v158, v138, s[2:3]
	v_cmp_le_i32_e64 s[2:3], v236, v184
	v_mfma_f32_16x16x32_bf16 v[126:129], v[98:101], v[44:47], 0
	s_nop 0
	v_cndmask_b32_e64 v139, v158, v139, s[2:3]
	v_cmp_le_i32_e64 s[2:3], v237, v184
	v_mfma_f32_16x16x32_bf16 v[126:129], v[94:97], v[48:51], v[126:129]
	v_max3_f32 v150, v150, v138, v139
	v_cndmask_b32_e64 v140, v158, v140, s[2:3]
	v_cmp_le_i32_e64 s[2:3], v238, v184
	s_nop 1
	v_cndmask_b32_e64 v141, v158, v141, s[2:3]
	v_cmp_lt_i32_e64 s[2:3], v204, v198
	v_max3_f32 v174, v150, v140, v141
	v_mfma_f32_16x16x32_bf16 v[150:153], v[88:91], v[52:55], v[126:129]
	v_mov_b32_e32 v195, v174
	s_nop 1
	v_permlane16_swap_b32_e32 v195, v174
	s_waitcnt lgkmcnt(0)
	v_max3_f32 v174, v174, v195, v158
	s_nop 0
	v_cndmask_b32_e64 v126, v197, v204, s[2:3]
	v_lshlrev_b32_e32 v177, 2, v126
	v_mov_b32_e32 v195, v174
	s_nop 1
	v_permlane32_swap_b32_e32 v195, v174
	s_waitcnt lgkmcnt(0)
	v_max3_f32 v174, v174, v195, v158
	v_cmp_lt_f32_e64 s[2:3], s86, v92
	v_max3_f32 v174, v172, v174, v158
	v_mfma_f32_16x16x32_bf16 v[126:129], v[84:87], v[44:47], 0
	v_sub_f32_e32 v195, v92, v174
	v_exp_f32_e32 v195, v195
	v_sub_f32_e32 v213, v192, v174
	v_exp_f32_e32 v213, v213
	v_mfma_f32_16x16x32_bf16 v[126:129], v[80:83], v[48:51], v[126:129]
	v_cndmask_b32_e64 v217, 0, v195, s[2:3]
	v_cmp_lt_f32_e64 s[2:3], s86, v192
	v_sub_f32_e32 v192, v193, v174
	v_exp_f32_e32 v192, v192
	v_cndmask_b32_e64 v218, 0, v213, s[2:3]
	v_sub_f32_e32 v195, v194, v174
	v_cmp_lt_f32_e64 s[2:3], s86, v193
	v_exp_f32_e32 v195, v195
	v_sub_f32_e32 v193, v131, v174
	v_cndmask_b32_e64 v219, 0, v192, s[2:3]
	v_sub_f32_e32 v192, v130, v174
	v_exp_f32_e32 v192, v192
	v_cmp_lt_f32_e64 s[2:3], s86, v194
	v_exp_f32_e32 v193, v193
	v_add_f32_e32 v92, 0, v217
	v_cndmask_b32_e64 v220, 0, v195, s[2:3]
	v_cmp_lt_f32_e64 s[2:3], s86, v130
	v_sub_f32_e32 v130, v132, v174
	v_exp_f32_e32 v130, v130
	v_cndmask_b32_e64 v221, 0, v192, s[2:3]
	v_cmp_lt_f32_e64 s[2:3], s86, v131
	v_sub_f32_e32 v131, v133, v174
	v_exp_f32_e32 v131, v131
	v_cndmask_b32_e64 v222, 0, v193, s[2:3]
	v_cmp_lt_f32_e64 s[2:3], s86, v132
	v_add_f32_e32 v92, v218, v92
	v_add_f32_e32 v92, v219, v92
	v_cndmask_b32_e64 v223, 0, v130, s[2:3]
	v_cmp_lt_f32_e64 s[2:3], s86, v133
	v_sub_f32_e32 v130, v134, v174
	v_exp_f32_e32 v130, v130
	v_cndmask_b32_e64 v224, 0, v131, s[2:3]
	v_sub_f32_e32 v131, v135, v174
	v_exp_f32_e32 v131, v131
	v_cmp_lt_f32_e64 s[2:3], s86, v134
	v_add_f32_e32 v92, v220, v92
	v_add_f32_e32 v92, v221, v92
	v_cndmask_b32_e64 v192, 0, v130, s[2:3]
	v_cmp_lt_f32_e64 s[2:3], s86, v135
	v_sub_f32_e32 v130, v136, v174
	v_exp_f32_e32 v130, v130
	v_cndmask_b32_e64 v193, 0, v131, s[2:3]
	v_sub_f32_e32 v131, v137, v174
	v_exp_f32_e32 v131, v131
	v_cmp_lt_f32_e64 s[2:3], s86, v136
	v_add_f32_e32 v92, v222, v92
	v_add_f32_e32 v92, v223, v92
	v_cndmask_b32_e64 v194, 0, v130, s[2:3]
	v_cmp_lt_f32_e64 s[2:3], s86, v137
	v_sub_f32_e32 v130, v138, v174
	v_exp_f32_e32 v130, v130
	v_cndmask_b32_e64 v195, 0, v131, s[2:3]
	v_sub_f32_e32 v131, v139, v174
	v_exp_f32_e32 v131, v131
	v_add_f32_e32 v92, v224, v92
	v_cmp_lt_f32_e64 s[2:3], s86, v138
	v_add_f32_e32 v92, v192, v92
	v_add_f32_e32 v92, v193, v92
	v_cndmask_b32_e64 v213, 0, v130, s[2:3]
	v_cmp_lt_f32_e64 s[2:3], s86, v139
	v_sub_f32_e32 v130, v140, v174
	v_exp_f32_e32 v130, v130
	v_cndmask_b32_e64 v214, 0, v131, s[2:3]
	v_sub_f32_e32 v131, v141, v174
	v_add_f32_e32 v92, v194, v92
	v_exp_f32_e32 v131, v131
	v_add_f32_e32 v92, v195, v92
	v_add_f32_e32 v92, v213, v92
	v_cmp_lt_f32_e64 s[2:3], s86, v140
	v_add_f32_e32 v92, v214, v92
	v_mfma_f32_16x16x32_bf16 v[154:157], v[154:157], v[52:55], v[126:129]
	v_cndmask_b32_e64 v215, 0, v130, s[2:3]
	v_cmp_lt_f32_e64 s[2:3], s86, v141
	v_add_f32_e32 v92, v215, v92
	v_mov_b64_e32 v[128:129], v[30:31]
	v_cndmask_b32_e64 v216, 0, v131, s[2:3]
	v_add_f32_e32 v130, v216, v92
	v_mov_b32_e32 v131, v130
	s_nop 1
	v_permlane16_swap_b32_e32 v131, v130
	v_sub_f32_e32 v92, v172, v174
	v_exp_f32_e32 v92, v92
	v_mov_b64_e32 v[136:137], v[74:75]
	v_mov_b64_e32 v[140:141], v[78:79]
	s_waitcnt lgkmcnt(0)
	v_add_f32_e32 v225, v130, v131
	ds_bpermute_b32 v226, v177, v225
	v_cmp_eq_f32_e64 s[2:3], 1.0, v92
	v_mov_b64_e32 v[132:133], v[70:71]
	s_cmp_eq_u64 s[2:3], exec
	v_mov_b64_e32 v[126:127], v[28:29]
	v_mov_b64_e32 v[130:131], v[68:69]
	v_mov_b64_e32 v[134:135], v[72:73]
	v_mov_b64_e32 v[138:139], v[76:77]
	s_cbranch_scc1 .LBB0_1994
	v_pk_mul_f32 v[140:141], v[78:79], v[92:93] op_sel_hi:[1,0]
	v_pk_mul_f32 v[138:139], v[76:77], v[92:93] op_sel_hi:[1,0]
	v_pk_mul_f32 v[136:137], v[74:75], v[92:93] op_sel_hi:[1,0]
	v_pk_mul_f32 v[134:135], v[72:73], v[92:93] op_sel_hi:[1,0]
	v_pk_mul_f32 v[132:133], v[70:71], v[92:93] op_sel_hi:[1,0]
	v_pk_mul_f32 v[130:131], v[68:69], v[92:93] op_sel_hi:[1,0]
	v_pk_mul_f32 v[128:129], v[30:31], v[92:93] op_sel_hi:[1,0]
	v_pk_mul_f32 v[126:127], v[28:29], v[92:93] op_sel_hi:[1,0]

.LBB0_2018:
	s_mov_b64 s[4:5], s[68:69]
	s_waitcnt vmcnt(0)
	s_barrier
	s_and_saveexec_b64 s[0:1], s[70:71]
	s_xor_b64 s[2:3], exec, s[0:1]
	s_cbranch_execz .LBB0_2071
	v_writelane_b32 v250, s8, 44
	v_writelane_b32 v250, s9, 45
	v_writelane_b32 v250, s10, 46
	v_writelane_b32 v250, s11, 47
	v_writelane_b32 v250, s12, 48
	v_writelane_b32 v250, s13, 49
	v_writelane_b32 v250, s14, 50
	v_writelane_b32 v250, s15, 51
	s_load_dwordx2 s[8:9], s[68:69], 0xb8
	v_readfirstlane_b32 s12, v0
	v_readfirstlane_b32 s13, v1
	v_readlane_b32 s10, v250, 63
	v_readlane_b32 s11, v250, 61
	v_readlane_b32 s14, v250, 59
	v_mov_b32_e32 v0, 0
	s_mov_b32 s15, 0
	s_waitcnt lgkmcnt(0)
	s_add_u32 s8, s8, s10
	s_addc_u32 s9, s9, 0
	s_cmp_lg_u32 s11, 0
	s_cbranch_scc1 .Lgb12_known
	global_load_dword v1, v0, s[8:9] offset:128 sc1
	s_waitcnt vmcnt(0)
	v_readfirstlane_b32 s10, v1
	s_sub_u32 s11, s10, 1
	s_and_b32 s11, s11, s10
	s_cmp_eq_u32 s11, 0
	s_cselect_b32 s11, 2, 1
	s_cmp_eq_u32 s10, 0
	s_cselect_b32 s11, 1, s11
	v_writelane_b32 v250, s11, 61
	s_nop 0
